# all remaining flat loads and stores converted to global
# speedup vs baseline: 1.0090x; 1.0027x over previous
;     __device__ __forceinline__ void operator()(AccT acc, const Unit& u, int wr, int wc, int fr, int fq) const {
;     ...
;             for (int m = 0; m < 4; ++m) { const size_t off = (size_t)(row0 + ai * HALF + m * 16) * D_ + col0;
; #pragma unroll
;                 for (int bj = 0; bj < 2; ++bj)
; #pragma unroll
;                     for (int n = 0; n < 2; ++n) { const f32x4 bs = *(const f32x4*)(xin + off + bj * HALF + n * 16); *(f32x4*)(xout + off + bj * HALF + n * 16) = bs + acc[ai][bj][m][n] * scale; }
;                 asm volatile("" ::: "memory"); }
.LBB0_49:
	v_lshl_add_u32 v20, s58, 8, v166
	v_lshl_or_b32 v18, s59, 8, v179
	v_ashrrev_i32_e32 v21, 31, v20
	v_ashrrev_i32_e32 v19, 31, v18
	v_lshlrev_b64 v[26:27], 12, v[20:21]
	v_lshl_add_u64 v[28:29], s[78:79], 0, v[26:27]
	v_lshlrev_b64 v[26:27], 2, v[18:19]
	v_lshl_add_u64 v[18:19], v[28:29], 0, v[26:27]
	global_load_dwordx4 v[42:45], v[18:19], off
	v_or_b32_e32 v28, 16, v20
	v_ashrrev_i32_e32 v29, 31, v28
	v_lshlrev_b64 v[28:29], 12, v[28:29]
	v_lshl_add_u64 v[28:29], s[78:79], 0, v[28:29]
	v_lshl_add_u64 v[28:29], v[28:29], 0, v[26:27]
	s_mov_b64 s[18:19], 0x80000
	s_waitcnt vmcnt(0) lgkmcnt(0)
	v_pk_add_f32 v[44:45], v[162:163], v[44:45]
	v_pk_add_f32 v[42:43], v[164:165], v[42:43]
	global_store_dwordx4 v[18:19], v[42:45], off
	global_load_dwordx4 v[42:45], v[18:19], off offset:64
	s_waitcnt vmcnt(0) lgkmcnt(0)
	v_pk_add_f32 v[44:45], v[154:155], v[44:45]
	v_pk_add_f32 v[42:43], v[156:157], v[42:43]
	global_store_dwordx4 v[18:19], v[42:45], off offset:64
	global_load_dwordx4 v[42:45], v[18:19], off offset:512
	s_waitcnt vmcnt(0) lgkmcnt(0)
	v_pk_add_f32 v[44:45], v[158:159], v[44:45]
	v_pk_add_f32 v[42:43], v[160:161], v[42:43]
	global_store_dwordx4 v[18:19], v[42:45], off offset:512
	global_load_dwordx4 v[42:45], v[18:19], off offset:576
	s_waitcnt vmcnt(0) lgkmcnt(0)
	v_pk_add_f32 v[44:45], v[126:127], v[44:45]
	v_pk_add_f32 v[42:43], v[128:129], v[42:43]
	global_store_dwordx4 v[18:19], v[42:45], off offset:576
	global_load_dwordx4 v[42:45], v[28:29], off
	s_waitcnt vmcnt(0) lgkmcnt(0)
	v_pk_add_f32 v[44:45], v[122:123], v[44:45]
	v_pk_add_f32 v[42:43], v[124:125], v[42:43]
	global_store_dwordx4 v[28:29], v[42:45], off
	global_load_dwordx4 v[42:45], v[28:29], off offset:64
	s_waitcnt vmcnt(0) lgkmcnt(0)
	v_pk_add_f32 v[44:45], v[116:117], v[44:45]
	v_pk_add_f32 v[42:43], v[114:115], v[42:43]
	global_store_dwordx4 v[28:29], v[42:45], off offset:64
	global_load_dwordx4 v[42:45], v[28:29], off offset:512
	s_waitcnt vmcnt(0) lgkmcnt(0)
	v_pk_add_f32 v[44:45], v[118:119], v[44:45]
	v_pk_add_f32 v[42:43], v[120:121], v[42:43]
	global_store_dwordx4 v[28:29], v[42:45], off offset:512
	global_load_dwordx4 v[42:45], v[28:29], off offset:576
	s_waitcnt vmcnt(0) lgkmcnt(0)
	v_pk_add_f32 v[44:45], v[110:111], v[44:45]
	v_pk_add_f32 v[42:43], v[112:113], v[42:43]
	global_store_dwordx4 v[28:29], v[42:45], off offset:576
	v_or_b32_e32 v28, 32, v20
	v_ashrrev_i32_e32 v29, 31, v28
	v_lshlrev_b64 v[28:29], 12, v[28:29]
	v_lshl_add_u64 v[28:29], s[78:79], 0, v[28:29]
	v_lshl_add_u64 v[28:29], v[28:29], 0, v[26:27]
	global_load_dwordx4 v[42:45], v[28:29], off
	v_or_b32_e32 v20, 48, v20
	v_ashrrev_i32_e32 v21, 31, v20
	v_lshlrev_b64 v[20:21], 12, v[20:21]
	v_lshl_add_u64 v[20:21], s[78:79], 0, v[20:21]
	v_lshl_add_u64 v[20:21], v[20:21], 0, v[26:27]
	s_waitcnt vmcnt(0) lgkmcnt(0)
	v_pk_add_f32 v[44:45], v[108:109], v[44:45]
	v_pk_add_f32 v[42:43], v[106:107], v[42:43]
	global_store_dwordx4 v[28:29], v[42:45], off
	global_load_dwordx4 v[42:45], v[28:29], off offset:64
	s_waitcnt vmcnt(0) lgkmcnt(0)
	v_pk_add_f32 v[44:45], v[100:101], v[44:45]
	v_pk_add_f32 v[42:43], v[98:99], v[42:43]
	global_store_dwordx4 v[28:29], v[42:45], off offset:64
	global_load_dwordx4 v[42:45], v[28:29], off offset:512
	s_waitcnt vmcnt(0) lgkmcnt(0)
	v_pk_add_f32 v[44:45], v[102:103], v[44:45]
	v_pk_add_f32 v[42:43], v[104:105], v[42:43]
	global_store_dwordx4 v[28:29], v[42:45], off offset:512
	global_load_dwordx4 v[42:45], v[28:29], off offset:576
	s_waitcnt vmcnt(0) lgkmcnt(0)
	v_pk_add_f32 v[44:45], v[94:95], v[44:45]
	v_pk_add_f32 v[42:43], v[96:97], v[42:43]
	global_store_dwordx4 v[28:29], v[42:45], off offset:576
	global_load_dwordx4 v[26:29], v[20:21], off
	s_waitcnt vmcnt(0) lgkmcnt(0)
	v_pk_add_f32 v[28:29], v[92:93], v[28:29]
	v_pk_add_f32 v[26:27], v[90:91], v[26:27]
	global_store_dwordx4 v[20:21], v[26:29], off
	global_load_dwordx4 v[26:29], v[20:21], off offset:64
	v_add_co_u32_e32 v42, vcc, s70, v18
	s_waitcnt vmcnt(0) lgkmcnt(0)
	v_pk_add_f32 v[28:29], v[84:85], v[28:29]
	v_pk_add_f32 v[26:27], v[82:83], v[26:27]
	global_store_dwordx4 v[20:21], v[26:29], off offset:64
	global_load_dwordx4 v[26:29], v[20:21], off offset:512
	v_addc_co_u32_e32 v43, vcc, 0, v19, vcc
	s_waitcnt vmcnt(0) lgkmcnt(0)
	v_pk_add_f32 v[28:29], v[86:87], v[28:29]
	v_pk_add_f32 v[26:27], v[88:89], v[26:27]
	global_store_dwordx4 v[20:21], v[26:29], off offset:512
	global_load_dwordx4 v[26:29], v[20:21], off offset:576
	s_waitcnt vmcnt(0) lgkmcnt(0)
;     __device__ __forceinline__ void operator()(AccT acc, const Unit& u, int wr, int wc, int fr, int fq) const {
;     ...
;             for (int m = 0; m < 4; ++m) { const size_t off = (size_t)(row0 + ai * HALF + m * 16) * D_ + col0;
; #pragma unroll
;                 for (int bj = 0; bj < 2; ++bj)
; #pragma unroll
;                     for (int n = 0; n < 2; ++n) { const f32x4 bs = *(const f32x4*)(xin + off + bj * HALF + n * 16); *(f32x4*)(xout + off + bj * HALF + n * 16) = bs + acc[ai][bj][m][n] * scale; }
;                 asm volatile("" ::: "memory"); }
	v_pk_add_f32 v[28:29], v[78:79], v[28:29]
	v_pk_add_f32 v[26:27], v[80:81], v[26:27]
	global_store_dwordx4 v[20:21], v[26:29], off offset:576
	global_load_dwordx4 v[26:29], v[42:43], off
	v_lshl_add_u64 v[20:21], v[18:19], 0, s[18:19]
	s_mov_b64 s[18:19], 0x90000
	s_waitcnt vmcnt(0) lgkmcnt(0)
	v_pk_add_f32 v[28:29], v[74:75], v[28:29]
	v_pk_add_f32 v[26:27], v[76:77], v[26:27]
	global_store_dwordx4 v[42:43], v[26:29], off
	global_load_dwordx4 v[26:29], v[20:21], off offset:64
	v_add_co_u32_e32 v42, vcc, s71, v18
	s_waitcnt vmcnt(0) lgkmcnt(0)
	v_pk_add_f32 v[28:29], v[66:67], v[28:29]
	v_pk_add_f32 v[26:27], v[68:69], v[26:27]
	global_store_dwordx4 v[20:21], v[26:29], off offset:64
	global_load_dwordx4 v[26:29], v[20:21], off offset:512
	v_addc_co_u32_e32 v43, vcc, 0, v19, vcc
	s_waitcnt vmcnt(0) lgkmcnt(0)
	v_pk_add_f32 v[28:29], v[70:71], v[28:29]
	v_pk_add_f32 v[26:27], v[72:73], v[26:27]
	global_store_dwordx4 v[20:21], v[26:29], off offset:512
	global_load_dwordx4 v[26:29], v[20:21], off offset:576
	s_waitcnt vmcnt(0) lgkmcnt(0)
	v_pk_add_f32 v[28:29], v[62:63], v[28:29]
	v_pk_add_f32 v[26:27], v[64:65], v[26:27]
	global_store_dwordx4 v[20:21], v[26:29], off offset:576
	global_load_dwordx4 v[26:29], v[42:43], off
	v_lshl_add_u64 v[20:21], v[18:19], 0, s[18:19]
	s_mov_b64 s[18:19], 0xa0000
	s_waitcnt vmcnt(0) lgkmcnt(0)
	v_pk_add_f32 v[28:29], v[58:59], v[28:29]
	v_pk_add_f32 v[26:27], v[60:61], v[26:27]
	global_store_dwordx4 v[42:43], v[26:29], off
	global_load_dwordx4 v[26:29], v[20:21], off offset:64
	v_lshl_add_u64 v[42:43], v[18:19], 0, s[18:19]
	s_mov_b64 s[18:19], 0xb0000
	s_waitcnt vmcnt(0) lgkmcnt(0)
	v_pk_add_f32 v[28:29], v[52:53], v[28:29]
	v_pk_add_f32 v[26:27], v[50:51], v[26:27]
	global_store_dwordx4 v[20:21], v[26:29], off offset:64
	global_load_dwordx4 v[26:29], v[20:21], off offset:512
	s_waitcnt vmcnt(0) lgkmcnt(0)
	v_pk_add_f32 v[28:29], v[54:55], v[28:29]
	v_pk_add_f32 v[26:27], v[56:57], v[26:27]
	global_store_dwordx4 v[20:21], v[26:29], off offset:512
	global_load_dwordx4 v[26:29], v[20:21], off offset:576
	s_waitcnt vmcnt(0) lgkmcnt(0)
	v_pk_add_f32 v[28:29], v[46:47], v[28:29]
	v_pk_add_f32 v[26:27], v[48:49], v[26:27]
	global_store_dwordx4 v[20:21], v[26:29], off offset:576
	v_add_co_u32_e32 v20, vcc, s72, v18
	s_nop 1
	v_addc_co_u32_e32 v21, vcc, 0, v19, vcc
	global_load_dwordx4 v[26:29], v[20:21], off
	s_waitcnt vmcnt(0) lgkmcnt(0)
	v_pk_add_f32 v[28:29], v[38:39], v[28:29]
	v_pk_add_f32 v[26:27], v[40:41], v[26:27]
	global_store_dwordx4 v[20:21], v[26:29], off
	global_load_dwordx4 v[26:29], v[42:43], off offset:64
	s_waitcnt vmcnt(0) lgkmcnt(0)
	v_pk_add_f32 v[28:29], v[30:31], v[28:29]
	v_pk_add_f32 v[26:27], v[32:33], v[26:27]
	global_store_dwordx4 v[42:43], v[26:29], off offset:64
	global_load_dwordx4 v[26:29], v[42:43], off offset:512
	s_waitcnt vmcnt(0) lgkmcnt(0)
	v_pk_add_f32 v[28:29], v[34:35], v[28:29]
	v_pk_add_f32 v[26:27], v[36:37], v[26:27]
	global_store_dwordx4 v[42:43], v[26:29], off offset:512
	global_load_dwordx4 v[26:29], v[42:43], off offset:576
	s_waitcnt vmcnt(0) lgkmcnt(0)
	v_pk_add_f32 v[22:23], v[22:23], v[28:29]
	v_pk_add_f32 v[20:21], v[24:25], v[26:27]
	global_store_dwordx4 v[42:43], v[20:23], off offset:576
	s_nop 1
	v_lshl_add_u64 v[22:23], v[18:19], 0, s[18:19]
	s_mov_b32 s18, 0xb0000
	v_add_co_u32_e32 v24, vcc, s18, v18
	s_mov_b64 s[18:19], -1
	s_nop 0
	v_addc_co_u32_e32 v25, vcc, 0, v19, vcc
	global_load_dwordx4 v[18:21], v[24:25], off
	s_and_b64 vcc, exec, s[2:3]
	s_waitcnt vmcnt(0) lgkmcnt(0)
	v_pk_add_f32 v[20:21], v[14:15], v[20:21]
	v_pk_add_f32 v[18:19], v[16:17], v[18:19]
	global_load_dwordx4 v[14:17], v[22:23], off offset:64
	s_waitcnt vmcnt(0) lgkmcnt(0)
	v_pk_add_f32 v[16:17], v[10:11], v[16:17]
	v_pk_add_f32 v[14:15], v[12:13], v[14:15]
	global_load_dwordx4 v[10:13], v[22:23], off offset:512
	s_waitcnt vmcnt(0) lgkmcnt(0)
	v_pk_add_f32 v[8:9], v[8:9], v[12:13]
	v_pk_add_f32 v[6:7], v[6:7], v[10:11]
	global_store_dwordx4 v[22:23], v[6:9], off offset:512
	global_load_dwordx4 v[6:9], v[22:23], off offset:576
	s_waitcnt vmcnt(0) lgkmcnt(0)
	v_pk_add_f32 v[4:5], v[4:5], v[8:9]
	v_pk_add_f32 v[2:3], v[2:3], v[6:7]
	global_store_dwordx4 v[24:25], v[18:21], off
	global_store_dwordx4 v[22:23], v[14:17], off offset:64
	global_store_dwordx4 v[22:23], v[2:5], off offset:576
	s_cbranch_vccnz .LBB0_32
	s_andn2_b64 vcc, exec, s[10:11]
	s_cbranch_vccnz .LBB0_31
	s_barrier
	s_branch .LBB0_31

; __device__ __forceinline__ float sigmoid_(float x) { return __builtin_amdgcn_rcpf(1.0f + __expf(-x)); }
; __device__ __forceinline__ uint4 pack8(const float (&f)[8]) { uint4 r; r.x = cvt_pk_bf16(f[0], f[1]); r.y = cvt_pk_bf16(f[2], f[3]); r.z = cvt_pk_bf16(f[4], f[5]); r.w = cvt_pk_bf16(f[6], f[7]); return r; }
; __device__ __forceinline__ void nt_store16(void* p, const uint4 v) { __builtin_nontemporal_store((u32x4){v.x, v.y, v.z, v.w}, (u32x4*)p); }
;     __device__ __forceinline__ void operator()(AccT acc, const Unit& u, int wr, int wc, int fr, int fq) const {
;     ...
;                 bf16_t* rowp = O + (size_t)(row0 + ai * HALF + m * 16) * FF_ + col0;
;                 float o[8];
; #pragma unroll
;                 for (int n = 0; n < 2; ++n)
; #pragma unroll
;                     for (int j = 0; j < 4; ++j) { const float gt = acc[ai][0][m][n][j], up = acc[ai][1][m][n][j]; o[n * 4 + j] = gt * sigmoid_(gt) * up; }
;                 nt_store16(rowp, pack8(o));
.LBB0_72:
	v_mul_f32_e32 v139, 0xbfb8aa3b, v126
	v_exp_f32_e32 v158, v139
	v_mul_f32_e32 v139, 0xbfb8aa3b, v127
	v_exp_f32_e32 v159, v139
	v_mul_f32_e32 v165, 0xbfb8aa3b, v128
	v_add_f32_e32 v158, 1.0, v158
	v_rcp_f32_e32 v166, v158
	v_add_f32_e32 v158, 1.0, v159
	v_rcp_f32_e32 v167, v158
	v_exp_f32_e32 v165, v165
	v_readlane_b32 s18, v254, 35
	v_lshl_or_b32 v138, s59, 7, v162
	v_pk_mul_f32 v[126:127], v[126:127], v[166:167]
	v_mul_f32_e32 v166, 0xbfb8aa3b, v129
	v_exp_f32_e32 v166, v166
	v_pk_mul_f32 v[122:123], v[122:123], v[126:127]
	v_add_f32_e32 v126, 1.0, v165
	v_mul_f32_e32 v165, 0xbfb8aa3b, v118
	v_add_f32_e32 v127, 1.0, v166
	v_rcp_f32_e32 v126, v126
	v_rcp_f32_e32 v127, v127
	v_exp_f32_e32 v165, v165
	v_mul_f32_e32 v166, 0xbfb8aa3b, v119
	v_exp_f32_e32 v166, v166
	v_pk_mul_f32 v[126:127], v[128:129], v[126:127]
	v_add_f32_e32 v128, 1.0, v165
	v_mul_f32_e32 v165, 0xbfb8aa3b, v120
	v_add_f32_e32 v129, 1.0, v166
	v_exp_f32_e32 v165, v165
	v_mul_f32_e32 v166, 0xbfb8aa3b, v121
	v_exp_f32_e32 v167, v166
	v_rcp_f32_e32 v128, v128
	v_add_f32_e32 v165, 1.0, v165
	v_rcp_f32_e32 v129, v129
	v_rcp_f32_e32 v166, v165
	v_add_f32_e32 v165, 1.0, v167
	v_rcp_f32_e32 v167, v165
	v_pk_mul_f32 v[118:119], v[118:119], v[128:129]
	v_readlane_b32 s19, v254, 36
	v_pk_mul_f32 v[118:119], v[114:115], v[118:119]
	v_pk_mul_f32 v[114:115], v[120:121], v[166:167]
	v_cvt_pk_bf16_f32 v118, v118, v119
	v_pk_mul_f32 v[120:121], v[116:117], v[114:115]
	v_lshl_add_u32 v164, s58, 8, v160
	v_cvt_pk_bf16_f32 v119, v120, v121
	v_mul_f32_e32 v120, 0xbfb8aa3b, v110
	v_mul_f32_e32 v121, 0xbfb8aa3b, v111
	v_exp_f32_e32 v120, v120
	v_exp_f32_e32 v121, v121
	v_ashrrev_i32_e32 v139, 31, v138
	v_mov_b64_e32 v[158:159], s[18:19]
	v_mad_i64_i32 v[178:179], s[18:19], v164, s67, v[158:159]
	v_pk_mul_f32 v[124:125], v[124:125], v[126:127]
	v_lshlrev_b64 v[114:115], 1, v[138:139]
	v_lshl_add_u64 v[126:127], v[178:179], 0, v[114:115]
	v_cvt_pk_bf16_f32 v116, v122, v123
	v_cvt_pk_bf16_f32 v117, v124, v125
	global_store_dwordx4 v[126:127], v[116:119], off
	s_and_b64 vcc, exec, s[2:3]
	s_mov_b64 s[2:3], -1
	v_add_f32_e32 v116, 1.0, v120
	v_add_f32_e32 v117, 1.0, v121
	v_rcp_f32_e32 v116, v116
	v_rcp_f32_e32 v117, v117
	v_or_b32_e32 v118, 16, v164
	v_mad_i64_i32 v[118:119], s[18:19], v118, s67, v[158:159]
	v_pk_mul_f32 v[110:111], v[110:111], v[116:117]
	v_mul_f32_e32 v116, 0xbfb8aa3b, v112
	v_mul_f32_e32 v117, 0xbfb8aa3b, v113
	v_exp_f32_e32 v116, v116
	v_exp_f32_e32 v117, v117
	v_pk_mul_f32 v[106:107], v[106:107], v[110:111]
	v_add_f32_e32 v110, 1.0, v116
	v_add_f32_e32 v111, 1.0, v117
	v_mul_f32_e32 v116, 0xbfb8aa3b, v102
	v_mul_f32_e32 v117, 0xbfb8aa3b, v103
	v_rcp_f32_e32 v110, v110
	v_rcp_f32_e32 v111, v111
	v_exp_f32_e32 v116, v116
	v_exp_f32_e32 v117, v117
	v_pk_mul_f32 v[110:111], v[112:113], v[110:111]
	v_add_f32_e32 v112, 1.0, v116
	v_add_f32_e32 v113, 1.0, v117
	v_mul_f32_e32 v116, 0xbfb8aa3b, v104
	v_mul_f32_e32 v117, 0xbfb8aa3b, v105
	v_exp_f32_e32 v116, v116
	v_exp_f32_e32 v117, v117
	v_rcp_f32_e32 v112, v112
	v_rcp_f32_e32 v113, v113
	v_add_f32_e32 v116, 1.0, v116
	v_add_f32_e32 v117, 1.0, v117
	v_rcp_f32_e32 v116, v116
	v_rcp_f32_e32 v117, v117
	v_pk_mul_f32 v[102:103], v[102:103], v[112:113]
	v_pk_mul_f32 v[108:109], v[108:109], v[110:111]
	v_pk_mul_f32 v[102:103], v[98:99], v[102:103]
	v_pk_mul_f32 v[98:99], v[104:105], v[116:117]
	v_lshl_add_u64 v[110:111], v[118:119], 0, v[114:115]
	v_pk_mul_f32 v[104:105], v[100:101], v[98:99]
	v_cvt_pk_bf16_f32 v100, v102, v103
	v_mul_f32_e32 v102, 0xbfb8aa3b, v94
	v_mul_f32_e32 v103, 0xbfb8aa3b, v95
	v_exp_f32_e32 v102, v102
	v_exp_f32_e32 v103, v103
	v_cvt_pk_bf16_f32 v98, v106, v107
	v_cvt_pk_bf16_f32 v99, v108, v109
	v_cvt_pk_bf16_f32 v101, v104, v105
	global_store_dwordx4 v[110:111], v[98:101], off
	s_nop 1
	v_add_f32_e32 v98, 1.0, v102
	v_add_f32_e32 v99, 1.0, v103
	v_rcp_f32_e32 v98, v98
	v_rcp_f32_e32 v99, v99
	v_or_b32_e32 v100, 32, v164
	v_mad_i64_i32 v[100:101], s[18:19], v100, s67, v[158:159]
	v_pk_mul_f32 v[94:95], v[94:95], v[98:99]
	v_mul_f32_e32 v98, 0xbfb8aa3b, v96
	v_mul_f32_e32 v99, 0xbfb8aa3b, v97
	v_exp_f32_e32 v98, v98
	v_exp_f32_e32 v99, v99
	v_pk_mul_f32 v[90:91], v[90:91], v[94:95]
	v_add_f32_e32 v94, 1.0, v98
	v_add_f32_e32 v95, 1.0, v99
	v_mul_f32_e32 v98, 0xbfb8aa3b, v86
	v_mul_f32_e32 v99, 0xbfb8aa3b, v87
	v_rcp_f32_e32 v94, v94
	v_rcp_f32_e32 v95, v95
	v_exp_f32_e32 v98, v98
	v_exp_f32_e32 v99, v99
	v_pk_mul_f32 v[94:95], v[96:97], v[94:95]
	v_add_f32_e32 v96, 1.0, v98
	v_add_f32_e32 v97, 1.0, v99
	v_mul_f32_e32 v98, 0xbfb8aa3b, v88
	v_mul_f32_e32 v99, 0xbfb8aa3b, v89
	v_exp_f32_e32 v98, v98
	v_exp_f32_e32 v99, v99
	v_rcp_f32_e32 v96, v96
	v_rcp_f32_e32 v97, v97
	v_add_f32_e32 v98, 1.0, v98
	v_add_f32_e32 v99, 1.0, v99
	v_rcp_f32_e32 v98, v98
	v_rcp_f32_e32 v99, v99
	v_pk_mul_f32 v[86:87], v[86:87], v[96:97]
	v_pk_mul_f32 v[92:93], v[92:93], v[94:95]
	v_pk_mul_f32 v[86:87], v[82:83], v[86:87]
	v_pk_mul_f32 v[82:83], v[88:89], v[98:99]
	v_lshl_add_u64 v[94:95], v[100:101], 0, v[114:115]
	v_pk_mul_f32 v[88:89], v[84:85], v[82:83]
	v_cvt_pk_bf16_f32 v84, v86, v87
	v_mul_f32_e32 v86, 0xbfb8aa3b, v78
	v_mul_f32_e32 v87, 0xbfb8aa3b, v79
	v_exp_f32_e32 v86, v86
	v_exp_f32_e32 v87, v87
	v_cvt_pk_bf16_f32 v82, v90, v91
	v_cvt_pk_bf16_f32 v83, v92, v93
	v_cvt_pk_bf16_f32 v85, v88, v89
	global_store_dwordx4 v[94:95], v[82:85], off
	s_nop 1
	v_add_f32_e32 v82, 1.0, v86
	v_add_f32_e32 v83, 1.0, v87
	v_rcp_f32_e32 v82, v82
	v_rcp_f32_e32 v83, v83
	v_or_b32_e32 v84, 48, v164
	v_mad_i64_i32 v[84:85], s[18:19], v84, s67, v[158:159]
	v_pk_mul_f32 v[78:79], v[78:79], v[82:83]
	v_mul_f32_e32 v82, 0xbfb8aa3b, v80
; __device__ __forceinline__ float sigmoid_(float x) { return __builtin_amdgcn_rcpf(1.0f + __expf(-x)); }
; __device__ __forceinline__ uint4 pack8(const float (&f)[8]) { uint4 r; r.x = cvt_pk_bf16(f[0], f[1]); r.y = cvt_pk_bf16(f[2], f[3]); r.z = cvt_pk_bf16(f[4], f[5]); r.w = cvt_pk_bf16(f[6], f[7]); return r; }
; __device__ __forceinline__ void nt_store16(void* p, const uint4 v) { __builtin_nontemporal_store((u32x4){v.x, v.y, v.z, v.w}, (u32x4*)p); }
;     __device__ __forceinline__ void operator()(AccT acc, const Unit& u, int wr, int wc, int fr, int fq) const {
;     ...
;                 bf16_t* rowp = O + (size_t)(row0 + ai * HALF + m * 16) * FF_ + col0;
;                 float o[8];
; #pragma unroll
;                 for (int n = 0; n < 2; ++n)
; #pragma unroll
;                     for (int j = 0; j < 4; ++j) { const float gt = acc[ai][0][m][n][j], up = acc[ai][1][m][n][j]; o[n * 4 + j] = gt * sigmoid_(gt) * up; }
;                 nt_store16(rowp, pack8(o));
	v_mul_f32_e32 v83, 0xbfb8aa3b, v81
	v_exp_f32_e32 v82, v82
	v_exp_f32_e32 v83, v83
	v_pk_mul_f32 v[74:75], v[74:75], v[78:79]
	v_add_f32_e32 v78, 1.0, v82
	v_add_f32_e32 v79, 1.0, v83
	v_mul_f32_e32 v82, 0xbfb8aa3b, v70
	v_mul_f32_e32 v83, 0xbfb8aa3b, v71
	v_rcp_f32_e32 v78, v78
	v_rcp_f32_e32 v79, v79
	v_exp_f32_e32 v82, v82
	v_exp_f32_e32 v83, v83
	v_pk_mul_f32 v[78:79], v[80:81], v[78:79]
	v_add_f32_e32 v80, 1.0, v82
	v_add_f32_e32 v81, 1.0, v83
	v_mul_f32_e32 v82, 0xbfb8aa3b, v72
	v_mul_f32_e32 v83, 0xbfb8aa3b, v73
	v_exp_f32_e32 v82, v82
	v_exp_f32_e32 v83, v83
	v_rcp_f32_e32 v80, v80
	v_rcp_f32_e32 v81, v81
	v_add_f32_e32 v82, 1.0, v82
	v_add_f32_e32 v83, 1.0, v83
	v_rcp_f32_e32 v82, v82
	v_rcp_f32_e32 v83, v83
	v_pk_mul_f32 v[70:71], v[70:71], v[80:81]
	v_pk_mul_f32 v[76:77], v[76:77], v[78:79]
	v_pk_mul_f32 v[70:71], v[66:67], v[70:71]
	v_pk_mul_f32 v[66:67], v[72:73], v[82:83]
	v_lshl_add_u64 v[78:79], v[84:85], 0, v[114:115]
	v_pk_mul_f32 v[72:73], v[68:69], v[66:67]
	v_cvt_pk_bf16_f32 v68, v70, v71
	v_mul_f32_e32 v70, 0xbfb8aa3b, v62
	v_mul_f32_e32 v71, 0xbfb8aa3b, v63
	v_exp_f32_e32 v70, v70
	v_exp_f32_e32 v71, v71
	v_cvt_pk_bf16_f32 v66, v74, v75
	v_cvt_pk_bf16_f32 v67, v76, v77
	v_cvt_pk_bf16_f32 v69, v72, v73
	global_store_dwordx4 v[78:79], v[66:69], off
	s_nop 1
	v_add_f32_e32 v66, 1.0, v70
	v_add_f32_e32 v67, 1.0, v71
	v_rcp_f32_e32 v66, v66
	v_rcp_f32_e32 v67, v67
	v_add_u32_e32 v68, 0x80, v164
	v_mad_i64_i32 v[68:69], s[18:19], v68, s67, v[158:159]
	v_pk_mul_f32 v[62:63], v[62:63], v[66:67]
	v_mul_f32_e32 v66, 0xbfb8aa3b, v64
	v_mul_f32_e32 v67, 0xbfb8aa3b, v65
	v_exp_f32_e32 v66, v66
	v_exp_f32_e32 v67, v67
	v_pk_mul_f32 v[58:59], v[58:59], v[62:63]
	v_add_f32_e32 v62, 1.0, v66
	v_add_f32_e32 v63, 1.0, v67
	v_mul_f32_e32 v66, 0xbfb8aa3b, v54
	v_mul_f32_e32 v67, 0xbfb8aa3b, v55
	v_rcp_f32_e32 v62, v62
	v_rcp_f32_e32 v63, v63
	v_exp_f32_e32 v66, v66
	v_exp_f32_e32 v67, v67
	v_pk_mul_f32 v[62:63], v[64:65], v[62:63]
	v_add_f32_e32 v64, 1.0, v66
	v_add_f32_e32 v65, 1.0, v67
	v_mul_f32_e32 v66, 0xbfb8aa3b, v56
	v_mul_f32_e32 v67, 0xbfb8aa3b, v57
	v_exp_f32_e32 v66, v66
	v_exp_f32_e32 v67, v67
	v_rcp_f32_e32 v64, v64
	v_rcp_f32_e32 v65, v65
	v_add_f32_e32 v66, 1.0, v66
	v_add_f32_e32 v67, 1.0, v67
	v_rcp_f32_e32 v66, v66
	v_rcp_f32_e32 v67, v67
	v_pk_mul_f32 v[54:55], v[54:55], v[64:65]
	v_pk_mul_f32 v[60:61], v[60:61], v[62:63]
	v_pk_mul_f32 v[54:55], v[50:51], v[54:55]
	v_pk_mul_f32 v[50:51], v[56:57], v[66:67]
	v_lshl_add_u64 v[62:63], v[68:69], 0, v[114:115]
	v_pk_mul_f32 v[56:57], v[52:53], v[50:51]
	v_cvt_pk_bf16_f32 v52, v54, v55
	v_mul_f32_e32 v54, 0xbfb8aa3b, v46
	v_mul_f32_e32 v55, 0xbfb8aa3b, v47
	v_exp_f32_e32 v54, v54
	v_exp_f32_e32 v55, v55
	v_cvt_pk_bf16_f32 v50, v58, v59
	v_cvt_pk_bf16_f32 v51, v60, v61
	v_cvt_pk_bf16_f32 v53, v56, v57
	global_store_dwordx4 v[62:63], v[50:53], off
	s_nop 1
	v_add_f32_e32 v50, 1.0, v54
	v_add_f32_e32 v51, 1.0, v55
	v_rcp_f32_e32 v50, v50
	v_rcp_f32_e32 v51, v51
	v_add_u32_e32 v52, 0x90, v164
	v_mad_i64_i32 v[52:53], s[18:19], v52, s67, v[158:159]
	v_pk_mul_f32 v[46:47], v[46:47], v[50:51]
	v_mul_f32_e32 v50, 0xbfb8aa3b, v48
	v_mul_f32_e32 v51, 0xbfb8aa3b, v49
	v_exp_f32_e32 v50, v50
	v_exp_f32_e32 v51, v51
	v_pk_mul_f32 v[42:43], v[42:43], v[46:47]
	v_add_f32_e32 v46, 1.0, v50
	v_add_f32_e32 v47, 1.0, v51
	v_mul_f32_e32 v50, 0xbfb8aa3b, v38
	v_mul_f32_e32 v51, 0xbfb8aa3b, v39
	v_rcp_f32_e32 v46, v46
	v_rcp_f32_e32 v47, v47
	v_exp_f32_e32 v50, v50
	v_exp_f32_e32 v51, v51
	v_pk_mul_f32 v[46:47], v[48:49], v[46:47]
	v_add_f32_e32 v48, 1.0, v50
	v_add_f32_e32 v49, 1.0, v51
	v_mul_f32_e32 v50, 0xbfb8aa3b, v40
	v_mul_f32_e32 v51, 0xbfb8aa3b, v41
	v_exp_f32_e32 v50, v50
	v_exp_f32_e32 v51, v51
	v_rcp_f32_e32 v48, v48
	v_rcp_f32_e32 v49, v49
; __device__ __forceinline__ float sigmoid_(float x) { return __builtin_amdgcn_rcpf(1.0f + __expf(-x)); }
; __device__ __forceinline__ uint4 pack8(const float (&f)[8]) { uint4 r; r.x = cvt_pk_bf16(f[0], f[1]); r.y = cvt_pk_bf16(f[2], f[3]); r.z = cvt_pk_bf16(f[4], f[5]); r.w = cvt_pk_bf16(f[6], f[7]); return r; }
; __device__ __forceinline__ void nt_store16(void* p, const uint4 v) { __builtin_nontemporal_store((u32x4){v.x, v.y, v.z, v.w}, (u32x4*)p); }
;     __device__ __forceinline__ void operator()(AccT acc, const Unit& u, int wr, int wc, int fr, int fq) const {
;         const int row0 = u.pm * BM + wr * 64 + fr, col0 = u.pn * 128 + wc * 32 + 8 * fq;
; #pragma unroll
;         for (int ai = 0; ai < 2; ++ai)
; #pragma unroll
;             for (int m = 0; m < 4; ++m) {
;                 bf16_t* rowp = O + (size_t)(row0 + ai * HALF + m * 16) * FF_ + col0;
;                 float o[8];
; #pragma unroll
;                 for (int n = 0; n < 2; ++n)
; #pragma unroll
;                     for (int j = 0; j < 4; ++j) { const float gt = acc[ai][0][m][n][j], up = acc[ai][1][m][n][j]; o[n * 4 + j] = gt * sigmoid_(gt) * up; }
;                 nt_store16(rowp, pack8(o));
;             }
	v_add_f32_e32 v50, 1.0, v50
	v_add_f32_e32 v51, 1.0, v51
	v_rcp_f32_e32 v50, v50
	v_rcp_f32_e32 v51, v51
	v_pk_mul_f32 v[38:39], v[38:39], v[48:49]
	v_pk_mul_f32 v[44:45], v[44:45], v[46:47]
	v_pk_mul_f32 v[38:39], v[34:35], v[38:39]
	v_pk_mul_f32 v[34:35], v[40:41], v[50:51]
	v_lshl_add_u64 v[46:47], v[52:53], 0, v[114:115]
	v_pk_mul_f32 v[40:41], v[36:37], v[34:35]
	v_cvt_pk_bf16_f32 v36, v38, v39
	v_mul_f32_e32 v38, 0xbfb8aa3b, v30
	v_mul_f32_e32 v39, 0xbfb8aa3b, v31
	v_exp_f32_e32 v38, v38
	v_exp_f32_e32 v39, v39
	v_cvt_pk_bf16_f32 v34, v42, v43
	v_cvt_pk_bf16_f32 v35, v44, v45
	v_cvt_pk_bf16_f32 v37, v40, v41
	global_store_dwordx4 v[46:47], v[34:37], off
	s_nop 1
	v_add_f32_e32 v34, 1.0, v38
	v_add_f32_e32 v35, 1.0, v39
	v_rcp_f32_e32 v34, v34
	v_rcp_f32_e32 v35, v35
	v_add_u32_e32 v36, 0xa0, v164
	v_mad_i64_i32 v[36:37], s[18:19], v36, s67, v[158:159]
	v_pk_mul_f32 v[30:31], v[30:31], v[34:35]
	v_mul_f32_e32 v34, 0xbfb8aa3b, v32
	v_mul_f32_e32 v35, 0xbfb8aa3b, v33
	v_exp_f32_e32 v34, v34
	v_exp_f32_e32 v35, v35
	v_pk_mul_f32 v[26:27], v[26:27], v[30:31]
	v_add_f32_e32 v30, 1.0, v34
	v_add_f32_e32 v31, 1.0, v35
	v_mul_f32_e32 v34, 0xbfb8aa3b, v22
	v_mul_f32_e32 v35, 0xbfb8aa3b, v23
	v_rcp_f32_e32 v30, v30
	v_rcp_f32_e32 v31, v31
	v_exp_f32_e32 v34, v34
	v_exp_f32_e32 v35, v35
	v_pk_mul_f32 v[30:31], v[32:33], v[30:31]
	v_add_f32_e32 v32, 1.0, v34
	v_add_f32_e32 v33, 1.0, v35
	v_mul_f32_e32 v34, 0xbfb8aa3b, v24
	v_mul_f32_e32 v35, 0xbfb8aa3b, v25
	v_exp_f32_e32 v34, v34
	v_exp_f32_e32 v35, v35
	v_rcp_f32_e32 v32, v32
	v_rcp_f32_e32 v33, v33
	v_add_f32_e32 v34, 1.0, v34
	v_add_f32_e32 v35, 1.0, v35
	v_rcp_f32_e32 v34, v34
	v_rcp_f32_e32 v35, v35
	v_pk_mul_f32 v[22:23], v[22:23], v[32:33]
	v_pk_mul_f32 v[28:29], v[28:29], v[30:31]
	v_pk_mul_f32 v[22:23], v[18:19], v[22:23]
	v_pk_mul_f32 v[18:19], v[24:25], v[34:35]
	v_lshl_add_u64 v[30:31], v[36:37], 0, v[114:115]
	v_pk_mul_f32 v[24:25], v[20:21], v[18:19]
	v_cvt_pk_bf16_f32 v20, v22, v23
	v_mul_f32_e32 v22, 0xbfb8aa3b, v14
	v_mul_f32_e32 v23, 0xbfb8aa3b, v15
	v_exp_f32_e32 v22, v22
	v_exp_f32_e32 v23, v23
	v_cvt_pk_bf16_f32 v18, v26, v27
	v_cvt_pk_bf16_f32 v19, v28, v29
	v_cvt_pk_bf16_f32 v21, v24, v25
	global_store_dwordx4 v[30:31], v[18:21], off
	s_nop 1
	v_add_f32_e32 v18, 1.0, v22
	v_add_f32_e32 v19, 1.0, v23
	v_rcp_f32_e32 v18, v18
	v_rcp_f32_e32 v19, v19
	v_add_u32_e32 v20, 0xb0, v164
	v_mad_i64_i32 v[20:21], s[18:19], v20, s67, v[158:159]
	v_pk_mul_f32 v[14:15], v[14:15], v[18:19]
	v_mul_f32_e32 v18, 0xbfb8aa3b, v16
	v_mul_f32_e32 v19, 0xbfb8aa3b, v17
	v_exp_f32_e32 v18, v18
	v_exp_f32_e32 v19, v19
	v_pk_mul_f32 v[10:11], v[10:11], v[14:15]
	v_add_f32_e32 v14, 1.0, v18
	v_add_f32_e32 v15, 1.0, v19
	v_mul_f32_e32 v18, 0xbfb8aa3b, v6
	v_mul_f32_e32 v19, 0xbfb8aa3b, v7
	v_rcp_f32_e32 v14, v14
	v_rcp_f32_e32 v15, v15
	v_exp_f32_e32 v18, v18
	v_exp_f32_e32 v19, v19
	v_pk_mul_f32 v[14:15], v[16:17], v[14:15]
	v_add_f32_e32 v16, 1.0, v18
	v_add_f32_e32 v17, 1.0, v19
	v_mul_f32_e32 v18, 0xbfb8aa3b, v8
	v_mul_f32_e32 v19, 0xbfb8aa3b, v9
	v_exp_f32_e32 v18, v18
	v_exp_f32_e32 v19, v19
	v_rcp_f32_e32 v16, v16
	v_rcp_f32_e32 v17, v17
	v_add_f32_e32 v18, 1.0, v18
	v_add_f32_e32 v19, 1.0, v19
	v_rcp_f32_e32 v18, v18
	v_rcp_f32_e32 v19, v19
	v_pk_mul_f32 v[6:7], v[6:7], v[16:17]
	v_pk_mul_f32 v[12:13], v[12:13], v[14:15]
	v_pk_mul_f32 v[6:7], v[2:3], v[6:7]
	v_pk_mul_f32 v[2:3], v[8:9], v[18:19]
	v_lshl_add_u64 v[14:15], v[20:21], 0, v[114:115]
	v_pk_mul_f32 v[8:9], v[4:5], v[2:3]
	v_cvt_pk_bf16_f32 v2, v10, v11
	v_cvt_pk_bf16_f32 v3, v12, v13
	v_cvt_pk_bf16_f32 v4, v6, v7
	v_cvt_pk_bf16_f32 v5, v8, v9
	global_store_dwordx4 v[14:15], v[2:5], off
	s_cbranch_vccnz .LBB0_60
	s_andn2_b64 vcc, exec, s[10:11]
	s_cbranch_vccnz .LBB0_59
	s_barrier
	s_branch .LBB0_59

;     __device__ __forceinline__ void operator()(AccT acc, const Unit& u, int wr, int wc, int fr, int fq) const {
;         const int row0 = u.pm * BM + wr * 64 + fr, col0 = u.pn * BM + wc * 32 + 4 * fq;
; #pragma unroll
;         for (int ai = 0; ai < 2; ++ai)
; #pragma unroll
;             for (int m = 0; m < 4; ++m) { const size_t off = (size_t)(row0 + ai * HALF + m * 16) * D_ + col0;
; #pragma unroll
;                 for (int bj = 0; bj < 2; ++bj)
; #pragma unroll
;                     for (int n = 0; n < 2; ++n) { const f32x4 bs = *(const f32x4*)(xin + off + bj * HALF + n * 16); *(f32x4*)(xout + off + bj * HALF + n * 16) = bs + acc[ai][bj][m][n] * scale; }
;                 asm volatile("" ::: "memory"); }
.LBB0_109:
	v_lshl_add_u32 v156, s58, 8, v160
	v_lshl_or_b32 v138, s59, 8, v162
	v_ashrrev_i32_e32 v157, 31, v156
	v_ashrrev_i32_e32 v139, 31, v138
	v_lshlrev_b64 v[154:155], 12, v[156:157]
	v_lshl_add_u64 v[154:155], s[78:79], 0, v[154:155]
	v_lshlrev_b64 v[158:159], 2, v[138:139]
	v_lshl_add_u64 v[154:155], v[154:155], 0, v[158:159]
	global_load_dwordx4 v[164:167], v[154:155], off
	s_mov_b64 s[18:19], 0x80000
	s_waitcnt vmcnt(0) lgkmcnt(0)
	v_pk_add_f32 v[128:129], v[128:129], v[166:167]
	v_pk_add_f32 v[126:127], v[126:127], v[164:165]
	global_store_dwordx4 v[154:155], v[126:129], off
	global_load_dwordx4 v[126:129], v[154:155], off offset:64
	s_waitcnt vmcnt(0) lgkmcnt(0)
	v_pk_add_f32 v[124:125], v[124:125], v[128:129]
	v_pk_add_f32 v[122:123], v[122:123], v[126:127]
	global_store_dwordx4 v[154:155], v[122:125], off offset:64
	global_load_dwordx4 v[122:125], v[154:155], off offset:512
	s_waitcnt vmcnt(0) lgkmcnt(0)
	v_pk_add_f32 v[120:121], v[120:121], v[124:125]
	v_pk_add_f32 v[118:119], v[118:119], v[122:123]
	global_store_dwordx4 v[154:155], v[118:121], off offset:512
	global_load_dwordx4 v[118:121], v[154:155], off offset:576
	s_waitcnt vmcnt(0) lgkmcnt(0)
	v_pk_add_f32 v[116:117], v[116:117], v[120:121]
	v_pk_add_f32 v[114:115], v[114:115], v[118:119]
	global_store_dwordx4 v[154:155], v[114:117], off offset:576
	s_nop 1
	v_or_b32_e32 v114, 16, v156
	v_ashrrev_i32_e32 v115, 31, v114
	v_lshlrev_b64 v[114:115], 12, v[114:115]
	v_lshl_add_u64 v[114:115], s[78:79], 0, v[114:115]
	v_lshl_add_u64 v[118:119], v[114:115], 0, v[158:159]
	global_load_dwordx4 v[114:117], v[118:119], off
	s_waitcnt vmcnt(0) lgkmcnt(0)
	v_pk_add_f32 v[112:113], v[112:113], v[116:117]
	v_pk_add_f32 v[110:111], v[110:111], v[114:115]
	global_store_dwordx4 v[118:119], v[110:113], off
	global_load_dwordx4 v[110:113], v[118:119], off offset:64
	s_waitcnt vmcnt(0) lgkmcnt(0)
	v_pk_add_f32 v[108:109], v[108:109], v[112:113]
	v_pk_add_f32 v[106:107], v[106:107], v[110:111]
	global_store_dwordx4 v[118:119], v[106:109], off offset:64
	global_load_dwordx4 v[106:109], v[118:119], off offset:512
	s_waitcnt vmcnt(0) lgkmcnt(0)
	v_pk_add_f32 v[104:105], v[104:105], v[108:109]
	v_pk_add_f32 v[102:103], v[102:103], v[106:107]
	global_store_dwordx4 v[118:119], v[102:105], off offset:512
	global_load_dwordx4 v[102:105], v[118:119], off offset:576
	s_waitcnt vmcnt(0) lgkmcnt(0)
	v_pk_add_f32 v[100:101], v[100:101], v[104:105]
	v_pk_add_f32 v[98:99], v[98:99], v[102:103]
	global_store_dwordx4 v[118:119], v[98:101], off offset:576
	s_nop 1
	v_or_b32_e32 v98, 32, v156
	v_ashrrev_i32_e32 v99, 31, v98
	v_lshlrev_b64 v[98:99], 12, v[98:99]
	v_lshl_add_u64 v[98:99], s[78:79], 0, v[98:99]
	v_lshl_add_u64 v[102:103], v[98:99], 0, v[158:159]
	global_load_dwordx4 v[98:101], v[102:103], off
	s_waitcnt vmcnt(0) lgkmcnt(0)
	v_pk_add_f32 v[96:97], v[96:97], v[100:101]
	v_pk_add_f32 v[94:95], v[94:95], v[98:99]
	global_store_dwordx4 v[102:103], v[94:97], off
	global_load_dwordx4 v[94:97], v[102:103], off offset:64
	s_waitcnt vmcnt(0) lgkmcnt(0)
	v_pk_add_f32 v[92:93], v[92:93], v[96:97]
	v_pk_add_f32 v[90:91], v[90:91], v[94:95]
	global_store_dwordx4 v[102:103], v[90:93], off offset:64
	global_load_dwordx4 v[90:93], v[102:103], off offset:512
	s_waitcnt vmcnt(0) lgkmcnt(0)
	v_pk_add_f32 v[88:89], v[88:89], v[92:93]
	v_pk_add_f32 v[86:87], v[86:87], v[90:91]
	global_store_dwordx4 v[102:103], v[86:89], off offset:512
	global_load_dwordx4 v[86:89], v[102:103], off offset:576
	s_waitcnt vmcnt(0) lgkmcnt(0)
	v_pk_add_f32 v[84:85], v[84:85], v[88:89]
	v_pk_add_f32 v[82:83], v[82:83], v[86:87]
	global_store_dwordx4 v[102:103], v[82:85], off offset:576
	s_nop 1
	v_or_b32_e32 v82, 48, v156
	v_ashrrev_i32_e32 v83, 31, v82
	v_lshlrev_b64 v[82:83], 12, v[82:83]
	v_lshl_add_u64 v[82:83], s[78:79], 0, v[82:83]
	v_lshl_add_u64 v[86:87], v[82:83], 0, v[158:159]
	global_load_dwordx4 v[82:85], v[86:87], off
	s_waitcnt vmcnt(0) lgkmcnt(0)
	v_pk_add_f32 v[80:81], v[80:81], v[84:85]
	v_pk_add_f32 v[78:79], v[78:79], v[82:83]
	global_store_dwordx4 v[86:87], v[78:81], off
	global_load_dwordx4 v[78:81], v[86:87], off offset:64
	s_waitcnt vmcnt(0) lgkmcnt(0)
	v_pk_add_f32 v[76:77], v[76:77], v[80:81]
	v_pk_add_f32 v[74:75], v[74:75], v[78:79]
	global_store_dwordx4 v[86:87], v[74:77], off offset:64
	global_load_dwordx4 v[74:77], v[86:87], off offset:512
	s_waitcnt vmcnt(0) lgkmcnt(0)
	v_pk_add_f32 v[72:73], v[72:73], v[76:77]
	v_pk_add_f32 v[70:71], v[70:71], v[74:75]
	global_store_dwordx4 v[86:87], v[70:73], off offset:512
	global_load_dwordx4 v[70:73], v[86:87], off offset:576
	s_waitcnt vmcnt(0) lgkmcnt(0)
;     __device__ __forceinline__ void operator()(AccT acc, const Unit& u, int wr, int wc, int fr, int fq) const {
;         const int row0 = u.pm * BM + wr * 64 + fr, col0 = u.pn * BM + wc * 32 + 4 * fq;
; #pragma unroll
;         for (int ai = 0; ai < 2; ++ai)
; #pragma unroll
;             for (int m = 0; m < 4; ++m) { const size_t off = (size_t)(row0 + ai * HALF + m * 16) * D_ + col0;
; #pragma unroll
;                 for (int bj = 0; bj < 2; ++bj)
; #pragma unroll
;                     for (int n = 0; n < 2; ++n) { const f32x4 bs = *(const f32x4*)(xin + off + bj * HALF + n * 16); *(f32x4*)(xout + off + bj * HALF + n * 16) = bs + acc[ai][bj][m][n] * scale; }
;                 asm volatile("" ::: "memory"); }
	v_pk_add_f32 v[68:69], v[68:69], v[72:73]
	v_pk_add_f32 v[66:67], v[66:67], v[70:71]
	global_store_dwordx4 v[86:87], v[66:69], off offset:576
	v_add_co_u32_e32 v72, vcc, s70, v154
	v_lshl_add_u64 v[70:71], v[154:155], 0, s[18:19]
	s_nop 0
	v_addc_co_u32_e32 v73, vcc, 0, v155, vcc
	global_load_dwordx4 v[66:69], v[72:73], off
	s_mov_b64 s[18:19], 0x90000
	s_waitcnt vmcnt(0) lgkmcnt(0)
	v_pk_add_f32 v[64:65], v[64:65], v[68:69]
	v_pk_add_f32 v[62:63], v[62:63], v[66:67]
	global_store_dwordx4 v[72:73], v[62:65], off
	global_load_dwordx4 v[62:65], v[70:71], off offset:64
	s_waitcnt vmcnt(0) lgkmcnt(0)
	v_pk_add_f32 v[60:61], v[60:61], v[64:65]
	v_pk_add_f32 v[58:59], v[58:59], v[62:63]
	global_store_dwordx4 v[70:71], v[58:61], off offset:64
	global_load_dwordx4 v[58:61], v[70:71], off offset:512
	s_waitcnt vmcnt(0) lgkmcnt(0)
	v_pk_add_f32 v[56:57], v[56:57], v[60:61]
	v_pk_add_f32 v[54:55], v[54:55], v[58:59]
	global_store_dwordx4 v[70:71], v[54:57], off offset:512
	global_load_dwordx4 v[54:57], v[70:71], off offset:576
	s_waitcnt vmcnt(0) lgkmcnt(0)
	v_pk_add_f32 v[52:53], v[52:53], v[56:57]
	v_pk_add_f32 v[50:51], v[50:51], v[54:55]
	global_store_dwordx4 v[70:71], v[50:53], off offset:576
	v_add_co_u32_e32 v56, vcc, s71, v154
	v_lshl_add_u64 v[54:55], v[154:155], 0, s[18:19]
	s_nop 0
	v_addc_co_u32_e32 v57, vcc, 0, v155, vcc
	global_load_dwordx4 v[50:53], v[56:57], off
	s_mov_b64 s[18:19], 0xa0000
	s_waitcnt vmcnt(0) lgkmcnt(0)
	v_pk_add_f32 v[48:49], v[48:49], v[52:53]
	v_pk_add_f32 v[46:47], v[46:47], v[50:51]
	global_store_dwordx4 v[56:57], v[46:49], off
	global_load_dwordx4 v[46:49], v[54:55], off offset:64
	s_waitcnt vmcnt(0) lgkmcnt(0)
	v_pk_add_f32 v[44:45], v[44:45], v[48:49]
	v_pk_add_f32 v[42:43], v[42:43], v[46:47]
	global_store_dwordx4 v[54:55], v[42:45], off offset:64
	global_load_dwordx4 v[42:45], v[54:55], off offset:512
	s_waitcnt vmcnt(0) lgkmcnt(0)
	v_pk_add_f32 v[40:41], v[40:41], v[44:45]
	v_pk_add_f32 v[38:39], v[38:39], v[42:43]
	global_store_dwordx4 v[54:55], v[38:41], off offset:512
	global_load_dwordx4 v[38:41], v[54:55], off offset:576
	s_waitcnt vmcnt(0) lgkmcnt(0)
	v_pk_add_f32 v[36:37], v[36:37], v[40:41]
	v_pk_add_f32 v[34:35], v[34:35], v[38:39]
	global_store_dwordx4 v[54:55], v[34:37], off offset:576
	v_add_co_u32_e32 v40, vcc, s72, v154
	v_lshl_add_u64 v[38:39], v[154:155], 0, s[18:19]
	s_nop 0
	v_addc_co_u32_e32 v41, vcc, 0, v155, vcc
	global_load_dwordx4 v[34:37], v[40:41], off
	s_mov_b64 s[18:19], 0xb0000
	s_waitcnt vmcnt(0) lgkmcnt(0)
	v_pk_add_f32 v[32:33], v[32:33], v[36:37]
	v_pk_add_f32 v[30:31], v[30:31], v[34:35]
	global_store_dwordx4 v[40:41], v[30:33], off
	global_load_dwordx4 v[30:33], v[38:39], off offset:64
	s_waitcnt vmcnt(0) lgkmcnt(0)
	v_pk_add_f32 v[28:29], v[28:29], v[32:33]
	v_pk_add_f32 v[26:27], v[26:27], v[30:31]
	global_store_dwordx4 v[38:39], v[26:29], off offset:64
	global_load_dwordx4 v[26:29], v[38:39], off offset:512
	s_waitcnt vmcnt(0) lgkmcnt(0)
	v_pk_add_f32 v[24:25], v[24:25], v[28:29]
	v_pk_add_f32 v[22:23], v[22:23], v[26:27]
	global_store_dwordx4 v[38:39], v[22:25], off offset:512
	global_load_dwordx4 v[22:25], v[38:39], off offset:576
	s_waitcnt vmcnt(0) lgkmcnt(0)
	v_pk_add_f32 v[20:21], v[20:21], v[24:25]
	v_pk_add_f32 v[18:19], v[18:19], v[22:23]
	v_lshl_add_u64 v[22:23], v[154:155], 0, s[18:19]
	s_mov_b32 s18, 0xb0000
	global_store_dwordx4 v[38:39], v[18:21], off offset:576
	v_add_co_u32_e32 v24, vcc, s18, v154
	s_mov_b64 s[18:19], -1
	s_nop 0
	v_addc_co_u32_e32 v25, vcc, 0, v155, vcc
	global_load_dwordx4 v[18:21], v[24:25], off
	s_and_b64 vcc, exec, s[2:3]
	s_waitcnt vmcnt(0) lgkmcnt(0)
	v_pk_add_f32 v[16:17], v[16:17], v[20:21]
	v_pk_add_f32 v[14:15], v[14:15], v[18:19]
	global_store_dwordx4 v[24:25], v[14:17], off
	global_load_dwordx4 v[14:17], v[22:23], off offset:64
	s_waitcnt vmcnt(0) lgkmcnt(0)
	v_pk_add_f32 v[12:13], v[12:13], v[16:17]
	v_pk_add_f32 v[10:11], v[10:11], v[14:15]
	global_store_dwordx4 v[22:23], v[10:13], off offset:64
	global_load_dwordx4 v[10:13], v[22:23], off offset:512
	s_waitcnt vmcnt(0) lgkmcnt(0)
	v_pk_add_f32 v[8:9], v[8:9], v[12:13]
	v_pk_add_f32 v[6:7], v[6:7], v[10:11]
	global_store_dwordx4 v[22:23], v[6:9], off offset:512
	global_load_dwordx4 v[6:9], v[22:23], off offset:576
	s_waitcnt vmcnt(0) lgkmcnt(0)
	v_pk_add_f32 v[4:5], v[4:5], v[8:9]
	v_pk_add_f32 v[2:3], v[2:3], v[6:7]
	global_store_dwordx4 v[22:23], v[2:5], off offset:576
	s_cbranch_vccnz .LBB0_93
	s_andn2_b64 vcc, exec, s[10:11]
	s_cbranch_vccnz .LBB0_92
	s_barrier
	s_branch .LBB0_92

; __device__ __forceinline__ uint4 pack_acc8(const f32x4 a, const f32x4 b, float s) { uint4 w; w.x = cvt_pk_bf16(a[0] * s, a[1] * s); w.y = cvt_pk_bf16(a[2] * s, a[3] * s); w.z = cvt_pk_bf16(b[0] * s, b[1] * s); w.w = cvt_pk_bf16(b[2] * s, b[3] * s); return w; }
;     __device__ __forceinline__ void operator()(AccM acc, const Unit& u, int wr, int wc, int fr, int fq) const {
;         const int row0 = u.pm * BM + wr * 64 + fr, col0 = u.pn * HALF + wc * 32 + 8 * fq;
;         const bf16_t* gb = G + (size_t)row0 * 3072 + u.z * 1024 + col0;
;         bf16_t* mb = MB + (size_t)row0 * D_ + col0;
;         const int z = u.z;
; #pragma unroll
;         for (int ai = 0; ai < 2; ++ai)
; #pragma unroll
;             for (int m = 0; m < 4; ++m) {
;                 const u32x4 gr_ = __builtin_nontemporal_load((const u32x4*)(gb + (size_t)(ai * HALF + m * 16) * 3072)); const uint4 gr = make_uint4(gr_[0], gr_[1], gr_[2], gr_[3]); float gf[8]; unpack8(gr, gf);
;                 f32x4 v0, v1;
; #pragma unroll
;                 for (int j = 0; j < 4; ++j) { v0[j] = gf[j] * acc[ai][0][m][0][j]; v1[j] = gf[4 + j] * acc[ai][0][m][1][j]; }
;                 if (z > 0) { v0 += acc[ai][1][m][0]; v1 += acc[ai][1][m][1]; }
;                 acc[ai][1][m][0] = v0; acc[ai][1][m][1] = v1;
;                 if (z == 2) *(uint4*)(mb + (size_t)(ai * HALF + m * 16) * D_) = pack_acc8(v0, v1, 1.0f);
;                 asm volatile("" ::: "memory");
;             }
.LBB0_141:
	v_readlane_b32 s4, v254, 35
	v_readlane_b32 s5, v254, 36
	v_lshl_add_u32 v138, s64, 8, v162
	v_lshl_or_b32 v158, s63, 7, v164
	v_mov_b64_e32 v[160:161], s[4:5]
	s_movk_i32 s4, 0x1800
	v_mad_i64_i32 v[160:161], s[4:5], v138, s4, v[160:161]
	s_lshl_b32 s4, s65, 10
	s_ashr_i32 s5, s4, 31
	v_ashrrev_i32_e32 v159, 31, v158
	v_lshl_add_u64 v[160:161], s[4:5], 1, v[160:161]
	v_lshlrev_b64 v[158:159], 1, v[158:159]
	v_lshl_add_u64 v[160:161], v[160:161], 0, v[158:159]
	global_load_dwordx4 v[180:183], v[160:161], off nt
	v_ashrrev_i32_e32 v139, 31, v138
	v_readlane_b32 s4, v254, 33
	v_lshlrev_b64 v[138:139], 11, v[138:139]
	v_readlane_b32 s5, v254, 34
	s_cmp_gt_i32 s65, 0
	s_waitcnt vmcnt(0) lgkmcnt(0)
	v_lshlrev_b32_e32 v166, 16, v182
	v_lshl_add_u64 v[138:139], s[4:5], 0, v[138:139]
	v_lshl_add_u64 v[158:159], v[138:139], 0, v[158:159]
	v_lshlrev_b32_e32 v138, 16, v180
	v_and_b32_e32 v139, 0xffff0000, v180
	v_and_b32_e32 v167, 0xffff0000, v182
	v_lshlrev_b32_e32 v178, 16, v181
	v_and_b32_e32 v179, 0xffff0000, v181
	v_lshlrev_b32_e32 v180, 16, v183
	v_and_b32_e32 v181, 0xffff0000, v183
	v_pk_mul_f32 v[182:183], v[64:65], v[180:181]
	v_pk_fma_f32 v[64:65], v[64:65], v[180:181], v[156:157]
	s_cselect_b64 s[4:5], -1, 0
	s_cmp_eq_u32 s65, 2
	v_pk_mul_f32 v[180:181], v[58:59], v[138:139]
	v_pk_mul_f32 v[184:185], v[62:63], v[166:167]
	v_pk_mul_f32 v[186:187], v[60:61], v[178:179]
	v_pk_fma_f32 v[60:61], v[60:61], v[178:179], v[154:155]
	v_pk_fma_f32 v[58:59], v[58:59], v[138:139], v[152:153]
	v_pk_fma_f32 v[62:63], v[62:63], v[166:167], v[150:151]
	s_cselect_b64 s[24:25], -1, 0
	s_cmp_lg_u32 s65, 2
	v_cndmask_b32_e64 v157, v183, v65, s[4:5]
	v_cndmask_b32_e64 v156, v182, v64, s[4:5]
	v_cndmask_b32_e64 v151, v185, v63, s[4:5]
	v_cndmask_b32_e64 v150, v184, v62, s[4:5]
	v_cndmask_b32_e64 v155, v187, v61, s[4:5]
	v_cndmask_b32_e64 v154, v186, v60, s[4:5]
	v_cndmask_b32_e64 v153, v181, v59, s[4:5]
	v_cndmask_b32_e64 v152, v180, v58, s[4:5]
	s_cbranch_scc1 .LBB0_143
	v_cvt_pk_bf16_f32 v58, v152, v153
	v_cvt_pk_bf16_f32 v59, v154, v155
	v_cvt_pk_bf16_f32 v60, v150, v151
	v_cvt_pk_bf16_f32 v61, v156, v157
	global_store_dwordx4 v[158:159], v[58:61], off
.LBB0_143:
	s_nop 1
	v_add_co_u32_e32 v58, vcc, 0x18000, v160
	v_cndmask_b32_e64 v62, 0, 1, s[24:25]
	s_nop 0
	v_addc_co_u32_e32 v59, vcc, 0, v161, vcc
	global_load_dwordx4 v[58:61], v[58:59], off nt
	v_cmp_ne_u32_e64 s[6:7], 1, v62
	s_andn2_b64 vcc, exec, s[24:25]
	s_waitcnt vmcnt(0) lgkmcnt(0)
	v_lshlrev_b32_e32 v62, 16, v58
	v_and_b32_e32 v63, 0xffff0000, v58
	v_lshlrev_b32_e32 v64, 16, v60
	v_and_b32_e32 v65, 0xffff0000, v60
	v_lshlrev_b32_e32 v58, 16, v59
	v_and_b32_e32 v59, 0xffff0000, v59
	v_lshlrev_b32_e32 v60, 16, v61
	v_and_b32_e32 v61, 0xffff0000, v61
	v_pk_mul_f32 v[138:139], v[54:55], v[62:63]
	v_pk_mul_f32 v[166:167], v[50:51], v[64:65]
	v_pk_mul_f32 v[178:179], v[56:57], v[58:59]
	v_pk_mul_f32 v[180:181], v[52:53], v[60:61]
	v_pk_fma_f32 v[56:57], v[56:57], v[58:59], v[148:149]
	v_pk_fma_f32 v[54:55], v[54:55], v[62:63], v[128:129]
	v_pk_fma_f32 v[52:53], v[52:53], v[60:61], v[122:123]
	v_pk_fma_f32 v[50:51], v[50:51], v[64:65], v[120:121]
	v_cndmask_b32_e64 v123, v181, v53, s[4:5]
	v_cndmask_b32_e64 v122, v180, v52, s[4:5]
	v_cndmask_b32_e64 v121, v167, v51, s[4:5]
	v_cndmask_b32_e64 v120, v166, v50, s[4:5]
	v_cndmask_b32_e64 v149, v179, v57, s[4:5]
	v_cndmask_b32_e64 v148, v178, v56, s[4:5]
	v_cndmask_b32_e64 v129, v139, v55, s[4:5]
	v_cndmask_b32_e64 v128, v138, v54, s[4:5]
	s_cbranch_vccnz .LBB0_145
	v_add_co_u32_e32 v54, vcc, 0x8000, v158
	v_cvt_pk_bf16_f32 v50, v128, v129
	v_cvt_pk_bf16_f32 v51, v148, v149
	v_cvt_pk_bf16_f32 v52, v120, v121
	v_cvt_pk_bf16_f32 v53, v122, v123
	v_addc_co_u32_e32 v55, vcc, 0, v159, vcc
	global_store_dwordx4 v[54:55], v[50:53], off
.LBB0_145:
	s_nop 1
	v_add_co_u32_e32 v50, vcc, 0x30000, v160
	s_nop 1
	v_addc_co_u32_e32 v51, vcc, 0, v161, vcc
	global_load_dwordx4 v[50:53], v[50:51], off nt
	s_and_b64 vcc, exec, s[6:7]
	s_waitcnt vmcnt(0) lgkmcnt(0)
	v_lshlrev_b32_e32 v54, 16, v50
	v_and_b32_e32 v55, 0xffff0000, v50
	v_lshlrev_b32_e32 v56, 16, v52
	v_and_b32_e32 v57, 0xffff0000, v52
	v_lshlrev_b32_e32 v50, 16, v51
	v_and_b32_e32 v51, 0xffff0000, v51
	v_lshlrev_b32_e32 v52, 16, v53
	v_and_b32_e32 v53, 0xffff0000, v53
	v_pk_mul_f32 v[58:59], v[46:47], v[54:55]
	v_pk_mul_f32 v[60:61], v[42:43], v[56:57]
	v_pk_mul_f32 v[62:63], v[48:49], v[50:51]
	v_pk_mul_f32 v[64:65], v[44:45], v[52:53]
	v_pk_fma_f32 v[48:49], v[48:49], v[50:51], v[126:127]
	v_pk_fma_f32 v[46:47], v[46:47], v[54:55], v[124:125]
	v_pk_fma_f32 v[44:45], v[44:45], v[52:53], v[114:115]
	v_pk_fma_f32 v[42:43], v[42:43], v[56:57], v[112:113]
	v_cndmask_b32_e64 v115, v65, v45, s[4:5]
	v_cndmask_b32_e64 v114, v64, v44, s[4:5]
	v_cndmask_b32_e64 v113, v61, v43, s[4:5]
	v_cndmask_b32_e64 v112, v60, v42, s[4:5]
	v_cndmask_b32_e64 v127, v63, v49, s[4:5]
	v_cndmask_b32_e64 v126, v62, v48, s[4:5]
	v_cndmask_b32_e64 v125, v59, v47, s[4:5]
	v_cndmask_b32_e64 v124, v58, v46, s[4:5]
	s_cbranch_vccnz .LBB0_147
	v_add_co_u32_e32 v46, vcc, 0x10000, v158
	v_cvt_pk_bf16_f32 v42, v124, v125
	v_cvt_pk_bf16_f32 v43, v126, v127
	v_cvt_pk_bf16_f32 v44, v112, v113
	v_cvt_pk_bf16_f32 v45, v114, v115
	v_addc_co_u32_e32 v47, vcc, 0, v159, vcc
	global_store_dwordx4 v[46:47], v[42:45], off
; __device__ __forceinline__ uint4 pack_acc8(const f32x4 a, const f32x4 b, float s) { uint4 w; w.x = cvt_pk_bf16(a[0] * s, a[1] * s); w.y = cvt_pk_bf16(a[2] * s, a[3] * s); w.z = cvt_pk_bf16(b[0] * s, b[1] * s); w.w = cvt_pk_bf16(b[2] * s, b[3] * s); return w; }
;     __device__ __forceinline__ void operator()(AccM acc, const Unit& u, int wr, int wc, int fr, int fq) const {
;     ...
;                 const u32x4 gr_ = __builtin_nontemporal_load((const u32x4*)(gb + (size_t)(ai * HALF + m * 16) * 3072)); const uint4 gr = make_uint4(gr_[0], gr_[1], gr_[2], gr_[3]); float gf[8]; unpack8(gr, gf);
;                 f32x4 v0, v1;
; #pragma unroll
;                 for (int j = 0; j < 4; ++j) { v0[j] = gf[j] * acc[ai][0][m][0][j]; v1[j] = gf[4 + j] * acc[ai][0][m][1][j]; }
;                 if (z > 0) { v0 += acc[ai][1][m][0]; v1 += acc[ai][1][m][1]; }
;                 acc[ai][1][m][0] = v0; acc[ai][1][m][1] = v1;
;                 if (z == 2) *(uint4*)(mb + (size_t)(ai * HALF + m * 16) * D_) = pack_acc8(v0, v1, 1.0f);
.LBB0_147:
	s_nop 1
	v_add_co_u32_e32 v42, vcc, 0x48000, v160
	s_nop 1
	v_addc_co_u32_e32 v43, vcc, 0, v161, vcc
	global_load_dwordx4 v[42:45], v[42:43], off nt
	s_and_b64 vcc, exec, s[6:7]
	s_waitcnt vmcnt(0) lgkmcnt(0)
	v_lshlrev_b32_e32 v46, 16, v42
	v_and_b32_e32 v47, 0xffff0000, v42
	v_lshlrev_b32_e32 v48, 16, v44
	v_and_b32_e32 v49, 0xffff0000, v44
	v_lshlrev_b32_e32 v42, 16, v43
	v_and_b32_e32 v43, 0xffff0000, v43
	v_lshlrev_b32_e32 v44, 16, v45
	v_and_b32_e32 v45, 0xffff0000, v45
	v_pk_mul_f32 v[50:51], v[38:39], v[46:47]
	v_pk_mul_f32 v[52:53], v[34:35], v[48:49]
	v_pk_mul_f32 v[54:55], v[40:41], v[42:43]
	v_pk_mul_f32 v[56:57], v[36:37], v[44:45]
	v_pk_fma_f32 v[40:41], v[40:41], v[42:43], v[118:119]
	v_pk_fma_f32 v[38:39], v[38:39], v[46:47], v[116:117]
	v_pk_fma_f32 v[36:37], v[36:37], v[44:45], v[106:107]
	v_pk_fma_f32 v[34:35], v[34:35], v[48:49], v[104:105]
	v_cndmask_b32_e64 v107, v57, v37, s[4:5]
	v_cndmask_b32_e64 v106, v56, v36, s[4:5]
	v_cndmask_b32_e64 v105, v53, v35, s[4:5]
	v_cndmask_b32_e64 v104, v52, v34, s[4:5]
	v_cndmask_b32_e64 v119, v55, v41, s[4:5]
	v_cndmask_b32_e64 v118, v54, v40, s[4:5]
	v_cndmask_b32_e64 v117, v51, v39, s[4:5]
	v_cndmask_b32_e64 v116, v50, v38, s[4:5]
	s_cbranch_vccnz .LBB0_149
	v_add_co_u32_e32 v38, vcc, 0x18000, v158
	v_cvt_pk_bf16_f32 v34, v116, v117
	v_cvt_pk_bf16_f32 v35, v118, v119
	v_cvt_pk_bf16_f32 v36, v104, v105
	v_cvt_pk_bf16_f32 v37, v106, v107
	v_addc_co_u32_e32 v39, vcc, 0, v159, vcc
	global_store_dwordx4 v[38:39], v[34:37], off
.LBB0_149:
	s_nop 1
	v_add_co_u32_e32 v34, vcc, 0xc0000, v160
	s_nop 1
	v_addc_co_u32_e32 v35, vcc, 0, v161, vcc
	global_load_dwordx4 v[34:37], v[34:35], off nt
	s_and_b64 vcc, exec, s[6:7]
	s_waitcnt vmcnt(0) lgkmcnt(0)
	v_lshlrev_b32_e32 v38, 16, v34
	v_and_b32_e32 v39, 0xffff0000, v34
	v_lshlrev_b32_e32 v40, 16, v36
	v_and_b32_e32 v41, 0xffff0000, v36
	v_lshlrev_b32_e32 v34, 16, v35
	v_and_b32_e32 v35, 0xffff0000, v35
	v_lshlrev_b32_e32 v36, 16, v37
	v_and_b32_e32 v37, 0xffff0000, v37
	v_pk_mul_f32 v[42:43], v[30:31], v[38:39]
	v_pk_mul_f32 v[44:45], v[26:27], v[40:41]
	v_pk_mul_f32 v[46:47], v[32:33], v[34:35]
	v_pk_mul_f32 v[48:49], v[28:29], v[36:37]
	v_pk_fma_f32 v[32:33], v[32:33], v[34:35], v[110:111]
	v_pk_fma_f32 v[30:31], v[30:31], v[38:39], v[108:109]
	v_pk_fma_f32 v[28:29], v[28:29], v[36:37], v[98:99]
	v_pk_fma_f32 v[26:27], v[26:27], v[40:41], v[96:97]
	v_cndmask_b32_e64 v99, v49, v29, s[4:5]
	v_cndmask_b32_e64 v98, v48, v28, s[4:5]
	v_cndmask_b32_e64 v97, v45, v27, s[4:5]
	v_cndmask_b32_e64 v96, v44, v26, s[4:5]
	v_cndmask_b32_e64 v111, v47, v33, s[4:5]
	v_cndmask_b32_e64 v110, v46, v32, s[4:5]
	v_cndmask_b32_e64 v109, v43, v31, s[4:5]
	v_cndmask_b32_e64 v108, v42, v30, s[4:5]
	s_cbranch_vccnz .LBB0_151
	v_add_co_u32_e32 v30, vcc, 0x40000, v158
	v_cvt_pk_bf16_f32 v26, v108, v109
	v_cvt_pk_bf16_f32 v27, v110, v111
	v_cvt_pk_bf16_f32 v28, v96, v97
	v_cvt_pk_bf16_f32 v29, v98, v99
	v_addc_co_u32_e32 v31, vcc, 0, v159, vcc
	global_store_dwordx4 v[30:31], v[26:29], off
; __device__ __forceinline__ uint4 pack_acc8(const f32x4 a, const f32x4 b, float s) { uint4 w; w.x = cvt_pk_bf16(a[0] * s, a[1] * s); w.y = cvt_pk_bf16(a[2] * s, a[3] * s); w.z = cvt_pk_bf16(b[0] * s, b[1] * s); w.w = cvt_pk_bf16(b[2] * s, b[3] * s); return w; }
;     __device__ __forceinline__ void operator()(AccM acc, const Unit& u, int wr, int wc, int fr, int fq) const {
;     ...
;                 const u32x4 gr_ = __builtin_nontemporal_load((const u32x4*)(gb + (size_t)(ai * HALF + m * 16) * 3072)); const uint4 gr = make_uint4(gr_[0], gr_[1], gr_[2], gr_[3]); float gf[8]; unpack8(gr, gf);
;                 f32x4 v0, v1;
; #pragma unroll
;                 for (int j = 0; j < 4; ++j) { v0[j] = gf[j] * acc[ai][0][m][0][j]; v1[j] = gf[4 + j] * acc[ai][0][m][1][j]; }
;                 if (z > 0) { v0 += acc[ai][1][m][0]; v1 += acc[ai][1][m][1]; }
;                 acc[ai][1][m][0] = v0; acc[ai][1][m][1] = v1;
;                 if (z == 2) *(uint4*)(mb + (size_t)(ai * HALF + m * 16) * D_) = pack_acc8(v0, v1, 1.0f);
.LBB0_151:
	s_nop 1
	v_add_co_u32_e32 v26, vcc, 0xd8000, v160
	s_nop 1
	v_addc_co_u32_e32 v27, vcc, 0, v161, vcc
	global_load_dwordx4 v[26:29], v[26:27], off nt
	s_and_b64 vcc, exec, s[6:7]
	s_waitcnt vmcnt(0) lgkmcnt(0)
	v_lshlrev_b32_e32 v30, 16, v26
	v_and_b32_e32 v31, 0xffff0000, v26
	v_lshlrev_b32_e32 v32, 16, v28
	v_and_b32_e32 v33, 0xffff0000, v28
	v_lshlrev_b32_e32 v26, 16, v27
	v_and_b32_e32 v27, 0xffff0000, v27
	v_lshlrev_b32_e32 v28, 16, v29
	v_and_b32_e32 v29, 0xffff0000, v29
	v_pk_mul_f32 v[34:35], v[22:23], v[30:31]
	v_pk_mul_f32 v[36:37], v[18:19], v[32:33]
	v_pk_mul_f32 v[38:39], v[24:25], v[26:27]
	v_pk_mul_f32 v[40:41], v[20:21], v[28:29]
	v_pk_fma_f32 v[24:25], v[24:25], v[26:27], v[102:103]
	v_pk_fma_f32 v[22:23], v[22:23], v[30:31], v[100:101]
	v_pk_fma_f32 v[20:21], v[20:21], v[28:29], v[90:91]
	v_pk_fma_f32 v[18:19], v[18:19], v[32:33], v[88:89]
	v_cndmask_b32_e64 v91, v41, v21, s[4:5]
	v_cndmask_b32_e64 v90, v40, v20, s[4:5]
	v_cndmask_b32_e64 v89, v37, v19, s[4:5]
	v_cndmask_b32_e64 v88, v36, v18, s[4:5]
	v_cndmask_b32_e64 v103, v39, v25, s[4:5]
	v_cndmask_b32_e64 v102, v38, v24, s[4:5]
	v_cndmask_b32_e64 v101, v35, v23, s[4:5]
	v_cndmask_b32_e64 v100, v34, v22, s[4:5]
	s_cbranch_vccnz .LBB0_153
	v_add_co_u32_e32 v22, vcc, 0x48000, v158
	v_cvt_pk_bf16_f32 v18, v100, v101
	v_cvt_pk_bf16_f32 v19, v102, v103
	v_cvt_pk_bf16_f32 v20, v88, v89
	v_cvt_pk_bf16_f32 v21, v90, v91
	v_addc_co_u32_e32 v23, vcc, 0, v159, vcc
	global_store_dwordx4 v[22:23], v[18:21], off
.LBB0_153:
	s_nop 1
	v_add_co_u32_e32 v18, vcc, 0xf0000, v160
	s_nop 1
	v_addc_co_u32_e32 v19, vcc, 0, v161, vcc
	global_load_dwordx4 v[18:21], v[18:19], off nt
	s_and_b64 vcc, exec, s[6:7]
	s_waitcnt vmcnt(0) lgkmcnt(0)
	v_lshlrev_b32_e32 v22, 16, v18
	v_and_b32_e32 v23, 0xffff0000, v18
	v_lshlrev_b32_e32 v24, 16, v20
	v_and_b32_e32 v25, 0xffff0000, v20
	v_lshlrev_b32_e32 v18, 16, v19
	v_and_b32_e32 v19, 0xffff0000, v19
	v_lshlrev_b32_e32 v20, 16, v21
	v_and_b32_e32 v21, 0xffff0000, v21
	v_pk_mul_f32 v[26:27], v[14:15], v[22:23]
	v_pk_mul_f32 v[28:29], v[10:11], v[24:25]
	v_pk_mul_f32 v[30:31], v[16:17], v[18:19]
	v_pk_mul_f32 v[32:33], v[12:13], v[20:21]
	v_pk_fma_f32 v[16:17], v[16:17], v[18:19], v[94:95]
	v_pk_fma_f32 v[14:15], v[14:15], v[22:23], v[92:93]
	v_pk_fma_f32 v[12:13], v[12:13], v[20:21], v[82:83]
	v_pk_fma_f32 v[10:11], v[10:11], v[24:25], v[80:81]
	v_cndmask_b32_e64 v83, v33, v13, s[4:5]
	v_cndmask_b32_e64 v82, v32, v12, s[4:5]
	v_cndmask_b32_e64 v81, v29, v11, s[4:5]
	v_cndmask_b32_e64 v80, v28, v10, s[4:5]
	v_cndmask_b32_e64 v95, v31, v17, s[4:5]
	v_cndmask_b32_e64 v94, v30, v16, s[4:5]
	v_cndmask_b32_e64 v93, v27, v15, s[4:5]
	v_cndmask_b32_e64 v92, v26, v14, s[4:5]
	s_cbranch_vccnz .LBB0_155
	v_add_co_u32_e32 v14, vcc, 0x50000, v158
	v_cvt_pk_bf16_f32 v10, v92, v93
	v_cvt_pk_bf16_f32 v11, v94, v95
	v_cvt_pk_bf16_f32 v12, v80, v81
	v_cvt_pk_bf16_f32 v13, v82, v83
	v_addc_co_u32_e32 v15, vcc, 0, v159, vcc
	global_store_dwordx4 v[14:15], v[10:13], off
.LBB0_155:
	s_nop 1
	v_add_co_u32_e32 v10, vcc, 0x108000, v160
	s_nop 1
	v_addc_co_u32_e32 v11, vcc, 0, v161, vcc
	global_load_dwordx4 v[10:13], v[10:11], off nt
	s_and_b64 vcc, exec, s[6:7]
	s_waitcnt vmcnt(0) lgkmcnt(0)
	v_lshlrev_b32_e32 v14, 16, v10
	v_and_b32_e32 v15, 0xffff0000, v10
	v_lshlrev_b32_e32 v16, 16, v12
	v_and_b32_e32 v17, 0xffff0000, v12
	v_lshlrev_b32_e32 v10, 16, v11
	v_and_b32_e32 v11, 0xffff0000, v11
	v_lshlrev_b32_e32 v12, 16, v13
	v_and_b32_e32 v13, 0xffff0000, v13
	v_pk_mul_f32 v[18:19], v[6:7], v[14:15]
	v_pk_mul_f32 v[20:21], v[2:3], v[16:17]
	v_pk_mul_f32 v[22:23], v[8:9], v[10:11]
	v_pk_mul_f32 v[24:25], v[4:5], v[12:13]
	v_pk_fma_f32 v[8:9], v[8:9], v[10:11], v[86:87]
	v_pk_fma_f32 v[6:7], v[6:7], v[14:15], v[84:85]
	v_pk_fma_f32 v[4:5], v[4:5], v[12:13], v[78:79]
	v_pk_fma_f32 v[2:3], v[2:3], v[16:17], v[76:77]
	v_cndmask_b32_e64 v79, v25, v5, s[4:5]
	v_cndmask_b32_e64 v78, v24, v4, s[4:5]
	v_cndmask_b32_e64 v77, v21, v3, s[4:5]
	v_cndmask_b32_e64 v76, v20, v2, s[4:5]
	v_cndmask_b32_e64 v87, v23, v9, s[4:5]
	v_cndmask_b32_e64 v86, v22, v8, s[4:5]
	v_cndmask_b32_e64 v85, v19, v7, s[4:5]
	v_cndmask_b32_e64 v84, v18, v6, s[4:5]
	s_cbranch_vccnz .LBB0_157
	v_add_co_u32_e32 v6, vcc, 0x58000, v158
	v_cvt_pk_bf16_f32 v2, v84, v85
	v_cvt_pk_bf16_f32 v3, v86, v87
	v_cvt_pk_bf16_f32 v4, v76, v77
	v_cvt_pk_bf16_f32 v5, v78, v79
	v_addc_co_u32_e32 v7, vcc, 0, v159, vcc
	global_store_dwordx4 v[6:7], v[2:5], off

; __device__ __forceinline__ uint4 pack8(const float (&f)[8]) { uint4 r; r.x = cvt_pk_bf16(f[0], f[1]); r.y = cvt_pk_bf16(f[2], f[3]); r.z = cvt_pk_bf16(f[4], f[5]); r.w = cvt_pk_bf16(f[6], f[7]); return r; }
; __device__ __forceinline__ void nt_store16(void* p, const uint4 v) { __builtin_nontemporal_store((u32x4){v.x, v.y, v.z, v.w}, (u32x4*)p); }
; __device__ __forceinline__ float sigmoid_(float x) { return __builtin_amdgcn_rcpf(1.0f + __expf(-x)); }
;     __device__ __forceinline__ void operator()(AccT acc, const Unit& u, int wr, int wc, int fr, int fq) const {
;         const int row0 = u.pm * BM + wr * 64 + fr, col0 = u.pn * BM + wc * 32 + 8 * fq;
; #pragma unroll
;         for (int ai = 0; ai < 2; ++ai)
; #pragma unroll
;             for (int m = 0; m < 4; ++m) { const size_t row = (size_t)(row0 + ai * HALF + m * 16);
; #pragma unroll
;                 for (int bj = 0; bj < 2; ++bj) { float o[8];
; #pragma unroll
;                     for (int n = 0; n < 2; ++n)
; #pragma unroll
;                         for (int j = 0; j < 4; ++j) o[n * 4 + j] = sigmoid_(acc[ai][bj][m][n][j]);
;                     nt_store16(G + row * 3072 + col0 + bj * HALF, pack8(o)); } }
.LBB0_180:
	v_mul_f32_e32 v126, 0xbfb8aa3b, v126
	v_mul_f32_e32 v122, 0xbfb8aa3b, v122
	v_exp_f32_e32 v126, v126
	v_mul_f32_e32 v127, 0xbfb8aa3b, v127
	v_exp_f32_e32 v122, v122
	v_mul_f32_e32 v123, 0xbfb8aa3b, v123
	v_exp_f32_e32 v127, v127
	v_exp_f32_e32 v123, v123
	v_add_f32_e32 v126, 1.0, v126
	v_add_f32_e32 v122, 1.0, v122
	v_rcp_f32_e32 v163, v126
	v_add_f32_e32 v126, 1.0, v127
	v_mul_f32_e32 v127, 0xbfb8aa3b, v128
	v_rcp_f32_e32 v165, v122
	v_add_f32_e32 v122, 1.0, v123
	v_mul_f32_e32 v123, 0xbfb8aa3b, v124
	v_exp_f32_e32 v127, v127
	v_mul_f32_e32 v128, 0xbfb8aa3b, v129
	v_exp_f32_e32 v123, v123
	v_mul_f32_e32 v124, 0xbfb8aa3b, v125
	v_exp_f32_e32 v128, v128
	v_exp_f32_e32 v124, v124
	v_rcp_f32_e32 v129, v126
	v_add_f32_e32 v126, 1.0, v127
	v_rcp_f32_e32 v166, v122
	v_add_f32_e32 v122, 1.0, v123
	v_rcp_f32_e32 v164, v126
	v_add_f32_e32 v126, 1.0, v128
	v_rcp_f32_e32 v167, v122
	v_add_f32_e32 v122, 1.0, v124
	v_mul_f32_e32 v114, 0xbfb8aa3b, v114
	v_rcp_f32_e32 v128, v126
	v_rcp_f32_e32 v178, v122
	v_readlane_b32 s18, v254, 35
	v_exp_f32_e32 v114, v114
	v_mul_f32_e32 v115, 0xbfb8aa3b, v115
	v_lshl_or_b32 v138, s59, 8, v160
	v_readlane_b32 s19, v254, 36
	v_exp_f32_e32 v115, v115
	v_lshl_add_u32 v162, s58, 8, v158
	v_ashrrev_i32_e32 v139, 31, v138
	v_mov_b64_e32 v[122:123], s[18:19]
	s_movk_i32 s20, 0x1800
	v_mad_i64_i32 v[126:127], s[18:19], v162, s20, v[122:123]
	v_lshlrev_b64 v[124:125], 1, v[138:139]
	v_lshl_add_u64 v[138:139], v[126:127], 0, v[124:125]
	v_cvt_pk_bf16_f32 v126, v163, v129
	v_cvt_pk_bf16_f32 v127, v164, v128
	v_cvt_pk_bf16_f32 v128, v165, v166
	v_cvt_pk_bf16_f32 v129, v167, v178
	v_add_f32_e32 v114, 1.0, v114
	global_store_dwordx4 v[138:139], v[126:129], off
	v_mul_f32_e32 v118, 0xbfb8aa3b, v118
	v_mul_f32_e32 v119, 0xbfb8aa3b, v119
	v_rcp_f32_e32 v126, v114
	v_add_f32_e32 v114, 1.0, v115
	v_mul_f32_e32 v115, 0xbfb8aa3b, v116
	v_mul_f32_e32 v120, 0xbfb8aa3b, v120
	v_mul_f32_e32 v121, 0xbfb8aa3b, v121
	v_exp_f32_e32 v115, v115
	v_mul_f32_e32 v116, 0xbfb8aa3b, v117
	v_exp_f32_e32 v118, v118
	v_exp_f32_e32 v119, v119
	v_exp_f32_e32 v120, v120
	v_exp_f32_e32 v121, v121
	v_exp_f32_e32 v116, v116
	v_rcp_f32_e32 v117, v114
	v_add_f32_e32 v114, 1.0, v115
	v_add_f32_e32 v118, 1.0, v118
	v_add_f32_e32 v119, 1.0, v119
	v_add_f32_e32 v120, 1.0, v120
	v_add_f32_e32 v121, 1.0, v121
	v_rcp_f32_e32 v127, v114
	v_add_f32_e32 v114, 1.0, v116
	v_mul_f32_e32 v110, 0xbfb8aa3b, v110
	v_mul_f32_e32 v106, 0xbfb8aa3b, v106
	v_rcp_f32_e32 v118, v118
	v_rcp_f32_e32 v119, v119
	v_rcp_f32_e32 v120, v120
	v_rcp_f32_e32 v121, v121
	v_rcp_f32_e32 v128, v114
	v_exp_f32_e32 v110, v110
	v_mul_f32_e32 v111, 0xbfb8aa3b, v111
	v_exp_f32_e32 v106, v106
	v_mul_f32_e32 v107, 0xbfb8aa3b, v107
	v_exp_f32_e32 v111, v111
	v_exp_f32_e32 v107, v107
	v_cvt_pk_bf16_f32 v114, v118, v119
	v_cvt_pk_bf16_f32 v115, v120, v121
	v_cvt_pk_bf16_f32 v116, v126, v117
	v_cvt_pk_bf16_f32 v117, v127, v128
	v_add_f32_e32 v110, 1.0, v110
	v_add_f32_e32 v106, 1.0, v106
	global_store_dwordx4 v[138:139], v[114:117], off offset:256
	v_mul_f32_e32 v98, 0xbfb8aa3b, v98
	v_exp_f32_e32 v98, v98
	v_rcp_f32_e32 v115, v110
	v_add_f32_e32 v110, 1.0, v111
	v_mul_f32_e32 v111, 0xbfb8aa3b, v112
	v_rcp_f32_e32 v117, v106
	v_add_f32_e32 v106, 1.0, v107
	v_mul_f32_e32 v107, 0xbfb8aa3b, v108
	v_exp_f32_e32 v111, v111
	v_mul_f32_e32 v112, 0xbfb8aa3b, v113
	v_exp_f32_e32 v107, v107
	v_mul_f32_e32 v108, 0xbfb8aa3b, v109
	v_exp_f32_e32 v112, v112
	v_exp_f32_e32 v108, v108
	v_rcp_f32_e32 v113, v110
	v_add_f32_e32 v110, 1.0, v111
	v_rcp_f32_e32 v109, v106
	v_add_f32_e32 v106, 1.0, v107
	v_rcp_f32_e32 v116, v110
	v_add_f32_e32 v110, 1.0, v112
	v_rcp_f32_e32 v118, v106
	v_add_f32_e32 v106, 1.0, v108
	v_rcp_f32_e32 v112, v110
	v_rcp_f32_e32 v119, v106
	v_mul_f32_e32 v99, 0xbfb8aa3b, v99
	v_exp_f32_e32 v99, v99
	v_or_b32_e32 v114, 16, v162
	v_mad_i64_i32 v[106:107], s[18:19], v114, s20, v[122:123]
	v_lshl_add_u64 v[110:111], v[106:107], 0, v[124:125]
	v_cvt_pk_bf16_f32 v106, v115, v113
	v_cvt_pk_bf16_f32 v107, v116, v112
	v_cvt_pk_bf16_f32 v108, v117, v109
	v_cvt_pk_bf16_f32 v109, v118, v119
	v_add_f32_e32 v98, 1.0, v98
	global_store_dwordx4 v[110:111], v[106:109], off
	v_mul_f32_e32 v102, 0xbfb8aa3b, v102
	v_mul_f32_e32 v103, 0xbfb8aa3b, v103
	v_rcp_f32_e32 v106, v98
	v_add_f32_e32 v98, 1.0, v99
	v_mul_f32_e32 v99, 0xbfb8aa3b, v100
	v_mul_f32_e32 v104, 0xbfb8aa3b, v104
	v_mul_f32_e32 v105, 0xbfb8aa3b, v105
	v_exp_f32_e32 v99, v99
	v_mul_f32_e32 v100, 0xbfb8aa3b, v101
	v_exp_f32_e32 v102, v102
	v_exp_f32_e32 v103, v103
	v_exp_f32_e32 v104, v104
	v_exp_f32_e32 v105, v105
	v_exp_f32_e32 v100, v100
	v_rcp_f32_e32 v101, v98
	v_add_f32_e32 v98, 1.0, v99
	v_add_f32_e32 v102, 1.0, v102
	v_add_f32_e32 v103, 1.0, v103
	v_add_f32_e32 v104, 1.0, v104
	v_add_f32_e32 v105, 1.0, v105
	v_rcp_f32_e32 v107, v98
	v_add_f32_e32 v98, 1.0, v100
	v_mul_f32_e32 v94, 0xbfb8aa3b, v94
	v_mul_f32_e32 v90, 0xbfb8aa3b, v90
	v_rcp_f32_e32 v102, v102
	v_rcp_f32_e32 v103, v103
	v_rcp_f32_e32 v104, v104
	v_rcp_f32_e32 v105, v105
	v_rcp_f32_e32 v108, v98
	v_exp_f32_e32 v94, v94
	v_mul_f32_e32 v95, 0xbfb8aa3b, v95
	v_exp_f32_e32 v90, v90
	v_mul_f32_e32 v91, 0xbfb8aa3b, v91
	v_exp_f32_e32 v95, v95
	v_exp_f32_e32 v91, v91
	v_cvt_pk_bf16_f32 v98, v102, v103
	v_cvt_pk_bf16_f32 v99, v104, v105
	v_cvt_pk_bf16_f32 v100, v106, v101
	v_cvt_pk_bf16_f32 v101, v107, v108
	v_add_f32_e32 v94, 1.0, v94
	v_add_f32_e32 v90, 1.0, v90
	global_store_dwordx4 v[110:111], v[98:101], off offset:256
	v_mul_f32_e32 v82, 0xbfb8aa3b, v82
	v_exp_f32_e32 v82, v82
	v_rcp_f32_e32 v99, v94
	v_add_f32_e32 v94, 1.0, v95
	v_mul_f32_e32 v95, 0xbfb8aa3b, v96
	v_rcp_f32_e32 v101, v90
; __device__ __forceinline__ float sigmoid_(float x) { return __builtin_amdgcn_rcpf(1.0f + __expf(-x)); }
; __device__ __forceinline__ uint4 pack8(const float (&f)[8]) { uint4 r; r.x = cvt_pk_bf16(f[0], f[1]); r.y = cvt_pk_bf16(f[2], f[3]); r.z = cvt_pk_bf16(f[4], f[5]); r.w = cvt_pk_bf16(f[6], f[7]); return r; }
; __device__ __forceinline__ void nt_store16(void* p, const uint4 v) { __builtin_nontemporal_store((u32x4){v.x, v.y, v.z, v.w}, (u32x4*)p); }
;     __device__ __forceinline__ void operator()(AccT acc, const Unit& u, int wr, int wc, int fr, int fq) const {
;     ...
;             for (int m = 0; m < 4; ++m) { const size_t row = (size_t)(row0 + ai * HALF + m * 16);
; #pragma unroll
;                 for (int bj = 0; bj < 2; ++bj) { float o[8];
; #pragma unroll
;                     for (int n = 0; n < 2; ++n)
; #pragma unroll
;                         for (int j = 0; j < 4; ++j) o[n * 4 + j] = sigmoid_(acc[ai][bj][m][n][j]);
;                     nt_store16(G + row * 3072 + col0 + bj * HALF, pack8(o)); } }
	v_add_f32_e32 v90, 1.0, v91
	v_mul_f32_e32 v91, 0xbfb8aa3b, v92
	v_exp_f32_e32 v95, v95
	v_mul_f32_e32 v96, 0xbfb8aa3b, v97
	v_exp_f32_e32 v91, v91
	v_mul_f32_e32 v92, 0xbfb8aa3b, v93
	v_exp_f32_e32 v96, v96
	v_exp_f32_e32 v92, v92
	v_rcp_f32_e32 v97, v94
	v_add_f32_e32 v94, 1.0, v95
	v_rcp_f32_e32 v93, v90
	v_add_f32_e32 v90, 1.0, v91
	v_rcp_f32_e32 v100, v94
	v_add_f32_e32 v94, 1.0, v96
	v_rcp_f32_e32 v102, v90
	v_add_f32_e32 v90, 1.0, v92
	v_rcp_f32_e32 v96, v94
	v_rcp_f32_e32 v103, v90
	v_mul_f32_e32 v83, 0xbfb8aa3b, v83
	v_exp_f32_e32 v83, v83
	v_or_b32_e32 v98, 32, v162
	v_mad_i64_i32 v[90:91], s[18:19], v98, s20, v[122:123]
	v_lshl_add_u64 v[94:95], v[90:91], 0, v[124:125]
	v_cvt_pk_bf16_f32 v90, v99, v97
	v_cvt_pk_bf16_f32 v91, v100, v96
	v_cvt_pk_bf16_f32 v92, v101, v93
	v_cvt_pk_bf16_f32 v93, v102, v103
	v_add_f32_e32 v82, 1.0, v82
	global_store_dwordx4 v[94:95], v[90:93], off
	v_mul_f32_e32 v86, 0xbfb8aa3b, v86
	v_mul_f32_e32 v87, 0xbfb8aa3b, v87
	v_rcp_f32_e32 v90, v82
	v_add_f32_e32 v82, 1.0, v83
	v_mul_f32_e32 v83, 0xbfb8aa3b, v84
	v_mul_f32_e32 v88, 0xbfb8aa3b, v88
	v_mul_f32_e32 v89, 0xbfb8aa3b, v89
	v_exp_f32_e32 v83, v83
	v_mul_f32_e32 v84, 0xbfb8aa3b, v85
	v_exp_f32_e32 v86, v86
	v_exp_f32_e32 v87, v87
	v_exp_f32_e32 v88, v88
	v_exp_f32_e32 v89, v89
	v_exp_f32_e32 v84, v84
	v_rcp_f32_e32 v85, v82
	v_add_f32_e32 v82, 1.0, v83
	v_add_f32_e32 v86, 1.0, v86
	v_add_f32_e32 v87, 1.0, v87
	v_add_f32_e32 v88, 1.0, v88
	v_add_f32_e32 v89, 1.0, v89
	v_rcp_f32_e32 v91, v82
	v_add_f32_e32 v82, 1.0, v84
	v_mul_f32_e32 v78, 0xbfb8aa3b, v78
	v_mul_f32_e32 v74, 0xbfb8aa3b, v74
	v_rcp_f32_e32 v86, v86
	v_rcp_f32_e32 v87, v87
	v_rcp_f32_e32 v88, v88
	v_rcp_f32_e32 v89, v89
	v_rcp_f32_e32 v92, v82
	v_exp_f32_e32 v78, v78
	v_mul_f32_e32 v79, 0xbfb8aa3b, v79
	v_exp_f32_e32 v74, v74
	v_mul_f32_e32 v75, 0xbfb8aa3b, v75
	v_exp_f32_e32 v79, v79
	v_exp_f32_e32 v75, v75
	v_cvt_pk_bf16_f32 v82, v86, v87
	v_cvt_pk_bf16_f32 v83, v88, v89
	v_cvt_pk_bf16_f32 v84, v90, v85
	v_cvt_pk_bf16_f32 v85, v91, v92
	v_add_f32_e32 v78, 1.0, v78
	v_add_f32_e32 v74, 1.0, v74
	global_store_dwordx4 v[94:95], v[82:85], off offset:256
	v_mul_f32_e32 v66, 0xbfb8aa3b, v66
	v_exp_f32_e32 v66, v66
	v_rcp_f32_e32 v83, v78
	v_add_f32_e32 v78, 1.0, v79
	v_mul_f32_e32 v79, 0xbfb8aa3b, v80
	v_rcp_f32_e32 v85, v74
	v_add_f32_e32 v74, 1.0, v75
	v_mul_f32_e32 v75, 0xbfb8aa3b, v76
	v_exp_f32_e32 v79, v79
	v_mul_f32_e32 v80, 0xbfb8aa3b, v81
	v_exp_f32_e32 v75, v75
	v_mul_f32_e32 v76, 0xbfb8aa3b, v77
	v_exp_f32_e32 v80, v80
	v_exp_f32_e32 v76, v76
	v_rcp_f32_e32 v81, v78
	v_add_f32_e32 v78, 1.0, v79
	v_rcp_f32_e32 v77, v74
	v_add_f32_e32 v74, 1.0, v75
	v_rcp_f32_e32 v84, v78
	v_add_f32_e32 v78, 1.0, v80
	v_rcp_f32_e32 v86, v74
	v_add_f32_e32 v74, 1.0, v76
	v_rcp_f32_e32 v80, v78
	v_rcp_f32_e32 v87, v74
	v_mul_f32_e32 v67, 0xbfb8aa3b, v67
	v_exp_f32_e32 v67, v67
	v_or_b32_e32 v82, 48, v162
	v_mad_i64_i32 v[74:75], s[18:19], v82, s20, v[122:123]
	v_lshl_add_u64 v[78:79], v[74:75], 0, v[124:125]
	v_cvt_pk_bf16_f32 v74, v83, v81
	v_cvt_pk_bf16_f32 v75, v84, v80
	v_cvt_pk_bf16_f32 v76, v85, v77
	v_cvt_pk_bf16_f32 v77, v86, v87
	v_add_f32_e32 v66, 1.0, v66
	global_store_dwordx4 v[78:79], v[74:77], off
	v_mul_f32_e32 v70, 0xbfb8aa3b, v70
	v_mul_f32_e32 v71, 0xbfb8aa3b, v71
	v_rcp_f32_e32 v74, v66
	v_add_f32_e32 v66, 1.0, v67
	v_mul_f32_e32 v67, 0xbfb8aa3b, v68
	v_mul_f32_e32 v72, 0xbfb8aa3b, v72
	v_mul_f32_e32 v73, 0xbfb8aa3b, v73
	v_exp_f32_e32 v67, v67
	v_mul_f32_e32 v68, 0xbfb8aa3b, v69
	v_exp_f32_e32 v70, v70
	v_exp_f32_e32 v71, v71
	v_exp_f32_e32 v72, v72
	v_exp_f32_e32 v73, v73
	v_exp_f32_e32 v68, v68
	v_rcp_f32_e32 v69, v66
	v_add_f32_e32 v66, 1.0, v67
	v_add_f32_e32 v70, 1.0, v70
	v_add_f32_e32 v71, 1.0, v71
	v_add_f32_e32 v72, 1.0, v72
	v_add_f32_e32 v73, 1.0, v73
	v_rcp_f32_e32 v75, v66
	v_add_f32_e32 v66, 1.0, v68
	v_mul_f32_e32 v62, 0xbfb8aa3b, v62
	v_mul_f32_e32 v58, 0xbfb8aa3b, v58
	v_rcp_f32_e32 v70, v70
	v_rcp_f32_e32 v71, v71
	v_rcp_f32_e32 v72, v72
	v_rcp_f32_e32 v73, v73
	v_rcp_f32_e32 v76, v66
	v_exp_f32_e32 v62, v62
	v_mul_f32_e32 v63, 0xbfb8aa3b, v63
	v_exp_f32_e32 v58, v58
	v_mul_f32_e32 v59, 0xbfb8aa3b, v59
	v_exp_f32_e32 v63, v63
	v_exp_f32_e32 v59, v59
	v_cvt_pk_bf16_f32 v66, v70, v71
	v_cvt_pk_bf16_f32 v67, v72, v73
	v_cvt_pk_bf16_f32 v68, v74, v69
	v_cvt_pk_bf16_f32 v69, v75, v76
	v_add_f32_e32 v62, 1.0, v62
	v_add_f32_e32 v58, 1.0, v58
	global_store_dwordx4 v[78:79], v[66:69], off offset:256
	v_mul_f32_e32 v50, 0xbfb8aa3b, v50
	v_exp_f32_e32 v50, v50
	v_rcp_f32_e32 v67, v62
	v_add_f32_e32 v62, 1.0, v63
	v_mul_f32_e32 v63, 0xbfb8aa3b, v64
	v_rcp_f32_e32 v69, v58
	v_add_f32_e32 v58, 1.0, v59
	v_mul_f32_e32 v59, 0xbfb8aa3b, v60
	v_exp_f32_e32 v63, v63
	v_mul_f32_e32 v64, 0xbfb8aa3b, v65
	v_exp_f32_e32 v59, v59
	v_mul_f32_e32 v60, 0xbfb8aa3b, v61
	v_exp_f32_e32 v64, v64
	v_exp_f32_e32 v60, v60
	v_rcp_f32_e32 v65, v62
	v_add_f32_e32 v62, 1.0, v63
	v_rcp_f32_e32 v61, v58
	v_add_f32_e32 v58, 1.0, v59
	v_rcp_f32_e32 v68, v62
	v_add_f32_e32 v62, 1.0, v64
	v_rcp_f32_e32 v70, v58
	v_add_f32_e32 v58, 1.0, v60
	v_rcp_f32_e32 v64, v62
	v_rcp_f32_e32 v71, v58
	v_mul_f32_e32 v51, 0xbfb8aa3b, v51
	v_exp_f32_e32 v51, v51
	v_add_u32_e32 v66, 0x80, v162
	v_mad_i64_i32 v[58:59], s[18:19], v66, s20, v[122:123]
	v_lshl_add_u64 v[62:63], v[58:59], 0, v[124:125]
	v_cvt_pk_bf16_f32 v58, v67, v65
	v_cvt_pk_bf16_f32 v59, v68, v64
	v_cvt_pk_bf16_f32 v60, v69, v61
	v_cvt_pk_bf16_f32 v61, v70, v71
	v_add_f32_e32 v50, 1.0, v50
	global_store_dwordx4 v[62:63], v[58:61], off
	v_mul_f32_e32 v54, 0xbfb8aa3b, v54
	v_mul_f32_e32 v55, 0xbfb8aa3b, v55
	v_rcp_f32_e32 v58, v50
	v_add_f32_e32 v50, 1.0, v51
; __device__ __forceinline__ float sigmoid_(float x) { return __builtin_amdgcn_rcpf(1.0f + __expf(-x)); }
; __device__ __forceinline__ uint4 pack8(const float (&f)[8]) { uint4 r; r.x = cvt_pk_bf16(f[0], f[1]); r.y = cvt_pk_bf16(f[2], f[3]); r.z = cvt_pk_bf16(f[4], f[5]); r.w = cvt_pk_bf16(f[6], f[7]); return r; }
; __device__ __forceinline__ void nt_store16(void* p, const uint4 v) { __builtin_nontemporal_store((u32x4){v.x, v.y, v.z, v.w}, (u32x4*)p); }
;     __device__ __forceinline__ void operator()(AccT acc, const Unit& u, int wr, int wc, int fr, int fq) const {
;     ...
;             for (int m = 0; m < 4; ++m) { const size_t row = (size_t)(row0 + ai * HALF + m * 16);
; #pragma unroll
;                 for (int bj = 0; bj < 2; ++bj) { float o[8];
; #pragma unroll
;                     for (int n = 0; n < 2; ++n)
; #pragma unroll
;                         for (int j = 0; j < 4; ++j) o[n * 4 + j] = sigmoid_(acc[ai][bj][m][n][j]);
;                     nt_store16(G + row * 3072 + col0 + bj * HALF, pack8(o)); } }
	v_mul_f32_e32 v51, 0xbfb8aa3b, v52
	v_mul_f32_e32 v56, 0xbfb8aa3b, v56
	v_mul_f32_e32 v57, 0xbfb8aa3b, v57
	v_exp_f32_e32 v51, v51
	v_mul_f32_e32 v52, 0xbfb8aa3b, v53
	v_exp_f32_e32 v54, v54
	v_exp_f32_e32 v55, v55
	v_exp_f32_e32 v56, v56
	v_exp_f32_e32 v57, v57
	v_exp_f32_e32 v52, v52
	v_rcp_f32_e32 v53, v50
	v_add_f32_e32 v50, 1.0, v51
	v_add_f32_e32 v54, 1.0, v54
	v_add_f32_e32 v55, 1.0, v55
	v_add_f32_e32 v56, 1.0, v56
	v_add_f32_e32 v57, 1.0, v57
	v_rcp_f32_e32 v59, v50
	v_add_f32_e32 v50, 1.0, v52
	v_mul_f32_e32 v46, 0xbfb8aa3b, v46
	v_mul_f32_e32 v42, 0xbfb8aa3b, v42
	v_rcp_f32_e32 v54, v54
	v_rcp_f32_e32 v55, v55
	v_rcp_f32_e32 v56, v56
	v_rcp_f32_e32 v57, v57
	v_rcp_f32_e32 v60, v50
	v_exp_f32_e32 v46, v46
	v_mul_f32_e32 v47, 0xbfb8aa3b, v47
	v_exp_f32_e32 v42, v42
	v_mul_f32_e32 v43, 0xbfb8aa3b, v43
	v_exp_f32_e32 v47, v47
	v_exp_f32_e32 v43, v43
	v_cvt_pk_bf16_f32 v50, v54, v55
	v_cvt_pk_bf16_f32 v51, v56, v57
	v_cvt_pk_bf16_f32 v52, v58, v53
	v_cvt_pk_bf16_f32 v53, v59, v60
	v_add_f32_e32 v46, 1.0, v46
	v_add_f32_e32 v42, 1.0, v42
	global_store_dwordx4 v[62:63], v[50:53], off offset:256
	v_mul_f32_e32 v34, 0xbfb8aa3b, v34
	v_exp_f32_e32 v34, v34
	v_rcp_f32_e32 v51, v46
	v_add_f32_e32 v46, 1.0, v47
	v_mul_f32_e32 v47, 0xbfb8aa3b, v48
	v_rcp_f32_e32 v53, v42
	v_add_f32_e32 v42, 1.0, v43
	v_mul_f32_e32 v43, 0xbfb8aa3b, v44
	v_exp_f32_e32 v47, v47
	v_mul_f32_e32 v48, 0xbfb8aa3b, v49
	v_exp_f32_e32 v43, v43
	v_mul_f32_e32 v44, 0xbfb8aa3b, v45
	v_exp_f32_e32 v48, v48
	v_exp_f32_e32 v44, v44
	v_rcp_f32_e32 v49, v46
	v_add_f32_e32 v46, 1.0, v47
	v_rcp_f32_e32 v45, v42
	v_add_f32_e32 v42, 1.0, v43
	v_rcp_f32_e32 v52, v46
	v_add_f32_e32 v46, 1.0, v48
	v_rcp_f32_e32 v54, v42
	v_add_f32_e32 v42, 1.0, v44
	v_rcp_f32_e32 v48, v46
	v_rcp_f32_e32 v55, v42
	v_mul_f32_e32 v35, 0xbfb8aa3b, v35
	v_exp_f32_e32 v35, v35
	v_add_u32_e32 v50, 0x90, v162
	v_mad_i64_i32 v[42:43], s[18:19], v50, s20, v[122:123]
	v_lshl_add_u64 v[46:47], v[42:43], 0, v[124:125]
	v_cvt_pk_bf16_f32 v42, v51, v49
	v_cvt_pk_bf16_f32 v43, v52, v48
	v_cvt_pk_bf16_f32 v44, v53, v45
	v_cvt_pk_bf16_f32 v45, v54, v55
	v_add_f32_e32 v34, 1.0, v34
	global_store_dwordx4 v[46:47], v[42:45], off
	v_mul_f32_e32 v38, 0xbfb8aa3b, v38
	v_mul_f32_e32 v39, 0xbfb8aa3b, v39
	v_rcp_f32_e32 v42, v34
	v_add_f32_e32 v34, 1.0, v35
	v_mul_f32_e32 v35, 0xbfb8aa3b, v36
	v_mul_f32_e32 v40, 0xbfb8aa3b, v40
	v_mul_f32_e32 v41, 0xbfb8aa3b, v41
	v_exp_f32_e32 v35, v35
	v_mul_f32_e32 v36, 0xbfb8aa3b, v37
	v_exp_f32_e32 v38, v38
	v_exp_f32_e32 v39, v39
	v_exp_f32_e32 v40, v40
	v_exp_f32_e32 v41, v41
	v_exp_f32_e32 v36, v36
	v_rcp_f32_e32 v37, v34
	v_add_f32_e32 v34, 1.0, v35
	v_add_f32_e32 v38, 1.0, v38
	v_add_f32_e32 v39, 1.0, v39
	v_add_f32_e32 v40, 1.0, v40
	v_add_f32_e32 v41, 1.0, v41
	v_rcp_f32_e32 v43, v34
	v_add_f32_e32 v34, 1.0, v36
	v_mul_f32_e32 v30, 0xbfb8aa3b, v30
	v_mul_f32_e32 v26, 0xbfb8aa3b, v26
	v_rcp_f32_e32 v38, v38
	v_rcp_f32_e32 v39, v39
	v_rcp_f32_e32 v40, v40
	v_rcp_f32_e32 v41, v41
	v_rcp_f32_e32 v44, v34
	v_exp_f32_e32 v30, v30
	v_mul_f32_e32 v31, 0xbfb8aa3b, v31
	v_exp_f32_e32 v26, v26
	v_mul_f32_e32 v27, 0xbfb8aa3b, v27
	v_exp_f32_e32 v31, v31
	v_exp_f32_e32 v27, v27
	v_cvt_pk_bf16_f32 v34, v38, v39
	v_cvt_pk_bf16_f32 v35, v40, v41
	v_cvt_pk_bf16_f32 v36, v42, v37
	v_cvt_pk_bf16_f32 v37, v43, v44
	v_add_f32_e32 v30, 1.0, v30
	v_add_f32_e32 v26, 1.0, v26
	global_store_dwordx4 v[46:47], v[34:37], off offset:256
	v_mul_f32_e32 v18, 0xbfb8aa3b, v18
	v_exp_f32_e32 v18, v18
	v_rcp_f32_e32 v35, v30
	v_add_f32_e32 v30, 1.0, v31
	v_mul_f32_e32 v31, 0xbfb8aa3b, v32
	v_rcp_f32_e32 v37, v26
	v_add_f32_e32 v26, 1.0, v27
	v_mul_f32_e32 v27, 0xbfb8aa3b, v28
	v_exp_f32_e32 v31, v31
	v_mul_f32_e32 v32, 0xbfb8aa3b, v33
	v_exp_f32_e32 v27, v27
	v_mul_f32_e32 v28, 0xbfb8aa3b, v29
	v_exp_f32_e32 v32, v32
	v_exp_f32_e32 v28, v28
	v_rcp_f32_e32 v33, v30
	v_add_f32_e32 v30, 1.0, v31
	v_rcp_f32_e32 v29, v26
; __device__ __forceinline__ float sigmoid_(float x) { return __builtin_amdgcn_rcpf(1.0f + __expf(-x)); }
; __device__ __forceinline__ uint4 pack8(const float (&f)[8]) { uint4 r; r.x = cvt_pk_bf16(f[0], f[1]); r.y = cvt_pk_bf16(f[2], f[3]); r.z = cvt_pk_bf16(f[4], f[5]); r.w = cvt_pk_bf16(f[6], f[7]); return r; }
; __device__ __forceinline__ void nt_store16(void* p, const uint4 v) { __builtin_nontemporal_store((u32x4){v.x, v.y, v.z, v.w}, (u32x4*)p); }
;     __device__ __forceinline__ void operator()(AccT acc, const Unit& u, int wr, int wc, int fr, int fq) const {
;     ...
;             for (int m = 0; m < 4; ++m) { const size_t row = (size_t)(row0 + ai * HALF + m * 16);
; #pragma unroll
;                 for (int bj = 0; bj < 2; ++bj) { float o[8];
; #pragma unroll
;                     for (int n = 0; n < 2; ++n)
; #pragma unroll
;                         for (int j = 0; j < 4; ++j) o[n * 4 + j] = sigmoid_(acc[ai][bj][m][n][j]);
;                     nt_store16(G + row * 3072 + col0 + bj * HALF, pack8(o)); } }
	v_add_f32_e32 v26, 1.0, v27
	v_rcp_f32_e32 v36, v30
	v_add_f32_e32 v30, 1.0, v32
	v_rcp_f32_e32 v38, v26
	v_add_f32_e32 v26, 1.0, v28
	v_rcp_f32_e32 v32, v30
	v_rcp_f32_e32 v39, v26
	v_mul_f32_e32 v19, 0xbfb8aa3b, v19
	v_exp_f32_e32 v19, v19
	v_add_u32_e32 v34, 0xa0, v162
	v_mad_i64_i32 v[26:27], s[18:19], v34, s20, v[122:123]
	v_lshl_add_u64 v[30:31], v[26:27], 0, v[124:125]
	v_cvt_pk_bf16_f32 v26, v35, v33
	v_cvt_pk_bf16_f32 v27, v36, v32
	v_cvt_pk_bf16_f32 v28, v37, v29
	v_cvt_pk_bf16_f32 v29, v38, v39
	v_add_f32_e32 v18, 1.0, v18
	global_store_dwordx4 v[30:31], v[26:29], off
	v_mul_f32_e32 v22, 0xbfb8aa3b, v22
	v_mul_f32_e32 v23, 0xbfb8aa3b, v23
	v_rcp_f32_e32 v26, v18
	v_add_f32_e32 v18, 1.0, v19
	v_mul_f32_e32 v19, 0xbfb8aa3b, v20
	v_mul_f32_e32 v24, 0xbfb8aa3b, v24
	v_mul_f32_e32 v25, 0xbfb8aa3b, v25
	v_exp_f32_e32 v19, v19
	v_mul_f32_e32 v20, 0xbfb8aa3b, v21
	v_exp_f32_e32 v22, v22
	v_exp_f32_e32 v23, v23
	v_exp_f32_e32 v24, v24
	v_exp_f32_e32 v25, v25
	v_exp_f32_e32 v20, v20
	v_rcp_f32_e32 v21, v18
	v_add_f32_e32 v18, 1.0, v19
	v_add_f32_e32 v22, 1.0, v22
	v_add_f32_e32 v23, 1.0, v23
	v_add_f32_e32 v24, 1.0, v24
	v_add_f32_e32 v25, 1.0, v25
	v_rcp_f32_e32 v27, v18
	v_add_f32_e32 v18, 1.0, v20
	v_mul_f32_e32 v14, 0xbfb8aa3b, v14
	v_mul_f32_e32 v10, 0xbfb8aa3b, v10
	v_rcp_f32_e32 v22, v22
	v_rcp_f32_e32 v23, v23
	v_rcp_f32_e32 v24, v24
	v_rcp_f32_e32 v25, v25
	v_rcp_f32_e32 v28, v18
	v_exp_f32_e32 v14, v14
	v_mul_f32_e32 v15, 0xbfb8aa3b, v15
	v_exp_f32_e32 v10, v10
	v_mul_f32_e32 v11, 0xbfb8aa3b, v11
	v_exp_f32_e32 v15, v15
	v_exp_f32_e32 v11, v11
	v_cvt_pk_bf16_f32 v18, v22, v23
	v_cvt_pk_bf16_f32 v19, v24, v25
	v_cvt_pk_bf16_f32 v20, v26, v21
	v_cvt_pk_bf16_f32 v21, v27, v28
	v_add_f32_e32 v14, 1.0, v14
	v_add_f32_e32 v10, 1.0, v10
	global_store_dwordx4 v[30:31], v[18:21], off offset:256
	v_mul_f32_e32 v2, 0xbfb8aa3b, v2
	v_exp_f32_e32 v2, v2
	v_rcp_f32_e32 v19, v14
	v_add_f32_e32 v14, 1.0, v15
	v_mul_f32_e32 v15, 0xbfb8aa3b, v16
	v_rcp_f32_e32 v21, v10
	v_add_f32_e32 v10, 1.0, v11
	v_mul_f32_e32 v11, 0xbfb8aa3b, v12
	v_exp_f32_e32 v15, v15
	v_mul_f32_e32 v16, 0xbfb8aa3b, v17
	v_exp_f32_e32 v11, v11
	v_mul_f32_e32 v12, 0xbfb8aa3b, v13
	v_exp_f32_e32 v16, v16
	v_exp_f32_e32 v12, v12
	v_rcp_f32_e32 v17, v14
	v_add_f32_e32 v14, 1.0, v15
	v_rcp_f32_e32 v13, v10
	v_add_f32_e32 v10, 1.0, v11
	v_rcp_f32_e32 v20, v14
	v_add_f32_e32 v14, 1.0, v16
	v_rcp_f32_e32 v22, v10
	v_add_f32_e32 v10, 1.0, v12
	v_rcp_f32_e32 v16, v14
	v_rcp_f32_e32 v23, v10
	v_mul_f32_e32 v3, 0xbfb8aa3b, v3
	v_exp_f32_e32 v3, v3
	v_add_u32_e32 v18, 0xb0, v162
	v_mad_i64_i32 v[10:11], s[18:19], v18, s20, v[122:123]
	v_lshl_add_u64 v[14:15], v[10:11], 0, v[124:125]
	v_cvt_pk_bf16_f32 v10, v19, v17
	v_cvt_pk_bf16_f32 v11, v20, v16
	v_cvt_pk_bf16_f32 v12, v21, v13
	v_cvt_pk_bf16_f32 v13, v22, v23
	v_add_f32_e32 v2, 1.0, v2
	global_store_dwordx4 v[14:15], v[10:13], off
	v_mul_f32_e32 v6, 0xbfb8aa3b, v6
	v_mul_f32_e32 v7, 0xbfb8aa3b, v7
	v_rcp_f32_e32 v10, v2
	v_add_f32_e32 v2, 1.0, v3
	v_mul_f32_e32 v3, 0xbfb8aa3b, v4
	v_mul_f32_e32 v8, 0xbfb8aa3b, v8
	v_mul_f32_e32 v9, 0xbfb8aa3b, v9
	v_exp_f32_e32 v3, v3
	v_mul_f32_e32 v4, 0xbfb8aa3b, v5
	v_exp_f32_e32 v6, v6
	v_exp_f32_e32 v7, v7
	v_exp_f32_e32 v8, v8
	v_exp_f32_e32 v9, v9
	v_exp_f32_e32 v4, v4
	v_rcp_f32_e32 v5, v2
	v_add_f32_e32 v2, 1.0, v3
	v_add_f32_e32 v6, 1.0, v6
	v_add_f32_e32 v7, 1.0, v7
	v_add_f32_e32 v8, 1.0, v8
	v_add_f32_e32 v9, 1.0, v9
	v_rcp_f32_e32 v11, v2
	v_add_f32_e32 v2, 1.0, v4
	v_rcp_f32_e32 v6, v6
	v_rcp_f32_e32 v7, v7
	v_rcp_f32_e32 v8, v8
	v_rcp_f32_e32 v9, v9
	v_rcp_f32_e32 v12, v2
	v_cvt_pk_bf16_f32 v2, v6, v7
	v_cvt_pk_bf16_f32 v4, v10, v5
	v_cvt_pk_bf16_f32 v3, v8, v9
	v_cvt_pk_bf16_f32 v5, v11, v12
	s_and_b64 vcc, exec, s[2:3]
	s_mov_b64 s[2:3], -1
	global_store_dwordx4 v[14:15], v[2:5], off offset:256
	s_cbranch_vccnz .LBB0_168
	s_andn2_b64 vcc, exec, s[10:11]
	s_cbranch_vccnz .LBB0_167
	s_barrier
	s_branch .LBB0_167

; #define LAS __attribute__((address_space(3)))
; __device__ void rwkv_post_phase(const Params& p, int l, LAS unsigned char* lds) {
;     ...
;             const f32x4 lg = *(const f32x4*)(lng + c), lb = *(const f32x4*)(lnb + c), m4 = *(const f32x4*)(mu + 1024 + c);
;             for (int tl = 0; tl < ntl; ++tl) {
;                 const size_t t0 = (size_t)(base + tl * NBLK()) * 64;
;                 __syncthreads();
; #pragma unroll
;                 for (int i = 0; i < 2; ++i) { const int id = wid + 8 * i, rt = id >> 2, ct = id & 3; const f32x4 z4 = {0.f, 0.f, 0.f, 0.f};
;                     const f32x4 acc = mm_nt<3>(sgb + tl * 6656, 104, rt * 16, g2T + h * 64 * 104, 104, ct * 16, r16, quad, z4);
; #pragma unroll
;                     for (int j = 0; j < 4; ++j) gs[(rt * 16 + quad * 4 + j) * 64 + ct * 16 + r16] = acc[j]; }
;                 __syncthreads();
;                 const f32x4 gA = *(const LAS f32x4*)(gs + tp * 64 + cg * 4), gB = *(const LAS f32x4*)(gs + (tp + 32) * 64 + cg * 4);
; #pragma unroll
;                 for (int which = 0; which < 2; ++which) {
;                     const size_t t = t0 + tp + which * 32; const int s = (int)(t & (SEQ_ - 1));
;                     const u32x2 yfr = *(const u32x2*)(YF + t * 512 + c), ybr = *(const u32x2*)(YBk + t * 512 + c);
;                     f32x4 y; y[0] = bf_lo(yfr.x) + bf_lo(ybr.x); y[1] = bf_hi(yfr.x) + bf_hi(ybr.x); y[2] = bf_lo(yfr.y) + bf_lo(ybr.y); y[3] = bf_hi(yfr.y) + bf_hi(ybr.y);
;                     const float mean = red16d(y[0] + y[1] + y[2] + y[3]) * (1.0f / 64.0f);
;                     const f32x4 d = y - mean;
;                     const float var = red16d(d[0] * d[0] + d[1] * d[1] + d[2] * d[2] + d[3] * d[3]) * (1.0f / 64.0f);
;                     const float rs = rsqrtf(var + 64e-5f);
;                     const bf16_t* zp = ZR + t * ZRC + 1024 + c;
;                     const u32x2 vc = *(const u32x2*)zp; u32x2 vp = {0u, 0u}, vn = {0u, 0u};
;                     if (s > 0) vp = *(const u32x2*)(zp - ZRC);
;                     if (s < SEQ_ - 1) vn = *(const u32x2*)(zp + ZRC);
;                     f32x4 vcur, vprev, vnext;
;                     vcur[0] = bf_lo(vc.x); vcur[1] = bf_hi(vc.x); vcur[2] = bf_lo(vc.y); vcur[3] = bf_hi(vc.y);
;                     vprev[0] = bf_lo(vp.x); vprev[1] = bf_hi(vp.x); vprev[2] = bf_lo(vp.y); vprev[3] = bf_hi(vp.y);
.LBB0_214:
	s_or_b64 exec, exec, s[20:21]
	v_lshlrev_b64 v[20:21], 5, v[20:21]
	v_lshl_add_u64 v[20:21], s[18:19], 0, v[20:21]
	global_load_dword v0, v[20:21], off
	v_add_f32_e32 v46, v45, v46
	s_waitcnt vmcnt(0) lgkmcnt(0)
	v_lshlrev_b32_e32 v20, 16, v38
	v_and_b32_e32 v21, 0xffff0000, v38
	v_lshlrev_b32_e32 v42, 16, v40
	v_and_b32_e32 v43, 0xffff0000, v40
	v_lshlrev_b32_e32 v40, 16, v41
	v_and_b32_e32 v41, 0xffff0000, v41
	v_lshlrev_b32_e32 v44, 16, v32
	v_and_b32_e32 v45, 0xffff0000, v32
	v_lshlrev_b32_e32 v32, 16, v33
	v_and_b32_e32 v33, 0xffff0000, v33
	v_fmamk_f32 v46, v46, 0x3c800000, v170
	v_pk_add_f32 v[32:33], v[40:41], v[32:33]
	v_pk_add_f32 v[40:41], v[42:43], v[44:45]
	v_xor_b32_e32 v43, 0x80000000, v21
	v_xor_b32_e32 v42, 0x80000000, v20
	v_mul_f32_e32 v47, 0x4b800000, v46
	v_cmp_gt_f32_e32 vcc, s33, v46
	v_pk_fma_f32 v[40:41], v[40:41], 0.5, v[42:43] op_sel_hi:[1,0,1]
	v_lshlrev_b32_e32 v38, 16, v39
	v_cndmask_b32_e32 v42, v46, v47, vcc
	v_rsq_f32_e32 v42, v42
	v_and_b32_e32 v39, 0xffff0000, v39
	v_xor_b32_e32 v45, 0x80000000, v39
	v_xor_b32_e32 v44, 0x80000000, v38
	v_pk_fma_f32 v[32:33], v[32:33], 0.5, v[44:45] op_sel_hi:[1,0,1]
	v_pk_fma_f32 v[20:21], v[10:11], v[40:41], v[20:21]
	v_pk_fma_f32 v[32:33], v[12:13], v[32:33], v[38:39]
	v_mul_f32_e32 v38, 0x45800000, v42
	v_cndmask_b32_e32 v38, v42, v38, vcc
	v_pk_mul_f32 v[34:35], v[34:35], v[38:39] op_sel_hi:[1,0]
	v_pk_mul_f32 v[36:37], v[36:37], v[38:39] op_sel_hi:[1,0]
	v_pk_fma_f32 v[34:35], v[2:3], v[34:35], v[6:7]
	v_pk_fma_f32 v[36:37], v[4:5], v[36:37], v[8:9]
	s_add_i32 s22, s22, 1
	s_cmp_eq_u32 s41, s22
	v_add_u32_e32 v57, 0x3400, v57
	v_pk_fma_f32 v[20:21], v[0:1], v[20:21], v[34:35] op_sel_hi:[0,1,1]
	v_pk_fma_f32 v[32:33], v[0:1], v[32:33], v[36:37] op_sel_hi:[0,1,1]
	v_pk_mul_f32 v[16:17], v[16:17], v[32:33]
	v_pk_mul_f32 v[14:15], v[14:15], v[20:21]
	s_nop 0
	v_cvt_pk_bf16_f32 v14, v14, v15
	v_cvt_pk_bf16_f32 v15, v16, v17
	global_store_dwordx2 v[18:19], v[14:15], off
	s_cbranch_scc1 .LBB0_212
.LBB0_215:
	s_mov_b32 s20, s39
	s_waitcnt lgkmcnt(0)
	s_barrier
	ds_read_b128 v[14:17], v57
	ds_read_b128 v[18:21], v27
	s_waitcnt lgkmcnt(0)
	v_mfma_f32_16x16x32_bf16 v[14:17], v[14:17], v[18:21], 0
	ds_read_b128 v[18:21], v57 offset:64
	ds_read_b128 v[32:35], v27 offset:64
	v_add_u32_e32 v0, v51, v53
	s_mul_i32 s20, s20, s22
	s_waitcnt lgkmcnt(0)
	v_mfma_f32_16x16x32_bf16 v[14:17], v[18:21], v[32:35], v[14:17]
	ds_read_b128 v[18:21], v57 offset:128
	ds_read_b128 v[32:35], v27 offset:128
	s_add_i32 s20, s20, s34
	s_ashr_i32 s21, s20, 31
	s_waitcnt lgkmcnt(0)
	v_mfma_f32_16x16x32_bf16 v[14:17], v[18:21], v[32:35], v[14:17]
	s_nop 7
	ds_write2st64_b32 v0, v14, v15 offset1:1
	ds_write2st64_b32 v0, v16, v17 offset0:2 offset1:3
	ds_read_b128 v[14:17], v57 offset:6656
	ds_read_b128 v[18:21], v27
	s_waitcnt lgkmcnt(0)
	v_mfma_f32_16x16x32_bf16 v[14:17], v[14:17], v[18:21], 0
	ds_read_b128 v[18:21], v57 offset:6720
	ds_read_b128 v[32:35], v27 offset:64
	s_lshl_b64 s[20:21], s[20:21], 6
	v_mov_b32_e32 v42, 0
	s_waitcnt lgkmcnt(0)
	v_mfma_f32_16x16x32_bf16 v[14:17], v[18:21], v[32:35], v[14:17]
	ds_read_b128 v[18:21], v57 offset:6784
	ds_read_b128 v[32:35], v27 offset:128
	v_mov_b32_e32 v48, 0
	v_mov_b32_e32 v49, 0
	s_waitcnt lgkmcnt(0)
	v_mfma_f32_16x16x32_bf16 v[14:17], v[18:21], v[32:35], v[14:17]
	v_lshl_add_u64 v[34:35], s[20:21], 0, v[24:25]
	v_lshlrev_b64 v[32:33], 10, v[34:35]
	v_lshl_add_u64 v[36:37], v[28:29], 0, v[32:33]
	v_lshl_add_u64 v[32:33], v[30:31], 0, v[32:33]
	global_load_dwordx2 v[40:41], v[36:37], off
	global_load_dwordx2 v[32:33], v[32:33], off
	s_nop 3
	ds_write2st64_b32 v56, v14, v15 offset1:1
	ds_write2st64_b32 v56, v16, v17 offset0:2 offset1:3
	s_waitcnt lgkmcnt(0)
	s_barrier
	ds_read_b128 v[18:21], v52
	ds_read_b128 v[14:17], v52 offset:8192
	v_and_b32_e32 v43, 0x7ff, v34
	v_cmp_ne_u32_e32 vcc, 0, v43
	s_waitcnt vmcnt(0) lgkmcnt(0)
	v_lshlrev_b32_e32 v38, 16, v40
	v_and_b32_e32 v39, 0xffff0000, v40
	v_lshlrev_b32_e32 v44, 16, v32
	v_and_b32_e32 v45, 0xffff0000, v32
	v_pk_add_f32 v[38:39], v[38:39], v[44:45]
	v_lshlrev_b32_e32 v40, 16, v41
	v_and_b32_e32 v41, 0xffff0000, v41
	v_lshlrev_b32_e32 v32, 16, v33
	v_and_b32_e32 v33, 0xffff0000, v33
	v_pk_add_f32 v[40:41], v[40:41], v[32:33]
	v_add_f32_e32 v0, v38, v39
	v_add_f32_e32 v0, v40, v0
	v_add_f32_e32 v0, v41, v0
	s_nop 1
	v_add_f32_dpp v0, v0, v0 quad_perm:[1,0,3,2] row_mask:0xf bank_mask:0xf bound_ctrl:1
	s_nop 1
	v_add_f32_dpp v0, v0, v0 quad_perm:[2,3,0,1] row_mask:0xf bank_mask:0xf bound_ctrl:1
	s_nop 1
	v_add_f32_dpp v0, v0, v0 row_half_mirror row_mask:0xf bank_mask:0xf bound_ctrl:1
	s_nop 1
	v_add_f32_dpp v0, v0, v0 row_mirror row_mask:0xf bank_mask:0xf bound_ctrl:1
	v_fmamk_f32 v39, v0, 0xbc800000, v39
	v_fmac_f32_e32 v38, 0xbc800000, v0
	v_fmamk_f32 v41, v0, 0xbc800000, v41
	v_fmac_f32_e32 v40, 0xbc800000, v0
	v_pk_mul_f32 v[44:45], v[38:39], v[38:39]
	v_pk_mul_f32 v[32:33], v[40:41], v[40:41]
	v_add_f32_e32 v0, v44, v45
	v_add_f32_e32 v0, v32, v0
	v_add_f32_e32 v0, v33, v0
	v_mov_b64_e32 v[32:33], s[4:5]
	v_mad_u64_u32 v[32:33], s[20:21], v34, s46, v[32:33]
	v_add_f32_dpp v0, v0, v0 quad_perm:[1,0,3,2] row_mask:0xf bank_mask:0xf bound_ctrl:1
	v_mad_i32_i24 v33, v35, s46, v33
	s_nop 0
	v_add_f32_dpp v0, v0, v0 quad_perm:[2,3,0,1] row_mask:0xf bank_mask:0xf bound_ctrl:1
	s_nop 1
	v_add_f32_dpp v58, v0, v0 row_half_mirror row_mask:0xf bank_mask:0xf bound_ctrl:1
	v_lshlrev_b32_e32 v0, 1, v26
	v_lshl_add_u64 v[44:45], v[32:33], 0, v[0:1]
	v_lshl_add_u64 v[46:47], v[44:45], 0, s[36:37]
	global_load_dwordx2 v[44:45], v[44:45], off offset:2048
	v_mov_b32_dpp v59, v58 row_mirror row_mask:0xf bank_mask:0xf bound_ctrl:1
	s_and_saveexec_b64 s[20:21], vcc
	s_cbranch_execz .LBB0_217
	v_add_co_u32_e32 v48, vcc, 0xfffff240, v46
	s_nop 1
	v_addc_co_u32_e32 v49, vcc, -1, v47, vcc
	global_load_dwordx2 v[48:49], v[48:49], off
; __device__ __forceinline__ unsigned cvt_pk_bf16(float lo, float hi) { const f32x2_t v = {lo, hi}; const bf16x2_t b = __builtin_convertvector(v, bf16x2_t); return __builtin_bit_cast(unsigned, b); }
; __device__ __forceinline__ float bf_lo(unsigned w) { return __uint_as_float(w << 16); }
; __device__ __forceinline__ float bf_hi(unsigned w) { return __uint_as_float(w & 0xffff0000u); }
; __device__ void rwkv_post_phase(const Params& p, int l, LAS unsigned char* lds) {
;     ...
;                     const size_t t = t0 + tp + which * 32; const int s = (int)(t & (SEQ_ - 1));
;                     const u32x2 yfr = *(const u32x2*)(YF + t * 512 + c), ybr = *(const u32x2*)(YBk + t * 512 + c);
;                     f32x4 y; y[0] = bf_lo(yfr.x) + bf_lo(ybr.x); y[1] = bf_hi(yfr.x) + bf_hi(ybr.x); y[2] = bf_lo(yfr.y) + bf_lo(ybr.y); y[3] = bf_hi(yfr.y) + bf_hi(ybr.y);
;                     const float mean = red16d(y[0] + y[1] + y[2] + y[3]) * (1.0f / 64.0f);
;                     const f32x4 d = y - mean;
;                     const float var = red16d(d[0] * d[0] + d[1] * d[1] + d[2] * d[2] + d[3] * d[3]) * (1.0f / 64.0f);
;                     const float rs = rsqrtf(var + 64e-5f);
;                     const bf16_t* zp = ZR + t * ZRC + 1024 + c;
;                     const u32x2 vc = *(const u32x2*)zp; u32x2 vp = {0u, 0u}, vn = {0u, 0u};
;                     if (s > 0) vp = *(const u32x2*)(zp - ZRC);
;                     if (s < SEQ_ - 1) vn = *(const u32x2*)(zp + ZRC);
;                     f32x4 vcur, vprev, vnext;
;                     vcur[0] = bf_lo(vc.x); vcur[1] = bf_hi(vc.x); vcur[2] = bf_lo(vc.y); vcur[3] = bf_hi(vc.y);
;                     vprev[0] = bf_lo(vp.x); vprev[1] = bf_hi(vp.x); vprev[2] = bf_lo(vp.y); vprev[3] = bf_hi(vp.y);
;                     vnext[0] = bf_lo(vn.x); vnext[1] = bf_hi(vn.x); vnext[2] = bf_lo(vn.y); vnext[3] = bf_hi(vn.y);
;                     const f32x4 vs = vcur + m4 * ((vprev + vnext) * 0.5f - vcur);
;                     const float bon = BON[t * 8 + h];
;                     const f32x4 gg = which ? gB : gA;
;                     const f32x4 o = (d * rs * lg + lb + vs * bon) * gg;
;                     u32x2 ow; ow.x = cvt_pk_bf16(o[0], o[1]); ow.y = cvt_pk_bf16(o[2], o[3]);
;                     *(u32x2*)(YF + t * 512 + c) = ow;
.LBB0_217:
	s_or_b64 exec, exec, s[20:21]
	v_cmp_ne_u32_e32 vcc, s75, v43
	v_mov_b32_e32 v43, 0
	s_and_saveexec_b64 s[20:21], vcc
	s_cbranch_execz .LBB0_219
	global_load_dwordx2 v[42:43], v[46:47], off offset:3520
.LBB0_219:
	s_or_b64 exec, exec, s[20:21]
	v_add_f32_e32 v46, v58, v59
	s_waitcnt vmcnt(0) lgkmcnt(0)
	v_lshlrev_b32_e32 v58, 16, v44
	v_and_b32_e32 v59, 0xffff0000, v44
	v_lshlrev_b32_e32 v60, 16, v48
	v_and_b32_e32 v61, 0xffff0000, v48
	v_lshlrev_b32_e32 v48, 16, v49
	v_and_b32_e32 v49, 0xffff0000, v49
	v_lshlrev_b32_e32 v62, 16, v42
	v_and_b32_e32 v63, 0xffff0000, v42
	v_lshlrev_b32_e32 v42, 16, v43
	v_and_b32_e32 v43, 0xffff0000, v43
	v_lshlrev_b32_e32 v44, 16, v45
	v_and_b32_e32 v45, 0xffff0000, v45
	v_pk_add_f32 v[42:43], v[48:49], v[42:43]
	v_pk_add_f32 v[48:49], v[60:61], v[62:63]
	v_xor_b32_e32 v61, 0x80000000, v59
	v_xor_b32_e32 v60, 0x80000000, v58
	v_pk_fma_f32 v[48:49], v[48:49], 0.5, v[60:61] op_sel_hi:[1,0,1]
	v_xor_b32_e32 v61, 0x80000000, v45
	v_xor_b32_e32 v60, 0x80000000, v44
	v_pk_fma_f32 v[42:43], v[42:43], 0.5, v[60:61] op_sel_hi:[1,0,1]
	v_fmamk_f32 v46, v46, 0x3c800000, v170
	v_pk_fma_f32 v[42:43], v[12:13], v[42:43], v[44:45]
	v_pk_fma_f32 v[44:45], v[10:11], v[48:49], v[58:59]
	v_lshlrev_b64 v[48:49], 5, v[34:35]
	v_lshl_add_u64 v[48:49], s[18:19], 0, v[48:49]
	global_load_dword v48, v[48:49], off
	v_cmp_gt_f32_e32 vcc, s33, v46
	v_mul_f32_e32 v47, 0x4b800000, v46
	v_lshl_add_u64 v[32:33], v[32:33], 0, v[0:1]
	v_cndmask_b32_e32 v46, v46, v47, vcc
	v_rsq_f32_e32 v46, v46
	s_mov_b64 s[20:21], 0x1c000
	v_mul_f32_e32 v47, 0x45800000, v46
	v_cndmask_b32_e32 v46, v46, v47, vcc
	v_pk_mul_f32 v[38:39], v[38:39], v[46:47] op_sel_hi:[1,0]
	v_pk_mul_f32 v[40:41], v[40:41], v[46:47] op_sel_hi:[1,0]
	v_pk_fma_f32 v[38:39], v[2:3], v[38:39], v[6:7]
	v_pk_fma_f32 v[40:41], v[4:5], v[40:41], v[8:9]
	s_waitcnt vmcnt(0) lgkmcnt(0)
	v_pk_fma_f32 v[38:39], v[48:49], v[44:45], v[38:39] op_sel_hi:[0,1,1]
	v_pk_fma_f32 v[40:41], v[48:49], v[42:43], v[40:41] op_sel_hi:[0,1,1]
	v_pk_mul_f32 v[20:21], v[20:21], v[40:41]
	v_pk_mul_f32 v[18:19], v[18:19], v[38:39]
	v_lshl_add_u64 v[42:43], v[32:33], 0, s[20:21]
	v_cvt_pk_bf16_f32 v18, v18, v19
	v_cvt_pk_bf16_f32 v19, v20, v21
	v_lshl_add_u64 v[20:21], v[34:35], 0, 32
	v_lshlrev_b64 v[34:35], 10, v[20:21]
	global_store_dwordx2 v[36:37], v[18:19], off
	v_lshl_add_u64 v[18:19], v[28:29], 0, v[34:35]
	v_lshl_add_u64 v[34:35], v[30:31], 0, v[34:35]
	global_load_dwordx2 v[36:37], v[18:19], off
	global_load_dwordx2 v[38:39], v[34:35], off
	v_add_co_u32_e32 v32, vcc, 0x1c000, v32
	v_and_b32_e32 v44, 0x7ff, v20
	s_nop 0
	v_addc_co_u32_e32 v33, vcc, 0, v33, vcc
	v_cmp_ne_u32_e32 vcc, 0, v44
	s_waitcnt vmcnt(0) lgkmcnt(0)
	v_lshlrev_b32_e32 v34, 16, v36
	v_and_b32_e32 v35, 0xffff0000, v36
	v_lshlrev_b32_e32 v40, 16, v38
	v_and_b32_e32 v41, 0xffff0000, v38
	v_pk_add_f32 v[34:35], v[34:35], v[40:41]
	v_lshlrev_b32_e32 v36, 16, v37
	v_and_b32_e32 v37, 0xffff0000, v37
	v_lshlrev_b32_e32 v38, 16, v39
	v_and_b32_e32 v39, 0xffff0000, v39
	v_pk_add_f32 v[36:37], v[36:37], v[38:39]
	v_add_f32_e32 v38, v34, v35
	v_add_f32_e32 v38, v36, v38
	v_add_f32_e32 v38, v37, v38
	s_nop 1
	v_add_f32_dpp v38, v38, v38 quad_perm:[1,0,3,2] row_mask:0xf bank_mask:0xf bound_ctrl:1
	s_nop 1
	v_add_f32_dpp v38, v38, v38 quad_perm:[2,3,0,1] row_mask:0xf bank_mask:0xf bound_ctrl:1
	s_nop 1
	v_add_f32_dpp v38, v38, v38 row_half_mirror row_mask:0xf bank_mask:0xf bound_ctrl:1
	s_nop 1
	v_add_f32_dpp v38, v38, v38 row_mirror row_mask:0xf bank_mask:0xf bound_ctrl:1
	v_fmamk_f32 v35, v38, 0xbc800000, v35
	v_fmac_f32_e32 v34, 0xbc800000, v38
	v_fmamk_f32 v37, v38, 0xbc800000, v37
	v_fmac_f32_e32 v36, 0xbc800000, v38
	v_pk_mul_f32 v[40:41], v[34:35], v[34:35]
	v_pk_mul_f32 v[38:39], v[36:37], v[36:37]
	v_add_f32_e32 v40, v40, v41
	v_add_f32_e32 v38, v38, v40
	v_add_f32_e32 v38, v39, v38
	v_mov_b32_e32 v40, 0
	v_mov_b32_e32 v41, 0
	v_add_f32_dpp v38, v38, v38 quad_perm:[1,0,3,2] row_mask:0xf bank_mask:0xf bound_ctrl:1
	s_nop 1
	v_add_f32_dpp v38, v38, v38 quad_perm:[2,3,0,1] row_mask:0xf bank_mask:0xf bound_ctrl:1
	s_nop 1
	v_add_f32_dpp v45, v38, v38 row_half_mirror row_mask:0xf bank_mask:0xf bound_ctrl:1
	global_load_dwordx2 v[38:39], v[32:33], off
	v_mov_b32_e32 v32, 0
	v_mov_b32_dpp v46, v45 row_mirror row_mask:0xf bank_mask:0xf bound_ctrl:1
	s_and_saveexec_b64 s[20:21], vcc
	s_cbranch_execz .LBB0_221
	v_add_co_u32_e32 v40, vcc, 0xfffff240, v42
	s_nop 1
	v_addc_co_u32_e32 v41, vcc, -1, v43, vcc
	global_load_dwordx2 v[40:41], v[40:41], off
.LBB0_221:
	s_or_b64 exec, exec, s[20:21]
	v_cmp_ne_u32_e32 vcc, s75, v44
	v_mov_b32_e32 v33, 0
	s_and_saveexec_b64 s[20:21], vcc
	s_cbranch_execz .LBB0_214
	global_load_dwordx2 v[32:33], v[42:43], off offset:3520
	s_branch .LBB0_214

; __device__ __forceinline__ uint4 pack8(const float (&f)[8]) { uint4 r; r.x = cvt_pk_bf16(f[0], f[1]); r.y = cvt_pk_bf16(f[2], f[3]); r.z = cvt_pk_bf16(f[4], f[5]); r.w = cvt_pk_bf16(f[6], f[7]); return r; }
; __device__ void fnet_combine_phase(const Params& p) {
;     ...
;     for (int idx = gtid; idx < NB_ * 1024 * 64; idx += gsz) {
;         const int n8 = (idx & 63) * 8, sp = (idx >> 6) & 1023, b = idx >> 16;
;         float pf[8], qf[8], d[8], sm[8];
;         unpack8(*(const uint4*)(PQ + ((size_t)(b * 2) * 1024 + sp) * 512 + n8), pf); unpack8(*(const uint4*)(PQ + ((size_t)(b * 2 + 1) * 1024 + sp) * 512 + n8), qf);
; #pragma unroll
;         for (int j = 0; j < 8; ++j) { d[j] = pf[j] - qf[j]; sm[j] = pf[j] + qf[j]; }
;         *(uint4*)(YB + ((size_t)b * SEQ_ + sp) * 512 + n8) = pack8(d);
;         if (sp > 0) *(uint4*)(YB + ((size_t)b * SEQ_ + (SEQ_ - sp)) * 512 + n8) = pack8(sm);
;     }
.LBB0_238:
	v_ashrrev_i32_e32 v18, 16, v20
	v_lshlrev_b32_e32 v10, 1, v18
	v_ashrrev_i32_e32 v11, 31, v10
	v_lshlrev_b64 v[2:3], 20, v[10:11]
	v_or_b32_e32 v10, 1, v10
	v_ashrrev_i32_e32 v11, 31, v10
	v_bfe_u32 v22, v20, 6, 10
	v_lshlrev_b64 v[10:11], 20, v[10:11]
	v_and_b32_e32 v0, 0x1f8, v21
	v_lshl_add_u64 v[2:3], s[4:5], 0, v[2:3]
	v_lshlrev_b32_e32 v12, 10, v22
	v_mov_b32_e32 v13, v1
	v_lshl_add_u64 v[10:11], s[4:5], 0, v[10:11]
	v_lshl_add_u64 v[2:3], v[2:3], 0, v[12:13]
	v_lshlrev_b32_e32 v0, 1, v0
	v_lshl_add_u64 v[10:11], v[10:11], 0, v[12:13]
	v_lshl_add_u64 v[2:3], v[2:3], 0, v[0:1]
	v_lshl_add_u64 v[10:11], v[10:11], 0, v[0:1]
	global_load_dwordx4 v[6:9], v[2:3], off
	global_load_dwordx4 v[14:17], v[10:11], off
	v_ashrrev_i32_e32 v19, 31, v18
	v_lshlrev_b64 v[18:19], 11, v[18:19]
	v_cmp_ne_u32_e32 vcc, 0, v22
	s_waitcnt vmcnt(0) lgkmcnt(0)
	v_lshlrev_b32_e32 v2, 16, v6
	v_and_b32_e32 v3, 0xffff0000, v6
	v_lshlrev_b32_e32 v4, 16, v7
	v_and_b32_e32 v5, 0xffff0000, v7
	v_lshlrev_b32_e32 v6, 16, v8
	v_and_b32_e32 v7, 0xffff0000, v8
	v_lshlrev_b32_e32 v10, 16, v14
	v_and_b32_e32 v11, 0xffff0000, v14
	v_lshlrev_b32_e32 v12, 16, v15
	v_and_b32_e32 v13, 0xffff0000, v15
	v_lshlrev_b32_e32 v14, 16, v16
	v_and_b32_e32 v15, 0xffff0000, v16
	v_pk_add_f32 v[24:25], v[2:3], v[10:11] neg_lo:[0,1] neg_hi:[0,1]
	v_pk_add_f32 v[26:27], v[4:5], v[12:13] neg_lo:[0,1] neg_hi:[0,1]
	v_pk_add_f32 v[28:29], v[6:7], v[14:15] neg_lo:[0,1] neg_hi:[0,1]
	v_cvt_pk_bf16_f32 v24, v24, v25
	v_cvt_pk_bf16_f32 v25, v26, v27
	v_cvt_pk_bf16_f32 v26, v28, v29
	v_or_b32_e32 v28, v18, v22
	v_mov_b32_e32 v29, v19
	v_lshlrev_b32_e32 v8, 16, v9
	v_and_b32_e32 v9, 0xffff0000, v9
	v_lshlrev_b32_e32 v16, 16, v17
	v_and_b32_e32 v17, 0xffff0000, v17
	v_lshlrev_b64 v[28:29], 10, v[28:29]
	v_pk_add_f32 v[30:31], v[8:9], v[16:17] neg_lo:[0,1] neg_hi:[0,1]
	v_lshl_add_u64 v[28:29], s[6:7], 0, v[28:29]
	v_cvt_pk_bf16_f32 v27, v30, v31
	v_lshl_add_u64 v[28:29], v[28:29], 0, v[0:1]
	global_store_dwordx4 v[28:29], v[24:27], off
	s_and_saveexec_b64 s[10:11], vcc
	s_cbranch_execz .LBB0_237
	v_pk_add_f32 v[6:7], v[6:7], v[14:15]
	v_pk_add_f32 v[4:5], v[4:5], v[12:13]
	v_pk_add_f32 v[2:3], v[2:3], v[10:11]
	v_pk_add_f32 v[8:9], v[8:9], v[16:17]
	v_cvt_pk_bf16_f32 v2, v2, v3
	v_cvt_pk_bf16_f32 v3, v4, v5
	v_cvt_pk_bf16_f32 v4, v6, v7
	v_sub_u32_e32 v6, 0x800, v22
	v_mov_b32_e32 v7, v1
	v_lshl_add_u64 v[6:7], v[18:19], 0, v[6:7]
	v_lshlrev_b64 v[6:7], 10, v[6:7]
	v_lshl_add_u64 v[6:7], s[6:7], 0, v[6:7]
	v_cvt_pk_bf16_f32 v5, v8, v9
	v_lshl_add_u64 v[6:7], v[6:7], 0, v[0:1]
	global_store_dwordx4 v[6:7], v[2:5], off
	s_branch .LBB0_237

; __device__ __forceinline__ unsigned cvt_pk_bf16(float lo, float hi) { const f32x2_t v = {lo, hi}; const bf16x2_t b = __builtin_convertvector(v, bf16x2_t); return __builtin_bit_cast(unsigned, b); }
; __device__ __forceinline__ void nt_store16(void* p, const uint4 v) { __builtin_nontemporal_store((u32x4){v.x, v.y, v.z, v.w}, (u32x4*)p); }
; __device__ __forceinline__ uint4 pack_acc8(const f32x4 a, const f32x4 b, float s) { uint4 w; w.x = cvt_pk_bf16(a[0] * s, a[1] * s); w.y = cvt_pk_bf16(a[2] * s, a[3] * s); w.z = cvt_pk_bf16(b[0] * s, b[1] * s); w.w = cvt_pk_bf16(b[2] * s, b[3] * s); return w; }
;     __device__ __forceinline__ void operator()(AccT acc, const Unit& u, int wr, int wc, int fr, int fq) const {
;         const int row0 = u.pm * BM + wr * 64 + fr, col0 = u.pn * BM + wc * 32 + 8 * fq;
; #pragma unroll
;         for (int ai = 0; ai < 2; ++ai)
; #pragma unroll
;             for (int m = 0; m < 4; ++m) { const size_t row = (size_t)u.z * 1024 + (row0 + ai * HALF + m * 16);
; #pragma unroll
;                 for (int bj = 0; bj < 2; ++bj) nt_store16(PQ + row * 512 + col0 + bj * HALF, pack_acc8(acc[ai][bj][m][0], acc[ai][bj][m][1], 1.0f / 512.0f)); }
.LBB0_386:
	v_lshl_add_u32 v164, s19, 8, v160
	s_ashr_i32 s19, s18, 31
	s_lshl_b64 s[18:19], s[18:19], 20
	v_lshl_or_b32 v138, s66, 8, v162
	v_ashrrev_i32_e32 v165, 31, v164
	s_add_u32 s18, s56, s18
	v_ashrrev_i32_e32 v139, 31, v138
	v_lshlrev_b64 v[158:159], 10, v[164:165]
	s_addc_u32 s19, s57, s19
	v_lshl_add_u64 v[158:159], s[18:19], 0, v[158:159]
	v_lshlrev_b64 v[138:139], 1, v[138:139]
	v_pk_mul_f32 v[62:63], v[62:63], s[38:39] op_sel_hi:[1,0]
	v_pk_mul_f32 v[64:65], v[64:65], s[38:39] op_sel_hi:[1,0]
	v_pk_mul_f32 v[58:59], v[58:59], s[38:39] op_sel_hi:[1,0]
	v_lshl_add_u64 v[158:159], v[158:159], 0, v[138:139]
	v_pk_mul_f32 v[118:119], v[118:119], s[38:39] op_sel_hi:[1,0]
	v_pk_mul_f32 v[120:121], v[120:121], s[38:39] op_sel_hi:[1,0]
	v_pk_mul_f32 v[114:115], v[114:115], s[38:39] op_sel_hi:[1,0]
	v_pk_mul_f32 v[102:103], v[102:103], s[38:39] op_sel_hi:[1,0]
	v_pk_mul_f32 v[104:105], v[104:105], s[38:39] op_sel_hi:[1,0]
	v_pk_mul_f32 v[98:99], v[98:99], s[38:39] op_sel_hi:[1,0]
	v_pk_mul_f32 v[86:87], v[86:87], s[38:39] op_sel_hi:[1,0]
	v_pk_mul_f32 v[88:89], v[88:89], s[38:39] op_sel_hi:[1,0]
	v_pk_mul_f32 v[82:83], v[82:83], s[38:39] op_sel_hi:[1,0]
	v_cvt_pk_bf16_f32 v62, v62, v63
	v_cvt_pk_bf16_f32 v63, v64, v65
	v_cvt_pk_bf16_f32 v64, v58, v59
	v_pk_mul_f32 v[58:59], v[60:61], s[38:39] op_sel_hi:[1,0]
	s_mov_b32 s17, 0x20000
	v_cvt_pk_bf16_f32 v118, v118, v119
	v_cvt_pk_bf16_f32 v119, v120, v121
	v_cvt_pk_bf16_f32 v120, v114, v115
	v_pk_mul_f32 v[114:115], v[116:117], s[38:39] op_sel_hi:[1,0]
	v_cvt_pk_bf16_f32 v102, v102, v103
	v_cvt_pk_bf16_f32 v103, v104, v105
	v_cvt_pk_bf16_f32 v104, v98, v99
	v_pk_mul_f32 v[98:99], v[100:101], s[38:39] op_sel_hi:[1,0]
	v_cvt_pk_bf16_f32 v86, v86, v87
	v_cvt_pk_bf16_f32 v87, v88, v89
	v_cvt_pk_bf16_f32 v88, v82, v83
	v_pk_mul_f32 v[82:83], v[84:85], s[38:39] op_sel_hi:[1,0]
	v_cvt_pk_bf16_f32 v65, v58, v59
	v_add_co_u32_e32 v58, vcc, s17, v158
	v_pk_mul_f32 v[46:47], v[46:47], s[38:39] op_sel_hi:[1,0]
	v_pk_mul_f32 v[48:49], v[48:49], s[38:39] op_sel_hi:[1,0]
	v_pk_mul_f32 v[42:43], v[42:43], s[38:39] op_sel_hi:[1,0]
	v_cvt_pk_bf16_f32 v121, v114, v115
	v_or_b32_e32 v114, 16, v164
	v_cvt_pk_bf16_f32 v105, v98, v99
	v_or_b32_e32 v98, 32, v164
	v_cvt_pk_bf16_f32 v89, v82, v83
	v_or_b32_e32 v82, 48, v164
	v_addc_co_u32_e32 v59, vcc, 0, v159, vcc
	v_cvt_pk_bf16_f32 v46, v46, v47
	v_cvt_pk_bf16_f32 v47, v48, v49
	v_cvt_pk_bf16_f32 v48, v42, v43
	v_pk_mul_f32 v[42:43], v[44:45], s[38:39] op_sel_hi:[1,0]
	s_mov_b32 s17, 0x24000
	v_ashrrev_i32_e32 v115, 31, v114
	v_ashrrev_i32_e32 v99, 31, v98
	v_ashrrev_i32_e32 v83, 31, v82
	v_cvt_pk_bf16_f32 v49, v42, v43
	v_add_co_u32_e32 v42, vcc, s17, v158
	v_pk_mul_f32 v[30:31], v[30:31], s[38:39] op_sel_hi:[1,0]
	v_pk_mul_f32 v[32:33], v[32:33], s[38:39] op_sel_hi:[1,0]
	v_pk_mul_f32 v[26:27], v[26:27], s[38:39] op_sel_hi:[1,0]
	v_lshlrev_b64 v[114:115], 10, v[114:115]
	v_lshlrev_b64 v[98:99], 10, v[98:99]
	v_lshlrev_b64 v[82:83], 10, v[82:83]
	v_pk_mul_f32 v[70:71], v[70:71], s[38:39] op_sel_hi:[1,0]
	v_pk_mul_f32 v[72:73], v[72:73], s[38:39] op_sel_hi:[1,0]
	v_pk_mul_f32 v[66:67], v[66:67], s[38:39] op_sel_hi:[1,0]
	v_addc_co_u32_e32 v43, vcc, 0, v159, vcc
	v_cvt_pk_bf16_f32 v30, v30, v31
	v_cvt_pk_bf16_f32 v31, v32, v33
	v_cvt_pk_bf16_f32 v32, v26, v27
	v_pk_mul_f32 v[26:27], v[28:29], s[38:39] op_sel_hi:[1,0]
	s_mov_b32 s17, 0x28000
	v_lshl_add_u64 v[114:115], s[18:19], 0, v[114:115]
	v_lshl_add_u64 v[98:99], s[18:19], 0, v[98:99]
	v_lshl_add_u64 v[82:83], s[18:19], 0, v[82:83]
	v_cvt_pk_bf16_f32 v70, v70, v71
	v_cvt_pk_bf16_f32 v71, v72, v73
	v_cvt_pk_bf16_f32 v72, v66, v67
	v_pk_mul_f32 v[66:67], v[68:69], s[38:39] op_sel_hi:[1,0]
	s_mov_b64 s[18:19], 0x20000
	v_pk_mul_f32 v[54:55], v[54:55], s[38:39] op_sel_hi:[1,0]
	v_pk_mul_f32 v[56:57], v[56:57], s[38:39] op_sel_hi:[1,0]
	v_pk_mul_f32 v[50:51], v[50:51], s[38:39] op_sel_hi:[1,0]
	v_cvt_pk_bf16_f32 v33, v26, v27
	v_add_co_u32_e32 v26, vcc, s17, v158
	v_pk_mul_f32 v[14:15], v[14:15], s[38:39] op_sel_hi:[1,0]
	v_pk_mul_f32 v[16:17], v[16:17], s[38:39] op_sel_hi:[1,0]
	v_pk_mul_f32 v[10:11], v[10:11], s[38:39] op_sel_hi:[1,0]
	v_cvt_pk_bf16_f32 v73, v66, v67
	v_lshl_add_u64 v[66:67], v[158:159], 0, s[18:19]
	v_cvt_pk_bf16_f32 v54, v54, v55
	v_cvt_pk_bf16_f32 v55, v56, v57
	v_cvt_pk_bf16_f32 v56, v50, v51
	v_pk_mul_f32 v[50:51], v[52:53], s[38:39] op_sel_hi:[1,0]
; __device__ __forceinline__ void nt_store16(void* p, const uint4 v) { __builtin_nontemporal_store((u32x4){v.x, v.y, v.z, v.w}, (u32x4*)p); }
; __device__ __forceinline__ uint4 pack_acc8(const f32x4 a, const f32x4 b, float s) { uint4 w; w.x = cvt_pk_bf16(a[0] * s, a[1] * s); w.y = cvt_pk_bf16(a[2] * s, a[3] * s); w.z = cvt_pk_bf16(b[0] * s, b[1] * s); w.w = cvt_pk_bf16(b[2] * s, b[3] * s); return w; }
;     __device__ __forceinline__ void operator()(AccT acc, const Unit& u, int wr, int wc, int fr, int fq) const {
;         const int row0 = u.pm * BM + wr * 64 + fr, col0 = u.pn * BM + wc * 32 + 8 * fq;
; #pragma unroll
;         for (int ai = 0; ai < 2; ++ai)
; #pragma unroll
;             for (int m = 0; m < 4; ++m) { const size_t row = (size_t)u.z * 1024 + (row0 + ai * HALF + m * 16);
; #pragma unroll
;                 for (int bj = 0; bj < 2; ++bj) nt_store16(PQ + row * 512 + col0 + bj * HALF, pack_acc8(acc[ai][bj][m][0], acc[ai][bj][m][1], 1.0f / 512.0f)); }
	s_mov_b64 s[18:19], 0x24000
	v_pk_mul_f32 v[38:39], v[38:39], s[38:39] op_sel_hi:[1,0]
	v_pk_mul_f32 v[40:41], v[40:41], s[38:39] op_sel_hi:[1,0]
	v_pk_mul_f32 v[34:35], v[34:35], s[38:39] op_sel_hi:[1,0]
	v_addc_co_u32_e32 v27, vcc, 0, v159, vcc
	v_cvt_pk_bf16_f32 v14, v14, v15
	v_cvt_pk_bf16_f32 v15, v16, v17
	v_cvt_pk_bf16_f32 v16, v10, v11
	v_pk_mul_f32 v[10:11], v[12:13], s[38:39] op_sel_hi:[1,0]
	s_mov_b32 s17, 0x2c000
	v_pk_mul_f32 v[126:127], v[126:127], s[38:39] op_sel_hi:[1,0]
	v_pk_mul_f32 v[128:129], v[128:129], s[38:39] op_sel_hi:[1,0]
	v_pk_mul_f32 v[122:123], v[122:123], s[38:39] op_sel_hi:[1,0]
	v_pk_mul_f32 v[110:111], v[110:111], s[38:39] op_sel_hi:[1,0]
	v_pk_mul_f32 v[112:113], v[112:113], s[38:39] op_sel_hi:[1,0]
	v_pk_mul_f32 v[106:107], v[106:107], s[38:39] op_sel_hi:[1,0]
	v_pk_mul_f32 v[94:95], v[94:95], s[38:39] op_sel_hi:[1,0]
	v_pk_mul_f32 v[96:97], v[96:97], s[38:39] op_sel_hi:[1,0]
	v_pk_mul_f32 v[90:91], v[90:91], s[38:39] op_sel_hi:[1,0]
	v_pk_mul_f32 v[78:79], v[78:79], s[38:39] op_sel_hi:[1,0]
	v_pk_mul_f32 v[80:81], v[80:81], s[38:39] op_sel_hi:[1,0]
	v_pk_mul_f32 v[74:75], v[74:75], s[38:39] op_sel_hi:[1,0]
	v_cvt_pk_bf16_f32 v57, v50, v51
	v_lshl_add_u64 v[50:51], v[158:159], 0, s[18:19]
	v_cvt_pk_bf16_f32 v38, v38, v39
	v_cvt_pk_bf16_f32 v39, v40, v41
	v_cvt_pk_bf16_f32 v40, v34, v35
	v_pk_mul_f32 v[34:35], v[36:37], s[38:39] op_sel_hi:[1,0]
	s_mov_b64 s[18:19], 0x28000
	v_pk_mul_f32 v[22:23], v[22:23], s[38:39] op_sel_hi:[1,0]
	v_pk_mul_f32 v[24:25], v[24:25], s[38:39] op_sel_hi:[1,0]
	v_pk_mul_f32 v[18:19], v[18:19], s[38:39] op_sel_hi:[1,0]
	v_cvt_pk_bf16_f32 v17, v10, v11
	v_add_co_u32_e32 v10, vcc, s17, v158
	v_pk_mul_f32 v[6:7], v[6:7], s[38:39] op_sel_hi:[1,0]
	v_pk_mul_f32 v[8:9], v[8:9], s[38:39] op_sel_hi:[1,0]
	v_pk_mul_f32 v[2:3], v[2:3], s[38:39] op_sel_hi:[1,0]
	v_cvt_pk_bf16_f32 v126, v126, v127
	v_cvt_pk_bf16_f32 v127, v128, v129
	v_cvt_pk_bf16_f32 v128, v122, v123
	v_pk_mul_f32 v[122:123], v[124:125], s[38:39] op_sel_hi:[1,0]
	v_cvt_pk_bf16_f32 v110, v110, v111
	v_cvt_pk_bf16_f32 v111, v112, v113
	v_cvt_pk_bf16_f32 v112, v106, v107
	v_pk_mul_f32 v[106:107], v[108:109], s[38:39] op_sel_hi:[1,0]
	v_cvt_pk_bf16_f32 v94, v94, v95
	v_cvt_pk_bf16_f32 v95, v96, v97
	v_cvt_pk_bf16_f32 v96, v90, v91
	v_pk_mul_f32 v[90:91], v[92:93], s[38:39] op_sel_hi:[1,0]
	v_cvt_pk_bf16_f32 v78, v78, v79
	v_cvt_pk_bf16_f32 v79, v80, v81
	v_cvt_pk_bf16_f32 v80, v74, v75
	v_pk_mul_f32 v[74:75], v[76:77], s[38:39] op_sel_hi:[1,0]
	v_cvt_pk_bf16_f32 v41, v34, v35
	v_lshl_add_u64 v[34:35], v[158:159], 0, s[18:19]
	v_cvt_pk_bf16_f32 v22, v22, v23
	v_cvt_pk_bf16_f32 v23, v24, v25
	v_cvt_pk_bf16_f32 v24, v18, v19
	v_pk_mul_f32 v[18:19], v[20:21], s[38:39] op_sel_hi:[1,0]
	s_mov_b64 s[18:19], 0x2c000
	v_addc_co_u32_e32 v11, vcc, 0, v159, vcc
	v_cvt_pk_bf16_f32 v6, v6, v7
	v_cvt_pk_bf16_f32 v7, v8, v9
	v_cvt_pk_bf16_f32 v8, v2, v3
	v_pk_mul_f32 v[2:3], v[4:5], s[38:39] op_sel_hi:[1,0]
	v_cvt_pk_bf16_f32 v129, v122, v123
	v_lshl_add_u64 v[114:115], v[114:115], 0, v[138:139]
	v_cvt_pk_bf16_f32 v113, v106, v107
	v_lshl_add_u64 v[98:99], v[98:99], 0, v[138:139]
	v_cvt_pk_bf16_f32 v97, v90, v91
	v_lshl_add_u64 v[82:83], v[82:83], 0, v[138:139]
	v_cvt_pk_bf16_f32 v81, v74, v75
	v_cvt_pk_bf16_f32 v25, v18, v19
	v_lshl_add_u64 v[18:19], v[158:159], 0, s[18:19]
	v_cvt_pk_bf16_f32 v9, v2, v3
	s_and_b64 vcc, exec, s[2:3]
	s_mov_b64 s[2:3], -1
	global_store_dwordx4 v[158:159], v[126:129], off
	global_store_dwordx4 v[158:159], v[118:121], off offset:256
	global_store_dwordx4 v[114:115], v[110:113], off
	global_store_dwordx4 v[114:115], v[102:105], off offset:256
	global_store_dwordx4 v[98:99], v[94:97], off
	global_store_dwordx4 v[98:99], v[86:89], off offset:256
	global_store_dwordx4 v[82:83], v[78:81], off
	global_store_dwordx4 v[82:83], v[70:73], off offset:256
	global_store_dwordx4 v[58:59], v[62:65], off
	global_store_dwordx4 v[66:67], v[54:57], off offset:256
	global_store_dwordx4 v[42:43], v[46:49], off
	global_store_dwordx4 v[50:51], v[38:41], off offset:256
	global_store_dwordx4 v[26:27], v[30:33], off
	global_store_dwordx4 v[34:35], v[22:25], off offset:256
	global_store_dwordx4 v[10:11], v[14:17], off
	global_store_dwordx4 v[18:19], v[6:9], off offset:256
	s_cbranch_vccnz .LBB0_374
	s_andn2_b64 vcc, exec, s[10:11]
	s_cbranch_vccnz .LBB0_373
	s_barrier
	s_branch .LBB0_373

; __device__ __forceinline__ unsigned cvt_pk_bf16(float lo, float hi) { const f32x2_t v = {lo, hi}; const bf16x2_t b = __builtin_convertvector(v, bf16x2_t); return __builtin_bit_cast(unsigned, b); }
; __device__ void fnet_nyquist_phase(const Params& p) {
;     ...
;     for (int pr = gw; pr < NB_ * 512; pr += nw) {
;         const int b = pr >> 9, n = pr & 511;
;         const bf16_t* a = FT + ((size_t)(b * 2) * 512 + n) * SEQ_;
;         float acc = 0.f;
; #pragma unroll
;         for (int i = 0; i < 4; ++i) { float f[8]; unpack8(*(const uint4*)(a + (lane + 64 * i) * 8), f); acc += (f[0] - f[1]) + (f[2] - f[3]) + (f[4] - f[5]) + (f[6] - f[7]); }
; #pragma unroll
;         for (int o = 32; o >= 1; o >>= 1) acc += __shfl_xor(acc, o);
;         if (lane == 0) { const float y = acc * (1.0f / 512.0f); YB[((size_t)b * SEQ_ + 1024) * 512 + n] = (bf16_t)(cvt_pk_bf16(y, y) & 0xffffu); }
;     }
.LBB0_393:
	v_ashrrev_i32_e32 v4, 9, v6
	v_lshlrev_b32_e32 v14, 1, v4
	v_ashrrev_i32_e32 v15, 31, v14
	v_and_b32_e32 v13, 0x1ff, v6
	v_lshlrev_b64 v[14:15], 21, v[14:15]
	v_lshl_add_u64 v[14:15], s[6:7], 0, v[14:15]
	v_lshlrev_b32_e32 v0, 12, v13
	v_lshl_add_u64 v[14:15], v[14:15], 0, v[0:1]
	s_waitcnt lgkmcnt(0)
	v_mov_b32_e32 v3, v1
	v_lshl_add_u64 v[18:19], v[14:15], 0, v[2:3]
	s_waitcnt vmcnt(0)
	global_load_dwordx4 v[14:17], v[18:19], off
	s_waitcnt vmcnt(0) lgkmcnt(0)
	v_lshlrev_b32_e32 v0, 16, v14
	v_and_b32_e32 v3, 0xffff0000, v14
	v_lshlrev_b32_e32 v5, 16, v15
	v_and_b32_e32 v14, 0xffff0000, v15
	v_lshlrev_b32_e32 v15, 16, v16
	v_and_b32_e32 v16, 0xffff0000, v16
	v_sub_f32_e32 v0, v0, v3
	v_sub_f32_e32 v3, v5, v14
	v_lshlrev_b32_e32 v20, 16, v17
	v_and_b32_e32 v17, 0xffff0000, v17
	v_add_f32_e32 v0, v0, v3
	v_sub_f32_e32 v3, v15, v16
	v_add_f32_e32 v0, v0, v3
	v_sub_f32_e32 v3, v20, v17
	global_load_dwordx4 v[14:17], v[18:19], off offset:1024
	v_add_f32_e32 v0, v0, v3
	v_add_f32_e32 v0, 0, v0
	s_waitcnt vmcnt(0) lgkmcnt(0)
	v_lshlrev_b32_e32 v3, 16, v14
	v_and_b32_e32 v5, 0xffff0000, v14
	v_lshlrev_b32_e32 v14, 16, v15
	v_and_b32_e32 v15, 0xffff0000, v15
	v_lshlrev_b32_e32 v20, 16, v16
	v_and_b32_e32 v16, 0xffff0000, v16
	v_sub_f32_e32 v3, v3, v5
	v_sub_f32_e32 v5, v14, v15
	v_lshlrev_b32_e32 v21, 16, v17
	v_and_b32_e32 v17, 0xffff0000, v17
	v_add_f32_e32 v3, v3, v5
	v_sub_f32_e32 v5, v20, v16
	v_add_f32_e32 v3, v3, v5
	v_sub_f32_e32 v5, v21, v17
	global_load_dwordx4 v[14:17], v[18:19], off offset:2048
	v_add_f32_e32 v3, v3, v5
	v_add_f32_e32 v0, v0, v3
	s_waitcnt vmcnt(0) lgkmcnt(0)
	v_lshlrev_b32_e32 v3, 16, v14
	v_and_b32_e32 v5, 0xffff0000, v14
	v_lshlrev_b32_e32 v14, 16, v15
	v_and_b32_e32 v15, 0xffff0000, v15
	v_lshlrev_b32_e32 v20, 16, v16
	v_and_b32_e32 v16, 0xffff0000, v16
	v_sub_f32_e32 v3, v3, v5
	v_sub_f32_e32 v5, v14, v15
	v_lshlrev_b32_e32 v21, 16, v17
	v_and_b32_e32 v17, 0xffff0000, v17
	v_add_f32_e32 v3, v3, v5
	v_sub_f32_e32 v5, v20, v16
	v_add_f32_e32 v3, v3, v5
	v_sub_f32_e32 v5, v21, v17
	global_load_dwordx4 v[14:17], v[18:19], off offset:3072
	v_add_f32_e32 v3, v3, v5
	v_add_f32_e32 v0, v0, v3
	s_waitcnt vmcnt(0) lgkmcnt(0)
	v_lshlrev_b32_e32 v3, 16, v14
	v_and_b32_e32 v5, 0xffff0000, v14
	v_lshlrev_b32_e32 v14, 16, v15
	v_and_b32_e32 v15, 0xffff0000, v15
	v_lshlrev_b32_e32 v18, 16, v16
	v_and_b32_e32 v16, 0xffff0000, v16
	v_sub_f32_e32 v3, v3, v5
	v_sub_f32_e32 v5, v14, v15
	v_lshlrev_b32_e32 v19, 16, v17
	v_and_b32_e32 v17, 0xffff0000, v17
	v_add_f32_e32 v3, v3, v5
	v_sub_f32_e32 v5, v18, v16
	v_add_f32_e32 v3, v3, v5
	v_sub_f32_e32 v5, v19, v17
	v_add_f32_e32 v3, v3, v5
	v_add_f32_e32 v0, v0, v3
	ds_bpermute_b32 v3, v7, v0
	s_waitcnt lgkmcnt(0)
	v_add_f32_e32 v0, v0, v3
	ds_bpermute_b32 v3, v8, v0
	s_waitcnt lgkmcnt(0)
	v_add_f32_e32 v0, v0, v3
	ds_bpermute_b32 v3, v9, v0
	s_waitcnt lgkmcnt(0)
	v_add_f32_e32 v0, v0, v3
	ds_bpermute_b32 v3, v10, v0
	s_waitcnt lgkmcnt(0)
	v_add_f32_e32 v0, v0, v3
	ds_bpermute_b32 v3, v11, v0
	s_waitcnt lgkmcnt(0)
	v_add_f32_e32 v0, v0, v3
	ds_bpermute_b32 v3, v12, v0
	s_and_saveexec_b64 s[2:3], vcc
	s_cbranch_execz .LBB0_392
	s_waitcnt lgkmcnt(0)
	v_add_f32_e32 v0, v0, v3
	v_ashrrev_i32_e32 v5, 31, v4
	v_mul_f32_e32 v0, 0x3b000000, v0
	v_lshlrev_b64 v[4:5], 21, v[4:5]
	v_cvt_pk_bf16_f32 v3, v0, s0
	v_lshl_add_u64 v[4:5], s[8:9], 0, v[4:5]
	v_lshlrev_b32_e32 v0, 1, v13
	v_lshl_add_u64 v[4:5], v[4:5], 0, v[0:1]
	global_store_short v[4:5], v3, off
	s_branch .LBB0_392

; __device__ __forceinline__ void nt_store16(void* p, const uint4 v) { __builtin_nontemporal_store((u32x4){v.x, v.y, v.z, v.w}, (u32x4*)p); }
; __device__ __forceinline__ uint4 pack_acc8(const f32x4 a, const f32x4 b, float s) { uint4 w; w.x = cvt_pk_bf16(a[0] * s, a[1] * s); w.y = cvt_pk_bf16(a[2] * s, a[3] * s); w.z = cvt_pk_bf16(b[0] * s, b[1] * s); w.w = cvt_pk_bf16(b[2] * s, b[3] * s); return w; }
;     __device__ __forceinline__ void operator()(AccT acc, const Unit& u, int wr, int wc, int fr, int fq) const {
;         const int row0 = u.pm * BM + wr * 64 + fr, col0 = u.pn * BM + wc * 32 + 8 * fq;
; #pragma unroll
;         for (int ai = 0; ai < 2; ++ai)
; #pragma unroll
;             for (int m = 0; m < 4; ++m) { const size_t row = (size_t)(row0 + ai * HALF + m * 16);
; #pragma unroll
;                 for (int bj = 0; bj < 2; ++bj) { const int c = col0 + bj * HALF;
;                     bf16_t* dst = (c < ZGC) ? (ZG + row * ZGC + c) : (ZR + row * ZRC + (c - ZGC));
;                     nt_store16(dst, pack_acc8(acc[ai][bj][m][0], acc[ai][bj][m][1], 1.0f)); } }
;     }
.LBB0_470:
	v_lshl_add_u32 v183, s67, 8, v179
	v_mad_i64_i32 v[138:139], s[4:5], v183, s46, 0
	v_lshl_or_b32 v160, s66, 8, v181
	s_movk_i32 s4, 0x61f
	v_cmp_lt_i32_e32 vcc, s4, v160
	v_lshl_add_u64 v[162:163], s[14:15], 0, v[138:139]
	s_and_saveexec_b64 s[4:5], vcc
	s_xor_b64 s[4:5], exec, s[4:5]
	v_mov_b32_e32 v161, v1
	s_movk_i32 s24, 0xf3c0
	v_lshl_add_u64 v[138:139], v[160:161], 1, v[162:163]
	s_mov_b32 s25, -1
	v_lshl_add_u64 v[166:167], v[138:139], 0, s[24:25]
	s_or_saveexec_b64 s[4:5], s[4:5]
	v_mad_i64_i32 v[138:139], s[24:25], v183, s47, 0
	v_readlane_b32 s24, v254, 35
	v_readlane_b32 s25, v254, 36
	v_ashrrev_i32_e32 v161, 31, v160
	s_mov_b64 s[66:67], 0x100
	v_lshl_add_u64 v[164:165], s[24:25], 0, v[138:139]
	s_xor_b64 exec, exec, s[4:5]
	v_lshl_add_u64 v[166:167], v[160:161], 1, v[164:165]
	s_or_b64 exec, exec, s[4:5]
	v_or_b32_e32 v0, 0x80, v160
	s_movk_i32 s4, 0x61f
	v_cvt_pk_bf16_f32 v122, v122, v123
	v_cvt_pk_bf16_f32 v123, v124, v125
	v_cvt_pk_bf16_f32 v124, v126, v127
	v_cvt_pk_bf16_f32 v125, v128, v129
	v_cmp_lt_i32_e64 s[4:5], s4, v0
	global_store_dwordx4 v[166:167], v[122:125], off
	s_and_saveexec_b64 s[24:25], s[4:5]
	s_xor_b64 s[24:25], exec, s[24:25]
	v_mov_b32_e32 v0, v160
	s_movk_i32 s34, 0xf4c0
	v_lshl_add_u64 v[122:123], v[0:1], 1, v[162:163]
	s_mov_b32 s35, -1
	v_lshl_add_u64 v[122:123], v[122:123], 0, s[34:35]
	s_andn2_saveexec_b64 s[24:25], s[24:25]
	v_lshl_add_u64 v[122:123], v[160:161], 1, v[164:165]
	v_lshl_add_u64 v[122:123], v[122:123], 0, s[66:67]
	s_or_b64 exec, exec, s[24:25]
	v_cvt_pk_bf16_f32 v118, v118, v119
	v_cvt_pk_bf16_f32 v119, v120, v121
	v_cvt_pk_bf16_f32 v121, v116, v117
	v_or_b32_e32 v116, 16, v183
	v_cvt_pk_bf16_f32 v120, v114, v115
	v_mad_i64_i32 v[114:115], s[24:25], v116, s46, 0
	v_lshl_add_u64 v[114:115], s[14:15], 0, v[114:115]
	global_store_dwordx4 v[122:123], v[118:121], off
	s_and_saveexec_b64 s[24:25], vcc
	s_xor_b64 s[24:25], exec, s[24:25]
	v_mov_b32_e32 v0, v160
	s_movk_i32 s34, 0xf3c0
	v_lshl_add_u64 v[118:119], v[0:1], 1, v[114:115]
	s_mov_b32 s35, -1
	v_lshl_add_u64 v[118:119], v[118:119], 0, s[34:35]
	s_or_saveexec_b64 s[24:25], s[24:25]
	v_mad_i64_i32 v[116:117], s[34:35], v116, s47, 0
	v_readlane_b32 s34, v254, 35
	v_readlane_b32 s35, v254, 36
	s_nop 1
	v_lshl_add_u64 v[116:117], s[34:35], 0, v[116:117]
	s_xor_b64 exec, exec, s[24:25]
	v_lshl_add_u64 v[118:119], v[160:161], 1, v[116:117]
	s_or_b64 exec, exec, s[24:25]
	v_cvt_pk_bf16_f32 v110, v110, v111
	v_cvt_pk_bf16_f32 v111, v112, v113
	v_cvt_pk_bf16_f32 v112, v106, v107
	v_cvt_pk_bf16_f32 v113, v108, v109
	global_store_dwordx4 v[118:119], v[110:113], off
	s_and_saveexec_b64 s[24:25], s[4:5]
	s_xor_b64 s[24:25], exec, s[24:25]
	v_mov_b32_e32 v0, v160
	s_movk_i32 s34, 0xf4c0
	v_lshl_add_u64 v[106:107], v[0:1], 1, v[114:115]
	s_mov_b32 s35, -1
	v_lshl_add_u64 v[106:107], v[106:107], 0, s[34:35]
	s_andn2_saveexec_b64 s[24:25], s[24:25]
	v_lshl_add_u64 v[106:107], v[160:161], 1, v[116:117]
	v_lshl_add_u64 v[106:107], v[106:107], 0, s[66:67]
	s_or_b64 exec, exec, s[24:25]
	v_cvt_pk_bf16_f32 v102, v102, v103
	v_cvt_pk_bf16_f32 v103, v104, v105
	v_cvt_pk_bf16_f32 v105, v100, v101
	v_or_b32_e32 v100, 32, v183
	v_cvt_pk_bf16_f32 v104, v98, v99
	v_mad_i64_i32 v[98:99], s[24:25], v100, s46, 0
	v_lshl_add_u64 v[98:99], s[14:15], 0, v[98:99]
	global_store_dwordx4 v[106:107], v[102:105], off
	s_and_saveexec_b64 s[24:25], vcc
	s_xor_b64 s[24:25], exec, s[24:25]
	v_mov_b32_e32 v0, v160
	s_movk_i32 s34, 0xf3c0
	v_lshl_add_u64 v[102:103], v[0:1], 1, v[98:99]
	s_mov_b32 s35, -1
	v_lshl_add_u64 v[102:103], v[102:103], 0, s[34:35]
	s_or_saveexec_b64 s[24:25], s[24:25]
	v_mad_i64_i32 v[100:101], s[34:35], v100, s47, 0
	v_readlane_b32 s34, v254, 35
	v_readlane_b32 s35, v254, 36
	s_nop 1
	v_lshl_add_u64 v[100:101], s[34:35], 0, v[100:101]
	s_xor_b64 exec, exec, s[24:25]
	v_lshl_add_u64 v[102:103], v[160:161], 1, v[100:101]
	s_or_b64 exec, exec, s[24:25]
	v_cvt_pk_bf16_f32 v94, v94, v95
	v_cvt_pk_bf16_f32 v95, v96, v97
	v_cvt_pk_bf16_f32 v96, v90, v91
	v_cvt_pk_bf16_f32 v97, v92, v93
	global_store_dwordx4 v[102:103], v[94:97], off
	s_and_saveexec_b64 s[24:25], s[4:5]
	s_xor_b64 s[24:25], exec, s[24:25]
	v_mov_b32_e32 v0, v160
	s_movk_i32 s34, 0xf4c0
	v_lshl_add_u64 v[90:91], v[0:1], 1, v[98:99]
	s_mov_b32 s35, -1
	v_lshl_add_u64 v[90:91], v[90:91], 0, s[34:35]
	s_andn2_saveexec_b64 s[24:25], s[24:25]
	v_lshl_add_u64 v[90:91], v[160:161], 1, v[100:101]
	v_lshl_add_u64 v[90:91], v[90:91], 0, s[66:67]
	s_or_b64 exec, exec, s[24:25]
	v_cvt_pk_bf16_f32 v86, v86, v87
	v_cvt_pk_bf16_f32 v87, v88, v89
	v_cvt_pk_bf16_f32 v89, v84, v85
	v_or_b32_e32 v84, 48, v183
	v_cvt_pk_bf16_f32 v88, v82, v83
	v_mad_i64_i32 v[82:83], s[24:25], v84, s46, 0
	v_lshl_add_u64 v[82:83], s[14:15], 0, v[82:83]
	global_store_dwordx4 v[90:91], v[86:89], off
	s_and_saveexec_b64 s[24:25], vcc
	s_xor_b64 s[24:25], exec, s[24:25]
	v_mov_b32_e32 v0, v160
	s_movk_i32 s34, 0xf3c0
	v_lshl_add_u64 v[86:87], v[0:1], 1, v[82:83]
	s_mov_b32 s35, -1
	v_lshl_add_u64 v[86:87], v[86:87], 0, s[34:35]
	s_or_saveexec_b64 s[24:25], s[24:25]
	v_mad_i64_i32 v[84:85], s[34:35], v84, s47, 0
	v_readlane_b32 s34, v254, 35
	v_readlane_b32 s35, v254, 36
	s_nop 1
	v_lshl_add_u64 v[84:85], s[34:35], 0, v[84:85]
	s_xor_b64 exec, exec, s[24:25]
	v_lshl_add_u64 v[86:87], v[160:161], 1, v[84:85]
	s_or_b64 exec, exec, s[24:25]
	v_cvt_pk_bf16_f32 v78, v78, v79
	v_cvt_pk_bf16_f32 v79, v80, v81
	v_cvt_pk_bf16_f32 v80, v74, v75
	v_cvt_pk_bf16_f32 v81, v76, v77
	global_store_dwordx4 v[86:87], v[78:81], off
	s_and_saveexec_b64 s[24:25], s[4:5]
	s_xor_b64 s[24:25], exec, s[24:25]
	v_mov_b32_e32 v0, v160
; __device__ __forceinline__ void nt_store16(void* p, const uint4 v) { __builtin_nontemporal_store((u32x4){v.x, v.y, v.z, v.w}, (u32x4*)p); }
; __device__ __forceinline__ uint4 pack_acc8(const f32x4 a, const f32x4 b, float s) { uint4 w; w.x = cvt_pk_bf16(a[0] * s, a[1] * s); w.y = cvt_pk_bf16(a[2] * s, a[3] * s); w.z = cvt_pk_bf16(b[0] * s, b[1] * s); w.w = cvt_pk_bf16(b[2] * s, b[3] * s); return w; }
;     __device__ __forceinline__ void operator()(AccT acc, const Unit& u, int wr, int wc, int fr, int fq) const {
;     ...
;             for (int m = 0; m < 4; ++m) { const size_t row = (size_t)(row0 + ai * HALF + m * 16);
; #pragma unroll
;                 for (int bj = 0; bj < 2; ++bj) { const int c = col0 + bj * HALF;
;                     bf16_t* dst = (c < ZGC) ? (ZG + row * ZGC + c) : (ZR + row * ZRC + (c - ZGC));
;                     nt_store16(dst, pack_acc8(acc[ai][bj][m][0], acc[ai][bj][m][1], 1.0f)); } }
;     }
	s_movk_i32 s34, 0xf4c0
	v_lshl_add_u64 v[74:75], v[0:1], 1, v[82:83]
	s_mov_b32 s35, -1
	v_lshl_add_u64 v[74:75], v[74:75], 0, s[34:35]
	s_andn2_saveexec_b64 s[24:25], s[24:25]
	v_lshl_add_u64 v[74:75], v[160:161], 1, v[84:85]
	v_lshl_add_u64 v[74:75], v[74:75], 0, s[66:67]
	s_or_b64 exec, exec, s[24:25]
	v_cvt_pk_bf16_f32 v70, v70, v71
	v_cvt_pk_bf16_f32 v71, v72, v73
	v_cvt_pk_bf16_f32 v73, v68, v69
	v_add_u32_e32 v68, 0x80, v183
	v_cvt_pk_bf16_f32 v72, v66, v67
	v_mad_i64_i32 v[66:67], s[24:25], v68, s46, 0
	v_lshl_add_u64 v[66:67], s[14:15], 0, v[66:67]
	global_store_dwordx4 v[74:75], v[70:73], off
	s_and_saveexec_b64 s[24:25], vcc
	s_xor_b64 s[24:25], exec, s[24:25]
	v_mov_b32_e32 v0, v160
	s_movk_i32 s34, 0xf3c0
	v_lshl_add_u64 v[70:71], v[0:1], 1, v[66:67]
	s_mov_b32 s35, -1
	v_lshl_add_u64 v[70:71], v[70:71], 0, s[34:35]
	s_or_saveexec_b64 s[24:25], s[24:25]
	v_mad_i64_i32 v[68:69], s[34:35], v68, s47, 0
	v_readlane_b32 s34, v254, 35
	v_readlane_b32 s35, v254, 36
	s_nop 1
	v_lshl_add_u64 v[68:69], s[34:35], 0, v[68:69]
	s_xor_b64 exec, exec, s[24:25]
	v_lshl_add_u64 v[70:71], v[160:161], 1, v[68:69]
	s_or_b64 exec, exec, s[24:25]
	v_cvt_pk_bf16_f32 v62, v62, v63
	v_cvt_pk_bf16_f32 v63, v64, v65
	v_cvt_pk_bf16_f32 v64, v58, v59
	v_cvt_pk_bf16_f32 v65, v60, v61
	global_store_dwordx4 v[70:71], v[62:65], off
	s_and_saveexec_b64 s[24:25], s[4:5]
	s_xor_b64 s[24:25], exec, s[24:25]
	v_mov_b32_e32 v0, v160
	s_movk_i32 s34, 0xf4c0
	v_lshl_add_u64 v[58:59], v[0:1], 1, v[66:67]
	s_mov_b32 s35, -1
	v_lshl_add_u64 v[58:59], v[58:59], 0, s[34:35]
	s_andn2_saveexec_b64 s[24:25], s[24:25]
	v_lshl_add_u64 v[58:59], v[160:161], 1, v[68:69]
	v_lshl_add_u64 v[58:59], v[58:59], 0, s[66:67]
	s_or_b64 exec, exec, s[24:25]
	v_cvt_pk_bf16_f32 v54, v54, v55
	v_cvt_pk_bf16_f32 v55, v56, v57
	v_cvt_pk_bf16_f32 v57, v52, v53
	v_add_u32_e32 v52, 0x90, v183
	v_cvt_pk_bf16_f32 v56, v50, v51
	v_mad_i64_i32 v[50:51], s[24:25], v52, s46, 0
	v_lshl_add_u64 v[50:51], s[14:15], 0, v[50:51]
	global_store_dwordx4 v[58:59], v[54:57], off
	s_and_saveexec_b64 s[24:25], vcc
	s_xor_b64 s[24:25], exec, s[24:25]
	v_mov_b32_e32 v0, v160
	s_movk_i32 s34, 0xf3c0
	v_lshl_add_u64 v[54:55], v[0:1], 1, v[50:51]
	s_mov_b32 s35, -1
	v_lshl_add_u64 v[54:55], v[54:55], 0, s[34:35]
	s_or_saveexec_b64 s[24:25], s[24:25]
	v_mad_i64_i32 v[52:53], s[34:35], v52, s47, 0
	v_readlane_b32 s34, v254, 35
	v_readlane_b32 s35, v254, 36
	s_nop 1
	v_lshl_add_u64 v[52:53], s[34:35], 0, v[52:53]
	s_xor_b64 exec, exec, s[24:25]
	v_lshl_add_u64 v[54:55], v[160:161], 1, v[52:53]
	s_or_b64 exec, exec, s[24:25]
	v_cvt_pk_bf16_f32 v46, v46, v47
	v_cvt_pk_bf16_f32 v47, v48, v49
	v_cvt_pk_bf16_f32 v48, v42, v43
	v_cvt_pk_bf16_f32 v49, v44, v45
	global_store_dwordx4 v[54:55], v[46:49], off
	s_and_saveexec_b64 s[24:25], s[4:5]
	s_xor_b64 s[24:25], exec, s[24:25]
	v_mov_b32_e32 v0, v160
	s_movk_i32 s34, 0xf4c0
	v_lshl_add_u64 v[42:43], v[0:1], 1, v[50:51]
	s_mov_b32 s35, -1
	v_lshl_add_u64 v[42:43], v[42:43], 0, s[34:35]
	s_andn2_saveexec_b64 s[24:25], s[24:25]
	v_lshl_add_u64 v[42:43], v[160:161], 1, v[52:53]
	v_lshl_add_u64 v[42:43], v[42:43], 0, s[66:67]
	s_or_b64 exec, exec, s[24:25]
	v_cvt_pk_bf16_f32 v38, v38, v39
	v_cvt_pk_bf16_f32 v39, v40, v41
	v_cvt_pk_bf16_f32 v41, v36, v37
	v_add_u32_e32 v36, 0xa0, v183
	v_cvt_pk_bf16_f32 v40, v34, v35
	v_mad_i64_i32 v[34:35], s[24:25], v36, s46, 0
	v_lshl_add_u64 v[34:35], s[14:15], 0, v[34:35]
	global_store_dwordx4 v[42:43], v[38:41], off
	s_and_saveexec_b64 s[24:25], vcc
	s_xor_b64 s[24:25], exec, s[24:25]
	v_mov_b32_e32 v0, v160
	s_movk_i32 s34, 0xf3c0
	v_lshl_add_u64 v[38:39], v[0:1], 1, v[34:35]
	s_mov_b32 s35, -1
	v_lshl_add_u64 v[38:39], v[38:39], 0, s[34:35]
	s_or_saveexec_b64 s[24:25], s[24:25]
	v_mad_i64_i32 v[36:37], s[34:35], v36, s47, 0
	v_readlane_b32 s34, v254, 35
	v_readlane_b32 s35, v254, 36
	s_nop 1
	v_lshl_add_u64 v[36:37], s[34:35], 0, v[36:37]
	s_xor_b64 exec, exec, s[24:25]
	v_lshl_add_u64 v[38:39], v[160:161], 1, v[36:37]
	s_or_b64 exec, exec, s[24:25]
	v_cvt_pk_bf16_f32 v30, v30, v31
	v_cvt_pk_bf16_f32 v31, v32, v33
	v_cvt_pk_bf16_f32 v32, v26, v27
	v_cvt_pk_bf16_f32 v33, v28, v29
	global_store_dwordx4 v[38:39], v[30:33], off
	s_and_saveexec_b64 s[24:25], s[4:5]
	s_xor_b64 s[24:25], exec, s[24:25]
	v_mov_b32_e32 v0, v160
	s_movk_i32 s34, 0xf4c0
	v_lshl_add_u64 v[26:27], v[0:1], 1, v[34:35]
	s_mov_b32 s35, -1
	v_lshl_add_u64 v[26:27], v[26:27], 0, s[34:35]
	s_andn2_saveexec_b64 s[24:25], s[24:25]
	v_lshl_add_u64 v[26:27], v[160:161], 1, v[36:37]
	v_lshl_add_u64 v[26:27], v[26:27], 0, s[66:67]
	s_or_b64 exec, exec, s[24:25]
	v_cvt_pk_bf16_f32 v22, v22, v23
	v_cvt_pk_bf16_f32 v23, v24, v25
	v_cvt_pk_bf16_f32 v25, v20, v21
	v_add_u32_e32 v20, 0xb0, v183
	v_cvt_pk_bf16_f32 v24, v18, v19
	v_mad_i64_i32 v[18:19], s[24:25], v20, s46, 0
	v_lshl_add_u64 v[18:19], s[14:15], 0, v[18:19]
	global_store_dwordx4 v[26:27], v[22:25], off
	s_and_saveexec_b64 s[24:25], vcc
	s_xor_b64 s[24:25], exec, s[24:25]
	v_mov_b32_e32 v0, v160
	s_movk_i32 s34, 0xf3c0
	v_lshl_add_u64 v[22:23], v[0:1], 1, v[18:19]
	s_mov_b32 s35, -1
	v_lshl_add_u64 v[22:23], v[22:23], 0, s[34:35]
	s_or_saveexec_b64 s[24:25], s[24:25]
	v_mad_i64_i32 v[20:21], s[34:35], v20, s47, 0
	v_readlane_b32 s34, v254, 35
	v_readlane_b32 s35, v254, 36
	s_nop 1
	v_lshl_add_u64 v[20:21], s[34:35], 0, v[20:21]
	s_xor_b64 exec, exec, s[24:25]
	v_lshl_add_u64 v[22:23], v[160:161], 1, v[20:21]
	s_or_b64 exec, exec, s[24:25]
	v_cvt_pk_bf16_f32 v14, v14, v15
	v_cvt_pk_bf16_f32 v15, v16, v17
	v_cvt_pk_bf16_f32 v16, v10, v11
	v_cvt_pk_bf16_f32 v17, v12, v13
	global_store_dwordx4 v[22:23], v[14:17], off
	s_and_saveexec_b64 s[24:25], s[4:5]
	s_xor_b64 s[4:5], exec, s[24:25]
	v_mov_b32_e32 v161, v1
	s_movk_i32 s24, 0xf4c0
	v_lshl_add_u64 v[10:11], v[160:161], 1, v[18:19]
	s_mov_b32 s25, -1
	v_lshl_add_u64 v[10:11], v[10:11], 0, s[24:25]
	s_andn2_saveexec_b64 s[4:5], s[4:5]
	v_lshl_add_u64 v[10:11], v[160:161], 1, v[20:21]
	v_lshl_add_u64 v[10:11], v[10:11], 0, s[66:67]
	s_or_b64 exec, exec, s[4:5]
	v_cvt_pk_bf16_f32 v6, v6, v7
	v_cvt_pk_bf16_f32 v7, v8, v9
	v_cvt_pk_bf16_f32 v8, v2, v3
	v_cvt_pk_bf16_f32 v9, v4, v5
	s_and_b64 vcc, exec, s[2:3]
	s_mov_b64 s[2:3], -1
	global_store_dwordx4 v[10:11], v[6:9], off
	s_cbranch_vccnz .LBB0_457
	s_andn2_b64 vcc, exec, s[12:13]
	s_cbranch_vccnz .LBB0_456
	s_barrier
	s_branch .LBB0_456

; __device__ __forceinline__ void nt_store16(void* p, const uint4 v) { __builtin_nontemporal_store((u32x4){v.x, v.y, v.z, v.w}, (u32x4*)p); }
; __device__ __forceinline__ uint4 pack_acc8(const f32x4 a, const f32x4 b, float s) { uint4 w; w.x = cvt_pk_bf16(a[0] * s, a[1] * s); w.y = cvt_pk_bf16(a[2] * s, a[3] * s); w.z = cvt_pk_bf16(b[0] * s, b[1] * s); w.w = cvt_pk_bf16(b[2] * s, b[3] * s); return w; }
;     __device__ __forceinline__ void operator()(AccT acc, const Unit& u, int wr, int wc, int fr, int fq) const {
;         const int row0 = u.pm * BM + wr * 64 + fr, col0 = u.pn * BM + wc * 32 + 8 * fq;
; #pragma unroll
;         for (int ai = 0; ai < 2; ++ai)
; #pragma unroll
;             for (int m = 0; m < 4; ++m) { const int row = row0 + ai * HALF + m * 16;
; #pragma unroll
;                 for (int bj = 0; bj < 2; ++bj) { const int c = col0 + bj * HALF; const int b = c >> 11, s = c & 2047;
;                     nt_store16(FT + ((size_t)((b * 2 + (row & 1)) * 512 + (row >> 1)) * SEQ_ + s), pack_acc8(acc[ai][bj][m][0], acc[ai][bj][m][1], 1.0f)); } }
;     }
.LBB0_561:
	s_lshl_b32 s20, s61, 8
	s_and_b32 s20, s20, 0x700
	v_or_b32_e32 v0, s20, v163
	s_lshr_b32 s20, s61, 2
	s_and_b32 s20, s20, 0x7ffffe
	v_lshl_add_u32 v165, s58, 8, v160
	v_or_b32_e32 v138, s20, v162
	v_lshlrev_b32_e32 v178, 9, v138
	v_ashrrev_i32_e32 v138, 1, v165
	v_cvt_pk_bf16_f32 v70, v70, v71
	v_cvt_pk_bf16_f32 v71, v72, v73
	v_cvt_pk_bf16_f32 v72, v66, v67
	v_add_u32_e32 v66, 0x80, v165
	v_cvt_pk_bf16_f32 v54, v54, v55
	v_cvt_pk_bf16_f32 v55, v56, v57
	v_cvt_pk_bf16_f32 v56, v50, v51
	v_add_u32_e32 v50, 0x90, v165
	v_cvt_pk_bf16_f32 v38, v38, v39
	v_cvt_pk_bf16_f32 v39, v40, v41
	v_cvt_pk_bf16_f32 v40, v34, v35
	v_add_u32_e32 v34, 0xa0, v165
	v_cvt_pk_bf16_f32 v22, v22, v23
	v_cvt_pk_bf16_f32 v23, v24, v25
	v_cvt_pk_bf16_f32 v24, v18, v19
	v_add_u32_e32 v18, 0xb0, v165
	v_add_u32_e32 v138, v138, v178
	v_ashrrev_i32_e32 v66, 1, v66
	v_ashrrev_i32_e32 v50, 1, v50
	v_ashrrev_i32_e32 v34, 1, v34
	v_ashrrev_i32_e32 v18, 1, v18
	v_cvt_pk_bf16_f32 v118, v118, v119
	v_cvt_pk_bf16_f32 v119, v120, v121
	v_cvt_pk_bf16_f32 v120, v114, v115
	v_add_u32_e32 v114, 8, v138
	v_cvt_pk_bf16_f32 v102, v102, v103
	v_cvt_pk_bf16_f32 v103, v104, v105
	v_cvt_pk_bf16_f32 v104, v98, v99
	v_add_u32_e32 v98, 16, v138
	v_cvt_pk_bf16_f32 v86, v86, v87
	v_cvt_pk_bf16_f32 v87, v88, v89
	v_cvt_pk_bf16_f32 v88, v82, v83
	v_add_u32_e32 v82, 24, v138
	v_add_u32_e32 v66, v66, v178
	v_add_u32_e32 v50, v50, v178
	v_add_u32_e32 v34, v34, v178
	v_add_u32_e32 v18, v18, v178
	v_ashrrev_i32_e32 v139, 31, v138
	v_ashrrev_i32_e32 v115, 31, v114
	v_ashrrev_i32_e32 v99, 31, v98
	v_ashrrev_i32_e32 v83, 31, v82
	v_ashrrev_i32_e32 v67, 31, v66
	v_ashrrev_i32_e32 v51, 31, v50
	v_ashrrev_i32_e32 v35, 31, v34
	v_ashrrev_i32_e32 v19, 31, v18
	v_lshlrev_b64 v[166:167], 12, v[138:139]
	v_lshlrev_b64 v[114:115], 12, v[114:115]
	v_lshlrev_b64 v[98:99], 12, v[98:99]
	v_lshlrev_b64 v[82:83], 12, v[82:83]
	v_lshlrev_b64 v[66:67], 12, v[66:67]
	v_lshlrev_b64 v[50:51], 12, v[50:51]
	v_lshlrev_b64 v[34:35], 12, v[34:35]
	v_lshlrev_b64 v[18:19], 12, v[18:19]
	v_lshl_add_u64 v[166:167], s[6:7], 0, v[166:167]
	v_lshlrev_b32_e32 v0, 1, v0
	v_lshl_add_u64 v[114:115], s[6:7], 0, v[114:115]
	v_lshl_add_u64 v[98:99], s[6:7], 0, v[98:99]
	v_lshl_add_u64 v[82:83], s[6:7], 0, v[82:83]
	v_lshl_add_u64 v[66:67], s[6:7], 0, v[66:67]
	v_lshl_add_u64 v[50:51], s[6:7], 0, v[50:51]
	v_lshl_add_u64 v[34:35], s[6:7], 0, v[34:35]
	v_lshl_add_u64 v[18:19], s[6:7], 0, v[18:19]
	v_lshl_add_u64 v[166:167], v[166:167], 0, v[0:1]
	v_cvt_pk_bf16_f32 v122, v122, v123
	v_cvt_pk_bf16_f32 v123, v124, v125
	v_cvt_pk_bf16_f32 v124, v126, v127
	v_cvt_pk_bf16_f32 v125, v128, v129
	v_cvt_pk_bf16_f32 v121, v116, v117
	v_lshl_add_u64 v[114:115], v[114:115], 0, v[0:1]
	v_cvt_pk_bf16_f32 v110, v110, v111
	v_cvt_pk_bf16_f32 v111, v112, v113
	v_cvt_pk_bf16_f32 v112, v106, v107
	v_cvt_pk_bf16_f32 v113, v108, v109
	v_cvt_pk_bf16_f32 v105, v100, v101
	v_lshl_add_u64 v[98:99], v[98:99], 0, v[0:1]
	v_cvt_pk_bf16_f32 v94, v94, v95
	v_cvt_pk_bf16_f32 v95, v96, v97
	v_cvt_pk_bf16_f32 v96, v90, v91
	v_cvt_pk_bf16_f32 v97, v92, v93
	v_cvt_pk_bf16_f32 v89, v84, v85
	v_lshl_add_u64 v[82:83], v[82:83], 0, v[0:1]
	v_cvt_pk_bf16_f32 v78, v78, v79
	v_cvt_pk_bf16_f32 v79, v80, v81
	v_cvt_pk_bf16_f32 v80, v74, v75
	v_cvt_pk_bf16_f32 v81, v76, v77
	v_cvt_pk_bf16_f32 v73, v68, v69
	v_lshl_add_u64 v[66:67], v[66:67], 0, v[0:1]
	v_cvt_pk_bf16_f32 v62, v62, v63
	v_cvt_pk_bf16_f32 v63, v64, v65
	v_cvt_pk_bf16_f32 v64, v58, v59
	v_cvt_pk_bf16_f32 v65, v60, v61
	v_cvt_pk_bf16_f32 v57, v52, v53
	v_lshl_add_u64 v[50:51], v[50:51], 0, v[0:1]
	v_cvt_pk_bf16_f32 v46, v46, v47
	v_cvt_pk_bf16_f32 v47, v48, v49
	v_cvt_pk_bf16_f32 v48, v42, v43
	v_cvt_pk_bf16_f32 v49, v44, v45
	v_cvt_pk_bf16_f32 v41, v36, v37
	v_lshl_add_u64 v[34:35], v[34:35], 0, v[0:1]
	v_cvt_pk_bf16_f32 v30, v30, v31
	v_cvt_pk_bf16_f32 v31, v32, v33
	v_cvt_pk_bf16_f32 v32, v26, v27
	v_cvt_pk_bf16_f32 v33, v28, v29
	v_cvt_pk_bf16_f32 v25, v20, v21
	v_lshl_add_u64 v[18:19], v[18:19], 0, v[0:1]
	v_cvt_pk_bf16_f32 v14, v14, v15
	v_cvt_pk_bf16_f32 v15, v16, v17
	v_cvt_pk_bf16_f32 v16, v10, v11
	v_cvt_pk_bf16_f32 v17, v12, v13
	v_cvt_pk_bf16_f32 v6, v6, v7
	v_cvt_pk_bf16_f32 v7, v8, v9
	v_cvt_pk_bf16_f32 v8, v2, v3
	v_cvt_pk_bf16_f32 v9, v4, v5
	s_and_b64 vcc, exec, s[2:3]
	s_mov_b64 s[2:3], -1
	global_store_dwordx4 v[166:167], v[122:125], off
	global_store_dwordx4 v[166:167], v[118:121], off offset:256
	global_store_dwordx4 v[114:115], v[110:113], off
	global_store_dwordx4 v[114:115], v[102:105], off offset:256
	global_store_dwordx4 v[98:99], v[94:97], off
	global_store_dwordx4 v[98:99], v[86:89], off offset:256
	global_store_dwordx4 v[82:83], v[78:81], off
	global_store_dwordx4 v[82:83], v[70:73], off offset:256
	global_store_dwordx4 v[66:67], v[62:65], off
	global_store_dwordx4 v[66:67], v[54:57], off offset:256
	global_store_dwordx4 v[50:51], v[46:49], off
	global_store_dwordx4 v[50:51], v[38:41], off offset:256
	global_store_dwordx4 v[34:35], v[30:33], off
	global_store_dwordx4 v[34:35], v[22:25], off offset:256
	global_store_dwordx4 v[18:19], v[14:17], off
	global_store_dwordx4 v[18:19], v[6:9], off offset:256
	s_cbranch_vccnz .LBB0_544
	s_andn2_b64 vcc, exec, s[8:9]
	s_cbranch_vccnz .LBB0_543
	s_barrier
	s_branch .LBB0_543

; __device__ __forceinline__ void nt_store16(void* p, const uint4 v) { __builtin_nontemporal_store((u32x4){v.x, v.y, v.z, v.w}, (u32x4*)p); }
; __device__ __forceinline__ uint4 pack_acc8(const f32x4 a, const f32x4 b, float s) { uint4 w; w.x = cvt_pk_bf16(a[0] * s, a[1] * s); w.y = cvt_pk_bf16(a[2] * s, a[3] * s); w.z = cvt_pk_bf16(b[0] * s, b[1] * s); w.w = cvt_pk_bf16(b[2] * s, b[3] * s); return w; }
;     __device__ __forceinline__ void operator()(AccT acc, const Unit& u, int wr, int wc, int fr, int fq) const {
;         const int row0 = u.pm * BM + wr * 64 + fr, col0 = u.pn * BM + wc * 32 + 8 * fq;
; #pragma unroll
;         for (int ai = 0; ai < 2; ++ai)
; #pragma unroll
;             for (int m = 0; m < 4; ++m) { const int row = row0 + ai * HALF + m * 16;
; #pragma unroll
;                 for (int bj = 0; bj < 2; ++bj) { const int c = col0 + bj * HALF; const int b = c >> 11, s = c & 2047;
;                     nt_store16(FT + ((size_t)((b * 2 + (row & 1)) * 512 + (row >> 1)) * SEQ_ + s), pack_acc8(acc[ai][bj][m][0], acc[ai][bj][m][1], 1.0f)); } }
;     }
.LBB0_594:
	s_lshl_b32 s22, s62, 8
	s_and_b32 s22, s22, 0x700
	v_or_b32_e32 v0, s22, v163
	s_lshr_b32 s22, s62, 2
	s_and_b32 s22, s22, 0x7ffffe
	v_lshl_add_u32 v165, s59, 8, v160
	v_or_b32_e32 v138, s22, v162
	v_lshlrev_b32_e32 v178, 9, v138
	v_ashrrev_i32_e32 v138, 1, v165
	v_cvt_pk_bf16_f32 v70, v70, v71
	v_cvt_pk_bf16_f32 v71, v72, v73
	v_cvt_pk_bf16_f32 v72, v66, v67
	v_add_u32_e32 v66, 0x80, v165
	v_cvt_pk_bf16_f32 v54, v54, v55
	v_cvt_pk_bf16_f32 v55, v56, v57
	v_cvt_pk_bf16_f32 v56, v50, v51
	v_add_u32_e32 v50, 0x90, v165
	v_cvt_pk_bf16_f32 v38, v38, v39
	v_cvt_pk_bf16_f32 v39, v40, v41
	v_cvt_pk_bf16_f32 v40, v34, v35
	v_add_u32_e32 v34, 0xa0, v165
	v_cvt_pk_bf16_f32 v22, v22, v23
	v_cvt_pk_bf16_f32 v23, v24, v25
	v_cvt_pk_bf16_f32 v24, v18, v19
	v_add_u32_e32 v18, 0xb0, v165
	v_add_u32_e32 v138, v138, v178
	v_ashrrev_i32_e32 v66, 1, v66
	v_ashrrev_i32_e32 v50, 1, v50
	v_ashrrev_i32_e32 v34, 1, v34
	v_ashrrev_i32_e32 v18, 1, v18
	v_cvt_pk_bf16_f32 v118, v118, v119
	v_cvt_pk_bf16_f32 v119, v120, v121
	v_cvt_pk_bf16_f32 v120, v114, v115
	v_add_u32_e32 v114, 8, v138
	v_cvt_pk_bf16_f32 v102, v102, v103
	v_cvt_pk_bf16_f32 v103, v104, v105
	v_cvt_pk_bf16_f32 v104, v98, v99
	v_add_u32_e32 v98, 16, v138
	v_cvt_pk_bf16_f32 v86, v86, v87
	v_cvt_pk_bf16_f32 v87, v88, v89
	v_cvt_pk_bf16_f32 v88, v82, v83
	v_add_u32_e32 v82, 24, v138
	v_add_u32_e32 v66, v66, v178
	v_add_u32_e32 v50, v50, v178
	v_add_u32_e32 v34, v34, v178
	v_add_u32_e32 v18, v18, v178
	v_ashrrev_i32_e32 v139, 31, v138
	v_ashrrev_i32_e32 v115, 31, v114
	v_ashrrev_i32_e32 v99, 31, v98
	v_ashrrev_i32_e32 v83, 31, v82
	v_ashrrev_i32_e32 v67, 31, v66
	v_ashrrev_i32_e32 v51, 31, v50
	v_ashrrev_i32_e32 v35, 31, v34
	v_ashrrev_i32_e32 v19, 31, v18
	v_lshlrev_b64 v[166:167], 12, v[138:139]
	v_lshlrev_b64 v[114:115], 12, v[114:115]
	v_lshlrev_b64 v[98:99], 12, v[98:99]
	v_lshlrev_b64 v[82:83], 12, v[82:83]
	v_lshlrev_b64 v[66:67], 12, v[66:67]
	v_lshlrev_b64 v[50:51], 12, v[50:51]
	v_lshlrev_b64 v[34:35], 12, v[34:35]
	v_lshlrev_b64 v[18:19], 12, v[18:19]
	v_lshl_add_u64 v[166:167], s[6:7], 0, v[166:167]
	v_lshlrev_b32_e32 v0, 1, v0
	v_lshl_add_u64 v[114:115], s[6:7], 0, v[114:115]
	v_lshl_add_u64 v[98:99], s[6:7], 0, v[98:99]
	v_lshl_add_u64 v[82:83], s[6:7], 0, v[82:83]
	v_lshl_add_u64 v[66:67], s[6:7], 0, v[66:67]
	v_lshl_add_u64 v[50:51], s[6:7], 0, v[50:51]
	v_lshl_add_u64 v[34:35], s[6:7], 0, v[34:35]
	v_lshl_add_u64 v[18:19], s[6:7], 0, v[18:19]
	v_lshl_add_u64 v[166:167], v[166:167], 0, v[0:1]
	v_cvt_pk_bf16_f32 v122, v122, v123
	v_cvt_pk_bf16_f32 v123, v124, v125
	v_cvt_pk_bf16_f32 v124, v126, v127
	v_cvt_pk_bf16_f32 v125, v128, v129
	v_cvt_pk_bf16_f32 v121, v116, v117
	v_lshl_add_u64 v[114:115], v[114:115], 0, v[0:1]
	v_cvt_pk_bf16_f32 v110, v110, v111
	v_cvt_pk_bf16_f32 v111, v112, v113
	v_cvt_pk_bf16_f32 v112, v106, v107
	v_cvt_pk_bf16_f32 v113, v108, v109
	v_cvt_pk_bf16_f32 v105, v100, v101
	v_lshl_add_u64 v[98:99], v[98:99], 0, v[0:1]
	v_cvt_pk_bf16_f32 v94, v94, v95
	v_cvt_pk_bf16_f32 v95, v96, v97
	v_cvt_pk_bf16_f32 v96, v90, v91
	v_cvt_pk_bf16_f32 v97, v92, v93
	v_cvt_pk_bf16_f32 v89, v84, v85
	v_lshl_add_u64 v[82:83], v[82:83], 0, v[0:1]
	v_cvt_pk_bf16_f32 v78, v78, v79
	v_cvt_pk_bf16_f32 v79, v80, v81
	v_cvt_pk_bf16_f32 v80, v74, v75
	v_cvt_pk_bf16_f32 v81, v76, v77
	v_cvt_pk_bf16_f32 v73, v68, v69
	v_lshl_add_u64 v[66:67], v[66:67], 0, v[0:1]
	v_cvt_pk_bf16_f32 v62, v62, v63
	v_cvt_pk_bf16_f32 v63, v64, v65
	v_cvt_pk_bf16_f32 v64, v58, v59
	v_cvt_pk_bf16_f32 v65, v60, v61
	v_cvt_pk_bf16_f32 v57, v52, v53
	v_lshl_add_u64 v[50:51], v[50:51], 0, v[0:1]
	v_cvt_pk_bf16_f32 v46, v46, v47
	v_cvt_pk_bf16_f32 v47, v48, v49
	v_cvt_pk_bf16_f32 v48, v42, v43
	v_cvt_pk_bf16_f32 v49, v44, v45
	v_cvt_pk_bf16_f32 v41, v36, v37
	v_lshl_add_u64 v[34:35], v[34:35], 0, v[0:1]
	v_cvt_pk_bf16_f32 v30, v30, v31
	v_cvt_pk_bf16_f32 v31, v32, v33
	v_cvt_pk_bf16_f32 v32, v26, v27
	v_cvt_pk_bf16_f32 v33, v28, v29
	v_cvt_pk_bf16_f32 v25, v20, v21
	v_lshl_add_u64 v[18:19], v[18:19], 0, v[0:1]
	v_cvt_pk_bf16_f32 v14, v14, v15
	v_cvt_pk_bf16_f32 v15, v16, v17
	v_cvt_pk_bf16_f32 v16, v10, v11
	v_cvt_pk_bf16_f32 v17, v12, v13
	v_cvt_pk_bf16_f32 v6, v6, v7
	v_cvt_pk_bf16_f32 v7, v8, v9
	v_cvt_pk_bf16_f32 v8, v2, v3
	v_cvt_pk_bf16_f32 v9, v4, v5
	s_and_b64 vcc, exec, s[2:3]
	s_mov_b64 s[2:3], -1
	global_store_dwordx4 v[166:167], v[122:125], off
	global_store_dwordx4 v[166:167], v[118:121], off offset:256
	global_store_dwordx4 v[114:115], v[110:113], off
	global_store_dwordx4 v[114:115], v[102:105], off offset:256
	global_store_dwordx4 v[98:99], v[94:97], off
	global_store_dwordx4 v[98:99], v[86:89], off offset:256
	global_store_dwordx4 v[82:83], v[78:81], off
	global_store_dwordx4 v[82:83], v[70:73], off offset:256
	global_store_dwordx4 v[66:67], v[62:65], off
	global_store_dwordx4 v[66:67], v[54:57], off offset:256
	global_store_dwordx4 v[50:51], v[46:49], off
	global_store_dwordx4 v[50:51], v[38:41], off offset:256
	global_store_dwordx4 v[34:35], v[30:33], off
	global_store_dwordx4 v[34:35], v[22:25], off offset:256
	global_store_dwordx4 v[18:19], v[14:17], off
	global_store_dwordx4 v[18:19], v[6:9], off offset:256
	s_cbranch_vccnz .LBB0_576
	s_andn2_b64 vcc, exec, s[12:13]
	s_cbranch_vccnz .LBB0_575
	s_barrier
	s_branch .LBB0_575

;     __device__ __forceinline__ void operator()(AccT acc, const Unit& u, int wr, int wc, int fr, int fq) const {
;         const int row0 = u.pm * BM + wr * 64 + fr, col0 = u.pn * BM + wc * 32 + 4 * fq;
; #pragma unroll
;         for (int ai = 0; ai < 2; ++ai)
; #pragma unroll
;             for (int m = 0; m < 4; ++m) { const size_t off = (size_t)(row0 + ai * HALF + m * 16) * D_ + col0;
; #pragma unroll
;                 for (int bj = 0; bj < 2; ++bj)
; #pragma unroll
;                     for (int n = 0; n < 2; ++n) { const f32x4 bs = *(const f32x4*)(xin + off + bj * HALF + n * 16); *(f32x4*)(xout + off + bj * HALF + n * 16) = bs + acc[ai][bj][m][n] * scale; }
;                 asm volatile("" ::: "memory"); }
.LBB0_634:
	v_lshl_add_u32 v26, s58, 8, v166
	v_lshl_or_b32 v20, s59, 8, v179
	v_ashrrev_i32_e32 v27, 31, v26
	v_ashrrev_i32_e32 v21, 31, v20
	v_lshlrev_b64 v[18:19], 10, v[26:27]
	v_lshl_add_u64 v[18:19], v[18:19], 0, v[20:21]
	v_readlane_b32 s20, v254, 29
	v_lshlrev_b64 v[18:19], 2, v[18:19]
	v_readlane_b32 s21, v254, 30
	s_mov_b64 s[18:19], 0x80000
	s_and_b64 vcc, exec, s[2:3]
	v_lshl_add_u64 v[28:29], s[20:21], 0, v[18:19]
	global_load_dwordx4 v[42:45], v[28:29], off
	s_waitcnt vmcnt(0) lgkmcnt(0)
	v_pk_add_f32 v[44:45], v[162:163], v[44:45]
	v_pk_add_f32 v[42:43], v[164:165], v[42:43]
	v_lshl_add_u64 v[162:163], s[78:79], 0, v[18:19]
	global_store_dwordx4 v[162:163], v[42:45], off
	global_load_dwordx4 v[42:45], v[28:29], off offset:64
	s_waitcnt vmcnt(0) lgkmcnt(0)
	v_pk_add_f32 v[44:45], v[128:129], v[44:45]
	v_pk_add_f32 v[42:43], v[126:127], v[42:43]
	global_store_dwordx4 v[162:163], v[42:45], off offset:64
	global_load_dwordx4 v[42:45], v[28:29], off offset:512
	s_waitcnt vmcnt(0) lgkmcnt(0)
	v_pk_add_f32 v[44:45], v[160:161], v[44:45]
	v_pk_add_f32 v[42:43], v[158:159], v[42:43]
	global_store_dwordx4 v[162:163], v[42:45], off offset:512
	global_load_dwordx4 v[42:45], v[28:29], off offset:576
	v_or_b32_e32 v28, 16, v26
	v_ashrrev_i32_e32 v29, 31, v28
	v_lshlrev_b64 v[28:29], 10, v[28:29]
	v_lshl_add_u64 v[28:29], v[28:29], 0, v[20:21]
	v_lshlrev_b64 v[28:29], 2, v[28:29]
	v_lshl_add_u64 v[126:127], s[20:21], 0, v[28:29]
	v_lshl_add_u64 v[28:29], s[78:79], 0, v[28:29]
	s_waitcnt vmcnt(0) lgkmcnt(0)
	v_pk_add_f32 v[44:45], v[154:155], v[44:45]
	v_pk_add_f32 v[42:43], v[156:157], v[42:43]
	global_store_dwordx4 v[162:163], v[42:45], off offset:576
	global_load_dwordx4 v[42:45], v[126:127], off
	s_waitcnt vmcnt(0) lgkmcnt(0)
	v_pk_add_f32 v[44:45], v[122:123], v[44:45]
	v_pk_add_f32 v[42:43], v[124:125], v[42:43]
	global_store_dwordx4 v[28:29], v[42:45], off
	global_load_dwordx4 v[42:45], v[126:127], off offset:64
	s_waitcnt vmcnt(0) lgkmcnt(0)
	v_pk_add_f32 v[44:45], v[112:113], v[44:45]
	v_pk_add_f32 v[42:43], v[110:111], v[42:43]
	global_store_dwordx4 v[28:29], v[42:45], off offset:64
	global_load_dwordx4 v[42:45], v[126:127], off offset:512
	s_waitcnt vmcnt(0) lgkmcnt(0)
	v_pk_add_f32 v[44:45], v[120:121], v[44:45]
	v_pk_add_f32 v[42:43], v[118:119], v[42:43]
	global_store_dwordx4 v[28:29], v[42:45], off offset:512
	global_load_dwordx4 v[42:45], v[126:127], off offset:576
	s_waitcnt vmcnt(0) lgkmcnt(0)
	v_pk_add_f32 v[44:45], v[114:115], v[44:45]
	v_pk_add_f32 v[42:43], v[116:117], v[42:43]
	global_store_dwordx4 v[28:29], v[42:45], off offset:576
	v_or_b32_e32 v28, 32, v26
	v_ashrrev_i32_e32 v29, 31, v28
	v_lshlrev_b64 v[28:29], 10, v[28:29]
	v_lshl_add_u64 v[28:29], v[28:29], 0, v[20:21]
	v_lshlrev_b64 v[28:29], 2, v[28:29]
	v_lshl_add_u64 v[110:111], s[20:21], 0, v[28:29]
	global_load_dwordx4 v[42:45], v[110:111], off
	v_lshl_add_u64 v[28:29], s[78:79], 0, v[28:29]
	v_or_b32_e32 v26, 48, v26
	v_ashrrev_i32_e32 v27, 31, v26
	v_lshlrev_b64 v[26:27], 10, v[26:27]
	v_lshl_add_u64 v[20:21], v[26:27], 0, v[20:21]
	v_lshlrev_b64 v[20:21], 2, v[20:21]
	s_waitcnt vmcnt(0) lgkmcnt(0)
	v_pk_add_f32 v[44:45], v[108:109], v[44:45]
	v_pk_add_f32 v[42:43], v[106:107], v[42:43]
	global_store_dwordx4 v[28:29], v[42:45], off
	global_load_dwordx4 v[42:45], v[110:111], off offset:64
	s_waitcnt vmcnt(0) lgkmcnt(0)
	v_pk_add_f32 v[44:45], v[96:97], v[44:45]
	v_pk_add_f32 v[42:43], v[94:95], v[42:43]
	global_store_dwordx4 v[28:29], v[42:45], off offset:64
	global_load_dwordx4 v[42:45], v[110:111], off offset:512
	s_waitcnt vmcnt(0) lgkmcnt(0)
	v_pk_add_f32 v[44:45], v[104:105], v[44:45]
	v_pk_add_f32 v[42:43], v[102:103], v[42:43]
	global_store_dwordx4 v[28:29], v[42:45], off offset:512
	global_load_dwordx4 v[42:45], v[110:111], off offset:576
	s_waitcnt vmcnt(0) lgkmcnt(0)
	v_pk_add_f32 v[44:45], v[98:99], v[44:45]
	v_pk_add_f32 v[42:43], v[100:101], v[42:43]
	global_store_dwordx4 v[28:29], v[42:45], off offset:576
	s_nop 1
	v_lshl_add_u64 v[42:43], s[20:21], 0, v[20:21]
	global_load_dwordx4 v[26:29], v[42:43], off
	v_lshl_add_u64 v[20:21], s[78:79], 0, v[20:21]
	s_waitcnt vmcnt(0) lgkmcnt(0)
	v_pk_add_f32 v[28:29], v[92:93], v[28:29]
	v_pk_add_f32 v[26:27], v[90:91], v[26:27]
	global_store_dwordx4 v[20:21], v[26:29], off
	global_load_dwordx4 v[26:29], v[42:43], off offset:64
	s_waitcnt vmcnt(0) lgkmcnt(0)
	v_pk_add_f32 v[28:29], v[80:81], v[28:29]
	v_pk_add_f32 v[26:27], v[78:79], v[26:27]
	global_store_dwordx4 v[20:21], v[26:29], off offset:64
	global_load_dwordx4 v[26:29], v[42:43], off offset:512
	s_waitcnt vmcnt(0) lgkmcnt(0)
;     __device__ __forceinline__ void operator()(AccT acc, const Unit& u, int wr, int wc, int fr, int fq) const {
;     ...
;             for (int m = 0; m < 4; ++m) { const size_t off = (size_t)(row0 + ai * HALF + m * 16) * D_ + col0;
; #pragma unroll
;                 for (int bj = 0; bj < 2; ++bj)
; #pragma unroll
;                     for (int n = 0; n < 2; ++n) { const f32x4 bs = *(const f32x4*)(xin + off + bj * HALF + n * 16); *(f32x4*)(xout + off + bj * HALF + n * 16) = bs + acc[ai][bj][m][n] * scale; }
;                 asm volatile("" ::: "memory"); }
	v_pk_add_f32 v[28:29], v[88:89], v[28:29]
	v_pk_add_f32 v[26:27], v[86:87], v[26:27]
	global_store_dwordx4 v[20:21], v[26:29], off offset:512
	global_load_dwordx4 v[26:29], v[42:43], off offset:576
	s_waitcnt vmcnt(0) lgkmcnt(0)
	v_pk_add_f32 v[28:29], v[82:83], v[28:29]
	v_pk_add_f32 v[26:27], v[84:85], v[26:27]
	global_store_dwordx4 v[20:21], v[26:29], off offset:576
	v_lshl_add_u64 v[20:21], v[18:19], 0, s[18:19]
	v_lshl_add_u64 v[42:43], s[20:21], 0, v[20:21]
	global_load_dwordx4 v[26:29], v[42:43], off
	v_lshl_add_u64 v[20:21], s[78:79], 0, v[20:21]
	s_mov_b64 s[18:19], 0x90000
	s_waitcnt vmcnt(0) lgkmcnt(0)
	v_pk_add_f32 v[28:29], v[74:75], v[28:29]
	v_pk_add_f32 v[26:27], v[76:77], v[26:27]
	global_store_dwordx4 v[20:21], v[26:29], off
	global_load_dwordx4 v[26:29], v[42:43], off offset:64
	s_waitcnt vmcnt(0) lgkmcnt(0)
	v_pk_add_f32 v[28:29], v[64:65], v[28:29]
	v_pk_add_f32 v[26:27], v[62:63], v[26:27]
	global_store_dwordx4 v[20:21], v[26:29], off offset:64
	global_load_dwordx4 v[26:29], v[42:43], off offset:512
	s_waitcnt vmcnt(0) lgkmcnt(0)
	v_pk_add_f32 v[28:29], v[72:73], v[28:29]
	v_pk_add_f32 v[26:27], v[70:71], v[26:27]
	global_store_dwordx4 v[20:21], v[26:29], off offset:512
	global_load_dwordx4 v[26:29], v[42:43], off offset:576
	s_waitcnt vmcnt(0) lgkmcnt(0)
	v_pk_add_f32 v[28:29], v[66:67], v[28:29]
	v_pk_add_f32 v[26:27], v[68:69], v[26:27]
	global_store_dwordx4 v[20:21], v[26:29], off offset:576
	v_lshl_add_u64 v[20:21], v[18:19], 0, s[18:19]
	v_lshl_add_u64 v[42:43], s[20:21], 0, v[20:21]
	global_load_dwordx4 v[26:29], v[42:43], off
	v_lshl_add_u64 v[20:21], s[78:79], 0, v[20:21]
	s_mov_b64 s[18:19], 0xa0000
	s_waitcnt vmcnt(0) lgkmcnt(0)
	v_pk_add_f32 v[28:29], v[58:59], v[28:29]
	v_pk_add_f32 v[26:27], v[60:61], v[26:27]
	global_store_dwordx4 v[20:21], v[26:29], off
	global_load_dwordx4 v[26:29], v[42:43], off offset:64
	s_waitcnt vmcnt(0) lgkmcnt(0)
	v_pk_add_f32 v[28:29], v[48:49], v[28:29]
	v_pk_add_f32 v[26:27], v[46:47], v[26:27]
	global_store_dwordx4 v[20:21], v[26:29], off offset:64
	global_load_dwordx4 v[26:29], v[42:43], off offset:512
	s_waitcnt vmcnt(0) lgkmcnt(0)
	v_pk_add_f32 v[28:29], v[56:57], v[28:29]
	v_pk_add_f32 v[26:27], v[54:55], v[26:27]
	global_store_dwordx4 v[20:21], v[26:29], off offset:512
	global_load_dwordx4 v[26:29], v[42:43], off offset:576
	s_waitcnt vmcnt(0) lgkmcnt(0)
	v_pk_add_f32 v[28:29], v[50:51], v[28:29]
	v_pk_add_f32 v[26:27], v[52:53], v[26:27]
	global_store_dwordx4 v[20:21], v[26:29], off offset:576
	v_lshl_add_u64 v[20:21], v[18:19], 0, s[18:19]
	v_lshl_add_u64 v[42:43], s[20:21], 0, v[20:21]
	global_load_dwordx4 v[26:29], v[42:43], off
	s_mov_b64 s[18:19], 0xb0000
	s_waitcnt vmcnt(0) lgkmcnt(0)
	v_pk_add_f32 v[28:29], v[38:39], v[28:29]
	v_pk_add_f32 v[26:27], v[40:41], v[26:27]
	v_lshl_add_u64 v[38:39], s[78:79], 0, v[20:21]
	global_store_dwordx4 v[38:39], v[26:29], off
	global_load_dwordx4 v[26:29], v[42:43], off offset:64
	s_waitcnt vmcnt(0) lgkmcnt(0)
	v_pk_add_f32 v[24:25], v[24:25], v[28:29]
	v_pk_add_f32 v[22:23], v[22:23], v[26:27]
	global_store_dwordx4 v[38:39], v[22:25], off offset:64
	global_load_dwordx4 v[20:23], v[42:43], off offset:512
	s_waitcnt vmcnt(0) lgkmcnt(0)
	v_pk_add_f32 v[20:21], v[34:35], v[20:21]
	v_pk_add_f32 v[22:23], v[36:37], v[22:23]
	global_store_dwordx4 v[38:39], v[20:23], off offset:512
	global_load_dwordx4 v[20:23], v[42:43], off offset:576
	s_waitcnt vmcnt(0) lgkmcnt(0)
	v_pk_add_f32 v[22:23], v[30:31], v[22:23]
	v_pk_add_f32 v[20:21], v[32:33], v[20:21]
	global_store_dwordx4 v[38:39], v[20:23], off offset:576
	s_nop 1
	v_lshl_add_u64 v[22:23], v[18:19], 0, s[18:19]
	v_lshl_add_u64 v[24:25], s[20:21], 0, v[22:23]
	global_load_dwordx4 v[18:21], v[24:25], off
	v_lshl_add_u64 v[22:23], s[78:79], 0, v[22:23]
	s_mov_b64 s[18:19], -1
	s_waitcnt vmcnt(0) lgkmcnt(0)
	v_pk_add_f32 v[20:21], v[14:15], v[20:21]
	v_pk_add_f32 v[18:19], v[16:17], v[18:19]
	global_store_dwordx4 v[22:23], v[18:21], off
	global_load_dwordx4 v[14:17], v[24:25], off offset:64
	s_waitcnt vmcnt(0) lgkmcnt(0)
	v_pk_add_f32 v[12:13], v[12:13], v[16:17]
	v_pk_add_f32 v[10:11], v[10:11], v[14:15]
	global_store_dwordx4 v[22:23], v[10:13], off offset:64
	global_load_dwordx4 v[10:13], v[24:25], off offset:512
	s_waitcnt vmcnt(0) lgkmcnt(0)
	v_pk_add_f32 v[8:9], v[8:9], v[12:13]
	v_pk_add_f32 v[6:7], v[6:7], v[10:11]
	global_store_dwordx4 v[22:23], v[6:9], off offset:512
	global_load_dwordx4 v[6:9], v[24:25], off offset:576
	s_waitcnt vmcnt(0) lgkmcnt(0)
	v_pk_add_f32 v[4:5], v[4:5], v[8:9]
	v_pk_add_f32 v[2:3], v[2:3], v[6:7]
	global_store_dwordx4 v[22:23], v[2:5], off offset:576
	s_cbranch_vccnz .LBB0_617
	s_andn2_b64 vcc, exec, s[10:11]
	s_cbranch_vccnz .LBB0_616
	s_barrier
	s_branch .LBB0_616

; __device__ __forceinline__ float sigmoid_(float x) { return __builtin_amdgcn_rcpf(1.0f + __expf(-x)); }
; __device__ __forceinline__ uint4 pack8(const float (&f)[8]) { uint4 r; r.x = cvt_pk_bf16(f[0], f[1]); r.y = cvt_pk_bf16(f[2], f[3]); r.z = cvt_pk_bf16(f[4], f[5]); r.w = cvt_pk_bf16(f[6], f[7]); return r; }
; __device__ __forceinline__ void nt_store16(void* p, const uint4 v) { __builtin_nontemporal_store((u32x4){v.x, v.y, v.z, v.w}, (u32x4*)p); }
;     __device__ __forceinline__ void operator()(AccT acc, const Unit& u, int wr, int wc, int fr, int fq) const {
;         const int row0 = u.pm * BM + wr * 64 + fr, col0 = u.pn * 128 + wc * 32 + 8 * fq;
; #pragma unroll
;         for (int ai = 0; ai < 2; ++ai)
; #pragma unroll
;             for (int m = 0; m < 4; ++m) {
;                 bf16_t* rowp = O + (size_t)(row0 + ai * HALF + m * 16) * FF_ + col0;
;                 float o[8];
; #pragma unroll
;                 for (int n = 0; n < 2; ++n)
; #pragma unroll
;                     for (int j = 0; j < 4; ++j) { const float gt = acc[ai][0][m][n][j], up = acc[ai][1][m][n][j]; o[n * 4 + j] = gt * sigmoid_(gt) * up; }
;                 nt_store16(rowp, pack8(o));
;             }
.LBB0_657:
	v_mul_f32_e32 v138, 0xbfb8aa3b, v126
	v_exp_f32_e32 v138, v138
	v_mul_f32_e32 v139, 0xbfb8aa3b, v127
	v_exp_f32_e32 v139, v139
	v_readlane_b32 s18, v254, 35
	v_add_f32_e32 v138, 1.0, v138
	v_rcp_f32_e32 v180, v138
	v_add_f32_e32 v138, 1.0, v139
	v_rcp_f32_e32 v181, v138
	v_mul_f32_e32 v138, 0xbfb8aa3b, v128
	v_mul_f32_e32 v139, 0xbfb8aa3b, v129
	v_exp_f32_e32 v138, v138
	v_exp_f32_e32 v139, v139
	v_pk_mul_f32 v[126:127], v[126:127], v[180:181]
	v_lshl_or_b32 v166, s59, 7, v162
	v_pk_mul_f32 v[122:123], v[122:123], v[126:127]
	v_add_f32_e32 v126, 1.0, v138
	v_add_f32_e32 v127, 1.0, v139
	v_mul_f32_e32 v138, 0xbfb8aa3b, v118
	v_rcp_f32_e32 v126, v126
	v_rcp_f32_e32 v127, v127
	v_exp_f32_e32 v138, v138
	v_mul_f32_e32 v139, 0xbfb8aa3b, v119
	v_exp_f32_e32 v139, v139
	v_pk_mul_f32 v[126:127], v[128:129], v[126:127]
	v_add_f32_e32 v128, 1.0, v138
	v_mul_f32_e32 v138, 0xbfb8aa3b, v120
	v_add_f32_e32 v129, 1.0, v139
	v_exp_f32_e32 v138, v138
	v_mul_f32_e32 v139, 0xbfb8aa3b, v121
	v_exp_f32_e32 v139, v139
	v_rcp_f32_e32 v128, v128
	v_add_f32_e32 v138, 1.0, v138
	v_rcp_f32_e32 v129, v129
	v_rcp_f32_e32 v180, v138
	v_add_f32_e32 v138, 1.0, v139
	v_rcp_f32_e32 v181, v138
	v_pk_mul_f32 v[118:119], v[118:119], v[128:129]
	v_readlane_b32 s19, v254, 36
	v_pk_mul_f32 v[118:119], v[114:115], v[118:119]
	v_pk_mul_f32 v[114:115], v[120:121], v[180:181]
	v_cvt_pk_bf16_f32 v118, v118, v119
	v_pk_mul_f32 v[120:121], v[116:117], v[114:115]
	v_lshl_add_u32 v164, s58, 8, v160
	v_cvt_pk_bf16_f32 v119, v120, v121
	v_mul_f32_e32 v120, 0xbfb8aa3b, v110
	v_mul_f32_e32 v121, 0xbfb8aa3b, v111
	v_exp_f32_e32 v120, v120
	v_exp_f32_e32 v121, v121
	v_ashrrev_i32_e32 v167, 31, v166
	v_mov_b64_e32 v[158:159], s[18:19]
	v_mad_i64_i32 v[182:183], s[18:19], v164, s67, v[158:159]
	v_pk_mul_f32 v[124:125], v[124:125], v[126:127]
	v_lshlrev_b64 v[114:115], 1, v[166:167]
	v_lshl_add_u64 v[126:127], v[182:183], 0, v[114:115]
	v_cvt_pk_bf16_f32 v116, v122, v123
	v_cvt_pk_bf16_f32 v117, v124, v125
	global_store_dwordx4 v[126:127], v[116:119], off
	s_and_b64 vcc, exec, s[2:3]
	s_mov_b64 s[2:3], -1
	v_add_f32_e32 v116, 1.0, v120
	v_add_f32_e32 v117, 1.0, v121
	v_rcp_f32_e32 v116, v116
	v_rcp_f32_e32 v117, v117
	v_or_b32_e32 v118, 16, v164
	v_mad_i64_i32 v[118:119], s[18:19], v118, s67, v[158:159]
	v_pk_mul_f32 v[110:111], v[110:111], v[116:117]
	v_mul_f32_e32 v116, 0xbfb8aa3b, v112
	v_mul_f32_e32 v117, 0xbfb8aa3b, v113
	v_exp_f32_e32 v116, v116
	v_exp_f32_e32 v117, v117
	v_pk_mul_f32 v[106:107], v[106:107], v[110:111]
	v_add_f32_e32 v110, 1.0, v116
	v_add_f32_e32 v111, 1.0, v117
	v_mul_f32_e32 v116, 0xbfb8aa3b, v102
	v_mul_f32_e32 v117, 0xbfb8aa3b, v103
	v_rcp_f32_e32 v110, v110
	v_rcp_f32_e32 v111, v111
	v_exp_f32_e32 v116, v116
	v_exp_f32_e32 v117, v117
	v_pk_mul_f32 v[110:111], v[112:113], v[110:111]
	v_add_f32_e32 v112, 1.0, v116
	v_add_f32_e32 v113, 1.0, v117
	v_mul_f32_e32 v116, 0xbfb8aa3b, v104
	v_mul_f32_e32 v117, 0xbfb8aa3b, v105
	v_exp_f32_e32 v116, v116
	v_exp_f32_e32 v117, v117
	v_rcp_f32_e32 v112, v112
	v_rcp_f32_e32 v113, v113
	v_add_f32_e32 v116, 1.0, v116
	v_add_f32_e32 v117, 1.0, v117
	v_rcp_f32_e32 v116, v116
	v_rcp_f32_e32 v117, v117
	v_pk_mul_f32 v[102:103], v[102:103], v[112:113]
	v_pk_mul_f32 v[108:109], v[108:109], v[110:111]
	v_pk_mul_f32 v[102:103], v[98:99], v[102:103]
	v_pk_mul_f32 v[98:99], v[104:105], v[116:117]
	v_lshl_add_u64 v[110:111], v[118:119], 0, v[114:115]
	v_pk_mul_f32 v[104:105], v[100:101], v[98:99]
	v_cvt_pk_bf16_f32 v100, v102, v103
	v_mul_f32_e32 v102, 0xbfb8aa3b, v94
	v_mul_f32_e32 v103, 0xbfb8aa3b, v95
	v_exp_f32_e32 v102, v102
	v_exp_f32_e32 v103, v103
	v_cvt_pk_bf16_f32 v98, v106, v107
	v_cvt_pk_bf16_f32 v99, v108, v109
	v_cvt_pk_bf16_f32 v101, v104, v105
	global_store_dwordx4 v[110:111], v[98:101], off
	s_nop 1
	v_add_f32_e32 v98, 1.0, v102
	v_add_f32_e32 v99, 1.0, v103
	v_rcp_f32_e32 v98, v98
	v_rcp_f32_e32 v99, v99
	v_or_b32_e32 v100, 32, v164
	v_mad_i64_i32 v[100:101], s[18:19], v100, s67, v[158:159]
	v_pk_mul_f32 v[94:95], v[94:95], v[98:99]
	v_mul_f32_e32 v98, 0xbfb8aa3b, v96
	v_mul_f32_e32 v99, 0xbfb8aa3b, v97
	v_exp_f32_e32 v98, v98
	v_exp_f32_e32 v99, v99
	v_pk_mul_f32 v[90:91], v[90:91], v[94:95]
	v_add_f32_e32 v94, 1.0, v98
	v_add_f32_e32 v95, 1.0, v99
	v_mul_f32_e32 v98, 0xbfb8aa3b, v86
	v_mul_f32_e32 v99, 0xbfb8aa3b, v87
	v_rcp_f32_e32 v94, v94
	v_rcp_f32_e32 v95, v95
	v_exp_f32_e32 v98, v98
	v_exp_f32_e32 v99, v99
	v_pk_mul_f32 v[94:95], v[96:97], v[94:95]
	v_add_f32_e32 v96, 1.0, v98
	v_add_f32_e32 v97, 1.0, v99
	v_mul_f32_e32 v98, 0xbfb8aa3b, v88
	v_mul_f32_e32 v99, 0xbfb8aa3b, v89
	v_exp_f32_e32 v98, v98
	v_exp_f32_e32 v99, v99
	v_rcp_f32_e32 v96, v96
	v_rcp_f32_e32 v97, v97
	v_add_f32_e32 v98, 1.0, v98
	v_add_f32_e32 v99, 1.0, v99
	v_rcp_f32_e32 v98, v98
	v_rcp_f32_e32 v99, v99
	v_pk_mul_f32 v[86:87], v[86:87], v[96:97]
	v_pk_mul_f32 v[92:93], v[92:93], v[94:95]
	v_pk_mul_f32 v[86:87], v[82:83], v[86:87]
	v_pk_mul_f32 v[82:83], v[88:89], v[98:99]
	v_lshl_add_u64 v[94:95], v[100:101], 0, v[114:115]
	v_pk_mul_f32 v[88:89], v[84:85], v[82:83]
	v_cvt_pk_bf16_f32 v84, v86, v87
	v_mul_f32_e32 v86, 0xbfb8aa3b, v78
	v_mul_f32_e32 v87, 0xbfb8aa3b, v79
	v_exp_f32_e32 v86, v86
	v_exp_f32_e32 v87, v87
	v_cvt_pk_bf16_f32 v82, v90, v91
	v_cvt_pk_bf16_f32 v83, v92, v93
	v_cvt_pk_bf16_f32 v85, v88, v89
	global_store_dwordx4 v[94:95], v[82:85], off
	s_nop 1
	v_add_f32_e32 v82, 1.0, v86
	v_add_f32_e32 v83, 1.0, v87
	v_rcp_f32_e32 v82, v82
	v_rcp_f32_e32 v83, v83
	v_or_b32_e32 v84, 48, v164
	v_mad_i64_i32 v[84:85], s[18:19], v84, s67, v[158:159]
	v_pk_mul_f32 v[78:79], v[78:79], v[82:83]
	v_mul_f32_e32 v82, 0xbfb8aa3b, v80
; __device__ __forceinline__ float sigmoid_(float x) { return __builtin_amdgcn_rcpf(1.0f + __expf(-x)); }
; __device__ __forceinline__ uint4 pack8(const float (&f)[8]) { uint4 r; r.x = cvt_pk_bf16(f[0], f[1]); r.y = cvt_pk_bf16(f[2], f[3]); r.z = cvt_pk_bf16(f[4], f[5]); r.w = cvt_pk_bf16(f[6], f[7]); return r; }
; __device__ __forceinline__ void nt_store16(void* p, const uint4 v) { __builtin_nontemporal_store((u32x4){v.x, v.y, v.z, v.w}, (u32x4*)p); }
;     __device__ __forceinline__ void operator()(AccT acc, const Unit& u, int wr, int wc, int fr, int fq) const {
;     ...
;             for (int m = 0; m < 4; ++m) {
;                 bf16_t* rowp = O + (size_t)(row0 + ai * HALF + m * 16) * FF_ + col0;
;                 float o[8];
; #pragma unroll
;                 for (int n = 0; n < 2; ++n)
; #pragma unroll
;                     for (int j = 0; j < 4; ++j) { const float gt = acc[ai][0][m][n][j], up = acc[ai][1][m][n][j]; o[n * 4 + j] = gt * sigmoid_(gt) * up; }
;                 nt_store16(rowp, pack8(o));
	v_mul_f32_e32 v83, 0xbfb8aa3b, v81
	v_exp_f32_e32 v82, v82
	v_exp_f32_e32 v83, v83
	v_pk_mul_f32 v[74:75], v[74:75], v[78:79]
	v_add_f32_e32 v78, 1.0, v82
	v_add_f32_e32 v79, 1.0, v83
	v_mul_f32_e32 v82, 0xbfb8aa3b, v70
	v_mul_f32_e32 v83, 0xbfb8aa3b, v71
	v_rcp_f32_e32 v78, v78
	v_rcp_f32_e32 v79, v79
	v_exp_f32_e32 v82, v82
	v_exp_f32_e32 v83, v83
	v_pk_mul_f32 v[78:79], v[80:81], v[78:79]
	v_add_f32_e32 v80, 1.0, v82
	v_add_f32_e32 v81, 1.0, v83
	v_mul_f32_e32 v82, 0xbfb8aa3b, v72
	v_mul_f32_e32 v83, 0xbfb8aa3b, v73
	v_exp_f32_e32 v82, v82
	v_exp_f32_e32 v83, v83
	v_rcp_f32_e32 v80, v80
	v_rcp_f32_e32 v81, v81
	v_add_f32_e32 v82, 1.0, v82
	v_add_f32_e32 v83, 1.0, v83
	v_rcp_f32_e32 v82, v82
	v_rcp_f32_e32 v83, v83
	v_pk_mul_f32 v[70:71], v[70:71], v[80:81]
	v_pk_mul_f32 v[76:77], v[76:77], v[78:79]
	v_pk_mul_f32 v[70:71], v[66:67], v[70:71]
	v_pk_mul_f32 v[66:67], v[72:73], v[82:83]
	v_lshl_add_u64 v[78:79], v[84:85], 0, v[114:115]
	v_pk_mul_f32 v[72:73], v[68:69], v[66:67]
	v_cvt_pk_bf16_f32 v68, v70, v71
	v_mul_f32_e32 v70, 0xbfb8aa3b, v62
	v_mul_f32_e32 v71, 0xbfb8aa3b, v63
	v_exp_f32_e32 v70, v70
	v_exp_f32_e32 v71, v71
	v_cvt_pk_bf16_f32 v66, v74, v75
	v_cvt_pk_bf16_f32 v67, v76, v77
	v_cvt_pk_bf16_f32 v69, v72, v73
	global_store_dwordx4 v[78:79], v[66:69], off
	s_nop 1
	v_add_f32_e32 v66, 1.0, v70
	v_add_f32_e32 v67, 1.0, v71
	v_rcp_f32_e32 v66, v66
	v_rcp_f32_e32 v67, v67
	v_add_u32_e32 v68, 0x80, v164
	v_mad_i64_i32 v[68:69], s[18:19], v68, s67, v[158:159]
	v_pk_mul_f32 v[62:63], v[62:63], v[66:67]
	v_mul_f32_e32 v66, 0xbfb8aa3b, v64
	v_mul_f32_e32 v67, 0xbfb8aa3b, v65
	v_exp_f32_e32 v66, v66
	v_exp_f32_e32 v67, v67
	v_pk_mul_f32 v[58:59], v[58:59], v[62:63]
	v_add_f32_e32 v62, 1.0, v66
	v_add_f32_e32 v63, 1.0, v67
	v_mul_f32_e32 v66, 0xbfb8aa3b, v54
	v_mul_f32_e32 v67, 0xbfb8aa3b, v55
	v_rcp_f32_e32 v62, v62
	v_rcp_f32_e32 v63, v63
	v_exp_f32_e32 v66, v66
	v_exp_f32_e32 v67, v67
	v_pk_mul_f32 v[62:63], v[64:65], v[62:63]
	v_add_f32_e32 v64, 1.0, v66
	v_add_f32_e32 v65, 1.0, v67
	v_mul_f32_e32 v66, 0xbfb8aa3b, v56
	v_mul_f32_e32 v67, 0xbfb8aa3b, v57
	v_exp_f32_e32 v66, v66
	v_exp_f32_e32 v67, v67
	v_rcp_f32_e32 v64, v64
	v_rcp_f32_e32 v65, v65
	v_add_f32_e32 v66, 1.0, v66
	v_add_f32_e32 v67, 1.0, v67
	v_rcp_f32_e32 v66, v66
	v_rcp_f32_e32 v67, v67
	v_pk_mul_f32 v[54:55], v[54:55], v[64:65]
	v_pk_mul_f32 v[60:61], v[60:61], v[62:63]
	v_pk_mul_f32 v[54:55], v[50:51], v[54:55]
	v_pk_mul_f32 v[50:51], v[56:57], v[66:67]
	v_lshl_add_u64 v[62:63], v[68:69], 0, v[114:115]
	v_pk_mul_f32 v[56:57], v[52:53], v[50:51]
	v_cvt_pk_bf16_f32 v52, v54, v55
	v_mul_f32_e32 v54, 0xbfb8aa3b, v46
	v_mul_f32_e32 v55, 0xbfb8aa3b, v47
	v_exp_f32_e32 v54, v54
	v_exp_f32_e32 v55, v55
	v_cvt_pk_bf16_f32 v50, v58, v59
	v_cvt_pk_bf16_f32 v51, v60, v61
	v_cvt_pk_bf16_f32 v53, v56, v57
	global_store_dwordx4 v[62:63], v[50:53], off
	s_nop 1
	v_add_f32_e32 v50, 1.0, v54
	v_add_f32_e32 v51, 1.0, v55
	v_rcp_f32_e32 v50, v50
	v_rcp_f32_e32 v51, v51
	v_add_u32_e32 v52, 0x90, v164
	v_mad_i64_i32 v[52:53], s[18:19], v52, s67, v[158:159]
	v_pk_mul_f32 v[46:47], v[46:47], v[50:51]
	v_mul_f32_e32 v50, 0xbfb8aa3b, v48
	v_mul_f32_e32 v51, 0xbfb8aa3b, v49
	v_exp_f32_e32 v50, v50
	v_exp_f32_e32 v51, v51
	v_pk_mul_f32 v[42:43], v[42:43], v[46:47]
	v_add_f32_e32 v46, 1.0, v50
	v_add_f32_e32 v47, 1.0, v51
	v_mul_f32_e32 v50, 0xbfb8aa3b, v38
	v_mul_f32_e32 v51, 0xbfb8aa3b, v39
	v_rcp_f32_e32 v46, v46
	v_rcp_f32_e32 v47, v47
	v_exp_f32_e32 v50, v50
	v_exp_f32_e32 v51, v51
	v_pk_mul_f32 v[46:47], v[48:49], v[46:47]
	v_add_f32_e32 v48, 1.0, v50
	v_add_f32_e32 v49, 1.0, v51
	v_mul_f32_e32 v50, 0xbfb8aa3b, v40
	v_mul_f32_e32 v51, 0xbfb8aa3b, v41
	v_exp_f32_e32 v50, v50
	v_exp_f32_e32 v51, v51
	v_rcp_f32_e32 v48, v48
	v_rcp_f32_e32 v49, v49
; __device__ __forceinline__ float sigmoid_(float x) { return __builtin_amdgcn_rcpf(1.0f + __expf(-x)); }
; __device__ __forceinline__ uint4 pack8(const float (&f)[8]) { uint4 r; r.x = cvt_pk_bf16(f[0], f[1]); r.y = cvt_pk_bf16(f[2], f[3]); r.z = cvt_pk_bf16(f[4], f[5]); r.w = cvt_pk_bf16(f[6], f[7]); return r; }
; __device__ __forceinline__ void nt_store16(void* p, const uint4 v) { __builtin_nontemporal_store((u32x4){v.x, v.y, v.z, v.w}, (u32x4*)p); }
;     __device__ __forceinline__ void operator()(AccT acc, const Unit& u, int wr, int wc, int fr, int fq) const {
;         const int row0 = u.pm * BM + wr * 64 + fr, col0 = u.pn * 128 + wc * 32 + 8 * fq;
; #pragma unroll
;         for (int ai = 0; ai < 2; ++ai)
; #pragma unroll
;             for (int m = 0; m < 4; ++m) {
;                 bf16_t* rowp = O + (size_t)(row0 + ai * HALF + m * 16) * FF_ + col0;
;                 float o[8];
; #pragma unroll
;                 for (int n = 0; n < 2; ++n)
; #pragma unroll
;                     for (int j = 0; j < 4; ++j) { const float gt = acc[ai][0][m][n][j], up = acc[ai][1][m][n][j]; o[n * 4 + j] = gt * sigmoid_(gt) * up; }
;                 nt_store16(rowp, pack8(o));
	v_add_f32_e32 v50, 1.0, v50
	v_add_f32_e32 v51, 1.0, v51
	v_rcp_f32_e32 v50, v50
	v_rcp_f32_e32 v51, v51
	v_pk_mul_f32 v[38:39], v[38:39], v[48:49]
	v_pk_mul_f32 v[44:45], v[44:45], v[46:47]
	v_pk_mul_f32 v[38:39], v[34:35], v[38:39]
	v_pk_mul_f32 v[34:35], v[40:41], v[50:51]
	v_lshl_add_u64 v[46:47], v[52:53], 0, v[114:115]
	v_pk_mul_f32 v[40:41], v[36:37], v[34:35]
	v_cvt_pk_bf16_f32 v36, v38, v39
	v_mul_f32_e32 v38, 0xbfb8aa3b, v30
	v_mul_f32_e32 v39, 0xbfb8aa3b, v31
	v_exp_f32_e32 v38, v38
	v_exp_f32_e32 v39, v39
	v_cvt_pk_bf16_f32 v34, v42, v43
	v_cvt_pk_bf16_f32 v35, v44, v45
	v_cvt_pk_bf16_f32 v37, v40, v41
	global_store_dwordx4 v[46:47], v[34:37], off
	s_nop 1
	v_add_f32_e32 v34, 1.0, v38
	v_add_f32_e32 v35, 1.0, v39
	v_rcp_f32_e32 v34, v34
	v_rcp_f32_e32 v35, v35
	v_add_u32_e32 v36, 0xa0, v164
	v_mad_i64_i32 v[36:37], s[18:19], v36, s67, v[158:159]
	v_pk_mul_f32 v[30:31], v[30:31], v[34:35]
	v_mul_f32_e32 v34, 0xbfb8aa3b, v32
	v_mul_f32_e32 v35, 0xbfb8aa3b, v33
	v_exp_f32_e32 v34, v34
	v_exp_f32_e32 v35, v35
	v_pk_mul_f32 v[26:27], v[26:27], v[30:31]
	v_add_f32_e32 v30, 1.0, v34
	v_add_f32_e32 v31, 1.0, v35
	v_mul_f32_e32 v34, 0xbfb8aa3b, v22
	v_mul_f32_e32 v35, 0xbfb8aa3b, v23
	v_rcp_f32_e32 v30, v30
	v_rcp_f32_e32 v31, v31
	v_exp_f32_e32 v34, v34
	v_exp_f32_e32 v35, v35
	v_pk_mul_f32 v[30:31], v[32:33], v[30:31]
	v_add_f32_e32 v32, 1.0, v34
	v_add_f32_e32 v33, 1.0, v35
	v_mul_f32_e32 v34, 0xbfb8aa3b, v24
	v_mul_f32_e32 v35, 0xbfb8aa3b, v25
	v_exp_f32_e32 v34, v34
	v_exp_f32_e32 v35, v35
	v_rcp_f32_e32 v32, v32
	v_rcp_f32_e32 v33, v33
	v_add_f32_e32 v34, 1.0, v34
	v_add_f32_e32 v35, 1.0, v35
	v_rcp_f32_e32 v34, v34
	v_rcp_f32_e32 v35, v35
	v_pk_mul_f32 v[22:23], v[22:23], v[32:33]
	v_pk_mul_f32 v[28:29], v[28:29], v[30:31]
	v_pk_mul_f32 v[22:23], v[18:19], v[22:23]
	v_pk_mul_f32 v[18:19], v[24:25], v[34:35]
	v_lshl_add_u64 v[30:31], v[36:37], 0, v[114:115]
	v_pk_mul_f32 v[24:25], v[20:21], v[18:19]
	v_cvt_pk_bf16_f32 v20, v22, v23
	v_mul_f32_e32 v22, 0xbfb8aa3b, v14
	v_mul_f32_e32 v23, 0xbfb8aa3b, v15
	v_exp_f32_e32 v22, v22
	v_exp_f32_e32 v23, v23
	v_cvt_pk_bf16_f32 v18, v26, v27
	v_cvt_pk_bf16_f32 v19, v28, v29
	v_cvt_pk_bf16_f32 v21, v24, v25
	global_store_dwordx4 v[30:31], v[18:21], off
	s_nop 1
	v_add_f32_e32 v18, 1.0, v22
	v_add_f32_e32 v19, 1.0, v23
	v_rcp_f32_e32 v18, v18
	v_rcp_f32_e32 v19, v19
	v_add_u32_e32 v20, 0xb0, v164
	v_mad_i64_i32 v[20:21], s[18:19], v20, s67, v[158:159]
	v_pk_mul_f32 v[14:15], v[14:15], v[18:19]
	v_mul_f32_e32 v18, 0xbfb8aa3b, v16
	v_mul_f32_e32 v19, 0xbfb8aa3b, v17
	v_exp_f32_e32 v18, v18
	v_exp_f32_e32 v19, v19
	v_pk_mul_f32 v[10:11], v[10:11], v[14:15]
	v_add_f32_e32 v14, 1.0, v18
	v_add_f32_e32 v15, 1.0, v19
	v_mul_f32_e32 v18, 0xbfb8aa3b, v6
	v_mul_f32_e32 v19, 0xbfb8aa3b, v7
	v_rcp_f32_e32 v14, v14
	v_rcp_f32_e32 v15, v15
	v_exp_f32_e32 v18, v18
	v_exp_f32_e32 v19, v19
	v_pk_mul_f32 v[14:15], v[16:17], v[14:15]
	v_add_f32_e32 v16, 1.0, v18
	v_add_f32_e32 v17, 1.0, v19
	v_mul_f32_e32 v18, 0xbfb8aa3b, v8
	v_mul_f32_e32 v19, 0xbfb8aa3b, v9
	v_exp_f32_e32 v18, v18
	v_exp_f32_e32 v19, v19
	v_rcp_f32_e32 v16, v16
	v_rcp_f32_e32 v17, v17
	v_add_f32_e32 v18, 1.0, v18
	v_add_f32_e32 v19, 1.0, v19
	v_rcp_f32_e32 v18, v18
	v_rcp_f32_e32 v19, v19
	v_pk_mul_f32 v[6:7], v[6:7], v[16:17]
	v_pk_mul_f32 v[12:13], v[12:13], v[14:15]
	v_pk_mul_f32 v[6:7], v[2:3], v[6:7]
	v_pk_mul_f32 v[2:3], v[8:9], v[18:19]
	v_lshl_add_u64 v[14:15], v[20:21], 0, v[114:115]
	v_pk_mul_f32 v[8:9], v[4:5], v[2:3]
	v_cvt_pk_bf16_f32 v2, v10, v11
	v_cvt_pk_bf16_f32 v3, v12, v13
	v_cvt_pk_bf16_f32 v4, v6, v7
	v_cvt_pk_bf16_f32 v5, v8, v9
	global_store_dwordx4 v[14:15], v[2:5], off
	s_cbranch_vccnz .LBB0_645
	s_andn2_b64 vcc, exec, s[10:11]
	s_cbranch_vccnz .LBB0_644
	s_barrier
	s_branch .LBB0_644

; __device__ __forceinline__ unsigned cvt_pk_bf16(float lo, float hi) { const f32x2_t v = {lo, hi}; const bf16x2_t b = __builtin_convertvector(v, bf16x2_t); return __builtin_bit_cast(unsigned, b); }
; __device__ void rmsnorm_phase(const float* __restrict__ x, const float* __restrict__ g, bf16_t* h, float* outf) {
;     ...
;     for (int row = gw; row < T_; row += nw) {
;         const float4* xr = (const float4*)(x + (size_t)row * D_);
;         float4 v[4]; float ss = 0.f;
; #pragma unroll
;         for (int i = 0; i < 4; ++i) { v[i] = xr[lane + 64 * i]; ss += v[i].x * v[i].x + v[i].y * v[i].y + v[i].z * v[i].z + v[i].w * v[i].w; }
; #pragma unroll
;         for (int o = 32; o >= 1; o >>= 1) ss += __shfl_xor(ss, o);
;         const float rs = rsqrtf(ss * (1.0f / 1024.0f) + 1e-6f);
; #pragma unroll
;         for (int i = 0; i < 4; ++i) {
;             const float a = v[i].x * rs * gv[i].x, b = v[i].y * rs * gv[i].y, c = v[i].z * rs * gv[i].z, d = v[i].w * rs * gv[i].w;
;             if (outf) ((float4*)(outf + (size_t)row * D_))[lane + 64 * i] = make_float4(a, b, c, d);
;             else { u32x2 w; w.x = cvt_pk_bf16(a, b); w.y = cvt_pk_bf16(c, d); *(u32x2*)(h + (size_t)row * D_ + (lane + 64 * i) * 4) = w; }
;         }
.LBB0_668:
	global_load_dwordx4 v[22:25], v[38:39], off offset:2048
	global_load_dwordx4 v[18:21], v[38:39], off offset:3072
	global_load_dwordx4 v[30:33], v[38:39], off
	global_load_dwordx4 v[26:29], v[38:39], off offset:1024
	s_andn2_b64 vcc, exec, s[12:13]
	s_waitcnt vmcnt(0) lgkmcnt(0)
	v_mov_b32_e32 v48, v23
	v_mov_b32_e32 v49, v19
	v_mov_b32_e32 v60, v31
	v_mov_b32_e32 v61, v27
	v_mov_b32_e32 v40, v22
	v_mov_b32_e32 v41, v18
	v_mov_b32_e32 v58, v30
	v_mov_b32_e32 v59, v26
	v_pk_mul_f32 v[48:49], v[48:49], v[48:49]
	v_pk_mul_f32 v[60:61], v[60:61], v[60:61]
	v_mov_b32_e32 v54, v32
	v_mov_b32_e32 v55, v28
	v_pk_fma_f32 v[40:41], v[40:41], v[40:41], v[48:49]
	v_pk_fma_f32 v[48:49], v[58:59], v[58:59], v[60:61]
	v_mov_b32_e32 v50, v24
	v_mov_b32_e32 v51, v20
	v_mov_b32_e32 v56, v33
	v_mov_b32_e32 v57, v29
	v_pk_fma_f32 v[48:49], v[54:55], v[54:55], v[48:49]
	v_mov_b32_e32 v52, v25
	v_mov_b32_e32 v53, v21
	v_pk_fma_f32 v[40:41], v[50:51], v[50:51], v[40:41]
	v_pk_fma_f32 v[48:49], v[56:57], v[56:57], v[48:49]
	v_pk_fma_f32 v[40:41], v[52:53], v[52:53], v[40:41]
	v_add_f32_e32 v35, v48, v49
	v_add_f32_e32 v35, v35, v40
	v_add_f32_e32 v35, v35, v41
	ds_bpermute_b32 v40, v0, v35
	s_waitcnt lgkmcnt(0)
	v_add_f32_e32 v35, v35, v40
	ds_bpermute_b32 v40, v42, v35
	s_waitcnt lgkmcnt(0)
	v_add_f32_e32 v35, v35, v40
	ds_bpermute_b32 v40, v43, v35
	s_waitcnt lgkmcnt(0)
	v_add_f32_e32 v35, v35, v40
	ds_bpermute_b32 v40, v44, v35
	s_waitcnt lgkmcnt(0)
	v_add_f32_e32 v35, v35, v40
	ds_bpermute_b32 v40, v45, v35
	s_waitcnt lgkmcnt(0)
	v_add_f32_e32 v35, v35, v40
	ds_bpermute_b32 v40, v46, v35
	s_waitcnt lgkmcnt(0)
	v_add_f32_e32 v35, v35, v40
	v_fmamk_f32 v35, v35, 0x3a800000, v169
	v_mul_f32_e32 v40, 0x4b800000, v35
	v_cmp_gt_f32_e64 s[4:5], s33, v35
	s_nop 1
	v_cndmask_b32_e64 v35, v35, v40, s[4:5]
	v_rsq_f32_e32 v35, v35
	v_cndmask_b32_e64 v40, 0, 1, s[12:13]
	v_cmp_ne_u32_e64 s[2:3], 1, v40
	v_mul_f32_e32 v40, 0x45800000, v35
	v_cndmask_b32_e64 v40, v35, v40, s[4:5]
	v_pk_mul_f32 v[30:31], v[30:31], v[40:41] op_sel_hi:[1,0]
	v_pk_mul_f32 v[32:33], v[32:33], v[40:41] op_sel_hi:[1,0]
	v_pk_mul_f32 v[30:31], v[2:3], v[30:31]
	v_pk_mul_f32 v[32:33], v[4:5], v[32:33]
	s_cbranch_vccnz .LBB0_679
	global_store_dwordx4 v[38:39], v[30:33], off
	s_cbranch_execnz .LBB0_671
.LBB0_670:
	s_nop 0
	v_cvt_pk_bf16_f32 v30, v30, v31
	v_cvt_pk_bf16_f32 v31, v32, v33
	global_store_dwordx2 v[36:37], v[30:31], off
.LBB0_671:
	v_mov_b32_e32 v41, v40
	v_pk_mul_f32 v[26:27], v[26:27], v[40:41]
	v_pk_mul_f32 v[28:29], v[28:29], v[40:41]
	v_pk_mul_f32 v[26:27], v[6:7], v[26:27]
	s_and_b64 vcc, exec, s[2:3]
	v_pk_mul_f32 v[28:29], v[8:9], v[28:29]
	s_cbranch_vccnz .LBB0_680
	global_store_dwordx4 v[38:39], v[26:29], off offset:1024
	s_cbranch_execnz .LBB0_674
.LBB0_673:
	s_nop 0
	v_cvt_pk_bf16_f32 v26, v26, v27
	v_cvt_pk_bf16_f32 v27, v28, v29
	global_store_dwordx2 v[36:37], v[26:27], off offset:512
.LBB0_674:
	v_pk_mul_f32 v[22:23], v[22:23], v[40:41]
	v_pk_mul_f32 v[24:25], v[24:25], v[40:41]
	v_pk_mul_f32 v[22:23], v[10:11], v[22:23]
	s_and_b64 vcc, exec, s[2:3]
	v_pk_mul_f32 v[24:25], v[12:13], v[24:25]
	s_cbranch_vccnz .LBB0_681
	global_store_dwordx4 v[38:39], v[22:25], off offset:2048
	s_cbranch_execnz .LBB0_677
.LBB0_676:
	s_nop 0
	v_cvt_pk_bf16_f32 v22, v22, v23
	v_cvt_pk_bf16_f32 v23, v24, v25
	global_store_dwordx2 v[36:37], v[22:23], off offset:1024
.LBB0_677:
	v_pk_mul_f32 v[18:19], v[18:19], v[40:41]
	v_pk_mul_f32 v[20:21], v[20:21], v[40:41]
	v_pk_mul_f32 v[18:19], v[14:15], v[18:19]
	s_and_b64 vcc, exec, s[2:3]
	v_pk_mul_f32 v[20:21], v[16:17], v[20:21]
	s_cbranch_vccnz .LBB0_682
	global_store_dwordx4 v[38:39], v[18:21], off offset:3072
	s_cbranch_execnz .LBB0_667
	s_branch .LBB0_683

; __device__ __forceinline__ unsigned cvt_pk_bf16(float lo, float hi) { const f32x2_t v = {lo, hi}; const bf16x2_t b = __builtin_convertvector(v, bf16x2_t); return __builtin_bit_cast(unsigned, b); }
; __device__ void rmsnorm_phase(const float* __restrict__ x, const float* __restrict__ g, bf16_t* h, float* outf) {
;     ...
;         for (int i = 0; i < 4; ++i) {
;             const float a = v[i].x * rs * gv[i].x, b = v[i].y * rs * gv[i].y, c = v[i].z * rs * gv[i].z, d = v[i].w * rs * gv[i].w;
;             if (outf) ((float4*)(outf + (size_t)row * D_))[lane + 64 * i] = make_float4(a, b, c, d);
;             else { u32x2 w; w.x = cvt_pk_bf16(a, b); w.y = cvt_pk_bf16(c, d); *(u32x2*)(h + (size_t)row * D_ + (lane + 64 * i) * 4) = w; }
.LBB0_682:
.LBB0_683:
	v_cvt_pk_bf16_f32 v18, v18, v19
	v_cvt_pk_bf16_f32 v19, v20, v21
	global_store_dwordx2 v[36:37], v[18:19], off offset:1536
	s_branch .LBB0_667

; __device__ __forceinline__ int NBLK() { int t = gridDim.x; asm volatile("" : "+s"(t)); return t; }
; __device__ __forceinline__ uint4 pack8(const float (&f)[8]) { uint4 r; r.x = cvt_pk_bf16(f[0], f[1]); r.y = cvt_pk_bf16(f[2], f[3]); r.z = cvt_pk_bf16(f[4], f[5]); r.w = cvt_pk_bf16(f[6], f[7]); return r; }
; __device__ __forceinline__ void tr_cvt(const float* __restrict__ src, const float* __restrict__ src2, int srcsel, int ld, int K, int N, bf16_t* __restrict__ dst, LAS float* tl) {
;     ...
; #pragma unroll
;         for (int q = 0; q < 2; ++q) if (q == 0 || has2) {
;             const int tt = t + q * NBLK(); const int n0 = (tt / nkt) * 64, k0 = (tt % nkt) * 64;
;             float f[8];
; #pragma unroll
;             for (int j = 0; j < 8; ++j) f[j] = tl[q * 4160 + (wk + j) * 65 + wn];
;             *(uint4*)(dst + (size_t)(n0 + wn) * K + k0 + wk) = pack8(f); }
.LBB0_761:
	s_mov_b32 s25, s39
	v_add_u32_e32 v0, 0x1000, v25
	s_waitcnt lgkmcnt(0)
	s_barrier
	ds_read2_b32 v[26:27], v0 offset1:65
	ds_read2_b32 v[28:29], v0 offset0:130 offset1:195
	v_add_u32_e32 v0, 0x1400, v25
	s_ashr_i32 s25, s18, 31
	ds_read2_b32 v[30:31], v0 offset0:4 offset1:69
	ds_read2_b32 v[32:33], v0 offset0:134 offset1:199
	s_lshr_b32 s25, s25, 28
	s_add_i32 s25, s18, s25
	s_ashr_i32 s25, s25, 4
	s_waitcnt lgkmcnt(0)
	v_cvt_pk_bf16_f32 v26, v26, v27
	s_waitcnt lgkmcnt(2)
	v_cvt_pk_bf16_f32 v27, v28, v29
	s_waitcnt lgkmcnt(1)
	v_cvt_pk_bf16_f32 v28, v30, v31
	v_lshl_add_u32 v30, s25, 6, v3
	s_lshl_b32 s34, s25, 10
	v_ashrrev_i32_e32 v31, 31, v30
	s_sub_i32 s34, s20, s34
	v_lshlrev_b64 v[30:31], 11, v[30:31]
	v_lshl_add_u64 v[30:31], s[2:3], 0, v[30:31]
	s_ashr_i32 s35, s34, 31
	v_lshl_add_u64 v[30:31], s[34:35], 1, v[30:31]
	v_lshlrev_b32_e32 v0, 1, v2
	s_waitcnt lgkmcnt(0)
	v_cvt_pk_bf16_f32 v29, v32, v33
	v_lshl_add_u64 v[30:31], v[30:31], 0, v[0:1]
	s_andn2_b64 vcc, exec, s[12:13]
	global_store_dwordx4 v[30:31], v[26:29], off
	s_cbranch_vccnz .LBB0_754
	s_mov_b32 s12, s39
	s_add_i32 s12, s12, s18
	v_add_u32_e32 v26, 0x5000, v25
	v_add_u32_e32 v28, 0x5200, v25
	v_add_u32_e32 v30, 0x5400, v25
	s_ashr_i32 s13, s12, 31
	ds_read2_b32 v[26:27], v26 offset0:64 offset1:129
	ds_read2_b32 v[28:29], v28 offset0:66 offset1:131
	ds_read2_b32 v[30:31], v30 offset0:68 offset1:133
	s_lshr_b32 s13, s13, 28
	s_add_i32 s13, s12, s13
	s_and_b32 s18, s13, 0x3fffff0
	s_lshl_b32 s13, s13, 2
	v_add_u32_e32 v32, 0x5600, v25
	s_andn2_b32 s13, s13, 63
	ds_read2_b32 v[32:33], v32 offset0:70 offset1:135
	s_waitcnt lgkmcnt(0)
	v_cvt_pk_bf16_f32 v26, v26, v27
	v_cvt_pk_bf16_f32 v27, v28, v29
	v_cvt_pk_bf16_f32 v28, v30, v31
	v_add_u32_e32 v30, s13, v3
	s_sub_i32 s12, s12, s18
	v_ashrrev_i32_e32 v31, 31, v30
	s_lshl_b32 s12, s12, 6
	v_lshlrev_b64 v[30:31], 11, v[30:31]
	v_lshl_add_u64 v[30:31], s[2:3], 0, v[30:31]
	s_ashr_i32 s13, s12, 31
	v_lshl_add_u64 v[30:31], s[12:13], 1, v[30:31]
	v_cvt_pk_bf16_f32 v29, v32, v33
	v_lshl_add_u64 v[30:31], v[30:31], 0, v[0:1]
	global_store_dwordx4 v[30:31], v[26:29], off
	s_branch .LBB0_754

; __device__ __forceinline__ int NBLK() { int t = gridDim.x; asm volatile("" : "+s"(t)); return t; }
; __device__ __forceinline__ uint4 pack8(const float (&f)[8]) { uint4 r; r.x = cvt_pk_bf16(f[0], f[1]); r.y = cvt_pk_bf16(f[2], f[3]); r.z = cvt_pk_bf16(f[4], f[5]); r.w = cvt_pk_bf16(f[6], f[7]); return r; }
; __device__ __forceinline__ void tr_cvt(const float* __restrict__ src, const float* __restrict__ src2, int srcsel, int ld, int K, int N, bf16_t* __restrict__ dst, LAS float* tl) {
;     ...
; #pragma unroll
;         for (int q = 0; q < 2; ++q) if (q == 0 || has2) {
;             const int tt = t + q * NBLK(); const int n0 = (tt / nkt) * 64, k0 = (tt % nkt) * 64;
;             float f[8];
; #pragma unroll
;             for (int j = 0; j < 8; ++j) f[j] = tl[q * 4160 + (wk + j) * 65 + wn];
;             *(uint4*)(dst + (size_t)(n0 + wn) * K + k0 + wk) = pack8(f); }
.LBB0_777:
	s_mov_b32 s25, s39
	v_add_u32_e32 v0, 0x1000, v25
	s_waitcnt lgkmcnt(0)
	s_barrier
	ds_read2_b32 v[26:27], v0 offset1:65
	ds_read2_b32 v[28:29], v0 offset0:130 offset1:195
	v_add_u32_e32 v0, 0x1400, v25
	s_mul_hi_i32 s25, s18, 0x2e8ba2e9
	ds_read2_b32 v[30:31], v0 offset0:4 offset1:69
	ds_read2_b32 v[32:33], v0 offset0:134 offset1:199
	s_lshr_b32 s34, s25, 31
	s_ashr_i32 s25, s25, 3
	s_add_i32 s25, s25, s34
	s_mul_i32 s34, s25, 0xfffff500
	s_add_i32 s34, s20, s34
	s_waitcnt lgkmcnt(0)
	v_cvt_pk_bf16_f32 v26, v26, v27
	s_waitcnt lgkmcnt(2)
	v_cvt_pk_bf16_f32 v27, v28, v29
	s_waitcnt lgkmcnt(1)
	v_cvt_pk_bf16_f32 v28, v30, v31
	v_lshl_add_u32 v0, s25, 6, v3
	v_mov_b64_e32 v[30:31], s[12:13]
	v_mad_i64_i32 v[30:31], s[40:41], v0, s67, v[30:31]
	s_ashr_i32 s35, s34, 31
	v_lshl_add_u64 v[30:31], s[34:35], 1, v[30:31]
	v_lshlrev_b32_e32 v0, 1, v2
	s_waitcnt lgkmcnt(0)
	v_cvt_pk_bf16_f32 v29, v32, v33
	v_lshl_add_u64 v[30:31], v[30:31], 0, v[0:1]
	s_andn2_b64 vcc, exec, s[16:17]
	global_store_dwordx4 v[30:31], v[26:29], off
	s_cbranch_vccnz .LBB0_770
	s_mov_b32 s16, s39
	s_add_i32 s16, s16, s18
	v_add_u32_e32 v26, 0x5000, v25
	v_add_u32_e32 v28, 0x5200, v25
	v_add_u32_e32 v30, 0x5400, v25
	v_add_u32_e32 v32, 0x5600, v25
	s_mul_hi_i32 s17, s16, 0x2e8ba2e9
	ds_read2_b32 v[26:27], v26 offset0:64 offset1:129
	ds_read2_b32 v[28:29], v28 offset0:66 offset1:131
	ds_read2_b32 v[30:31], v30 offset0:68 offset1:133
	ds_read2_b32 v[32:33], v32 offset0:70 offset1:135
	s_lshr_b32 s18, s17, 31
	s_ashr_i32 s17, s17, 3
	s_add_i32 s17, s17, s18
	s_mul_i32 s18, s17, 44
	s_sub_i32 s16, s16, s18
	s_lshl_b32 s16, s16, 6
	s_waitcnt lgkmcnt(0)
	v_cvt_pk_bf16_f32 v26, v26, v27
	v_cvt_pk_bf16_f32 v27, v28, v29
	v_cvt_pk_bf16_f32 v28, v30, v31
	v_cvt_pk_bf16_f32 v29, v32, v33
	v_lshl_add_u32 v32, s17, 6, v3
	v_mov_b64_e32 v[30:31], s[12:13]
	v_mad_i64_i32 v[30:31], s[34:35], v32, s67, v[30:31]
	s_ashr_i32 s17, s16, 31
	v_lshl_add_u64 v[30:31], s[16:17], 1, v[30:31]
	v_lshl_add_u64 v[30:31], v[30:31], 0, v[0:1]
	global_store_dwordx4 v[30:31], v[26:29], off
	s_branch .LBB0_770

; __device__ __forceinline__ int NBLK() { int t = gridDim.x; asm volatile("" : "+s"(t)); return t; }
; __device__ __forceinline__ uint4 pack8(const float (&f)[8]) { uint4 r; r.x = cvt_pk_bf16(f[0], f[1]); r.y = cvt_pk_bf16(f[2], f[3]); r.z = cvt_pk_bf16(f[4], f[5]); r.w = cvt_pk_bf16(f[6], f[7]); return r; }
; __device__ __forceinline__ void tr_cvt(const float* __restrict__ src, const float* __restrict__ src2, int srcsel, int ld, int K, int N, bf16_t* __restrict__ dst, LAS float* tl) {
;     ...
; #pragma unroll
;         for (int q = 0; q < 2; ++q) if (q == 0 || has2) {
;             const int tt = t + q * NBLK(); const int n0 = (tt / nkt) * 64, k0 = (tt % nkt) * 64;
;             float f[8];
; #pragma unroll
;             for (int j = 0; j < 8; ++j) f[j] = tl[q * 4160 + (wk + j) * 65 + wn];
;             *(uint4*)(dst + (size_t)(n0 + wn) * K + k0 + wk) = pack8(f); }
.LBB0_793:
	s_mov_b32 s21, s39
	v_add_u32_e32 v0, 0x1000, v25
	s_waitcnt lgkmcnt(0)
	s_barrier
	ds_read2_b32 v[26:27], v0 offset1:65
	ds_read2_b32 v[28:29], v0 offset0:130 offset1:195
	v_add_u32_e32 v0, 0x1400, v25
	s_ashr_i32 s21, s16, 31
	ds_read2_b32 v[30:31], v0 offset0:4 offset1:69
	ds_read2_b32 v[32:33], v0 offset0:134 offset1:199
	s_lshr_b32 s21, s21, 28
	s_add_i32 s21, s16, s21
	s_ashr_i32 s21, s21, 4
	s_waitcnt lgkmcnt(0)
	v_cvt_pk_bf16_f32 v26, v26, v27
	v_cvt_pk_bf16_f32 v27, v28, v29
	v_cvt_pk_bf16_f32 v28, v30, v31
	v_lshl_add_u32 v30, s21, 6, v3
	s_lshl_b32 s24, s21, 10
	v_ashrrev_i32_e32 v31, 31, v30
	s_sub_i32 s24, s18, s24
	v_lshlrev_b64 v[30:31], 11, v[30:31]
	v_lshl_add_u64 v[30:31], s[10:11], 0, v[30:31]
	s_ashr_i32 s25, s24, 31
	v_lshl_add_u64 v[30:31], s[24:25], 1, v[30:31]
	v_lshlrev_b32_e32 v0, 1, v2
	v_cvt_pk_bf16_f32 v29, v32, v33
	v_lshl_add_u64 v[30:31], v[30:31], 0, v[0:1]
	s_andn2_b64 vcc, exec, s[14:15]
	global_store_dwordx4 v[30:31], v[26:29], off
	s_cbranch_vccnz .LBB0_786
	s_mov_b32 s14, s39
	s_add_i32 s14, s14, s16
	v_add_u32_e32 v26, 0x5000, v25
	v_add_u32_e32 v28, 0x5200, v25
	v_add_u32_e32 v30, 0x5400, v25
	s_ashr_i32 s15, s14, 31
	ds_read2_b32 v[26:27], v26 offset0:64 offset1:129
	ds_read2_b32 v[28:29], v28 offset0:66 offset1:131
	ds_read2_b32 v[30:31], v30 offset0:68 offset1:133
	s_lshr_b32 s15, s15, 28
	s_add_i32 s15, s14, s15
	s_and_b32 s16, s15, 0x3fffff0
	s_lshl_b32 s15, s15, 2
	v_add_u32_e32 v32, 0x5600, v25
	s_andn2_b32 s15, s15, 63
	ds_read2_b32 v[32:33], v32 offset0:70 offset1:135
	s_waitcnt lgkmcnt(0)
	v_cvt_pk_bf16_f32 v26, v26, v27
	v_cvt_pk_bf16_f32 v27, v28, v29
	v_cvt_pk_bf16_f32 v28, v30, v31
	v_add_u32_e32 v30, s15, v3
	s_sub_i32 s14, s14, s16
	v_ashrrev_i32_e32 v31, 31, v30
	s_lshl_b32 s14, s14, 6
	v_lshlrev_b64 v[30:31], 11, v[30:31]
	v_lshl_add_u64 v[30:31], s[10:11], 0, v[30:31]
	s_ashr_i32 s15, s14, 31
	v_lshl_add_u64 v[30:31], s[14:15], 1, v[30:31]
	v_cvt_pk_bf16_f32 v29, v32, v33
	v_lshl_add_u64 v[30:31], v[30:31], 0, v[0:1]
	global_store_dwordx4 v[30:31], v[26:29], off
	s_branch .LBB0_786

; __device__ __forceinline__ int NBLK() { int t = gridDim.x; asm volatile("" : "+s"(t)); return t; }
; __device__ __forceinline__ uint4 pack8(const float (&f)[8]) { uint4 r; r.x = cvt_pk_bf16(f[0], f[1]); r.y = cvt_pk_bf16(f[2], f[3]); r.z = cvt_pk_bf16(f[4], f[5]); r.w = cvt_pk_bf16(f[6], f[7]); return r; }
; __device__ __forceinline__ void tr_cvt(const float* __restrict__ src, const float* __restrict__ src2, int srcsel, int ld, int K, int N, bf16_t* __restrict__ dst, LAS float* tl) {
;     ...
; #pragma unroll
;         for (int q = 0; q < 2; ++q) if (q == 0 || has2) {
;             const int tt = t + q * NBLK(); const int n0 = (tt / nkt) * 64, k0 = (tt % nkt) * 64;
;             float f[8];
; #pragma unroll
;             for (int j = 0; j < 8; ++j) f[j] = tl[q * 4160 + (wk + j) * 65 + wn];
;             *(uint4*)(dst + (size_t)(n0 + wn) * K + k0 + wk) = pack8(f); }
.LBB0_809:
	s_mov_b32 s35, s39
	v_add_u32_e32 v0, 0x1000, v25
	s_waitcnt lgkmcnt(0)
	s_barrier
	ds_read2_b32 v[26:27], v0 offset1:65
	ds_read2_b32 v[28:29], v0 offset0:130 offset1:195
	v_add_u32_e32 v0, 0x1400, v25
	s_ashr_i32 s35, s20, 31
	ds_read2_b32 v[30:31], v0 offset0:4 offset1:69
	ds_read2_b32 v[32:33], v0 offset0:134 offset1:199
	s_lshr_b32 s35, s35, 28
	s_add_i32 s35, s20, s35
	s_ashr_i32 s35, s35, 4
	s_waitcnt lgkmcnt(0)
	v_cvt_pk_bf16_f32 v26, v26, v27
	v_cvt_pk_bf16_f32 v27, v28, v29
	v_cvt_pk_bf16_f32 v28, v30, v31
	v_lshl_add_u32 v30, s35, 6, v3
	s_lshl_b32 s40, s35, 10
	v_ashrrev_i32_e32 v31, 31, v30
	s_sub_i32 s40, s24, s40
	v_lshlrev_b64 v[30:31], 11, v[30:31]
	v_lshl_add_u64 v[30:31], s[14:15], 0, v[30:31]
	s_ashr_i32 s41, s40, 31
	v_lshl_add_u64 v[30:31], s[40:41], 1, v[30:31]
	v_lshlrev_b32_e32 v0, 1, v2
	v_cvt_pk_bf16_f32 v29, v32, v33
	v_lshl_add_u64 v[30:31], v[30:31], 0, v[0:1]
	s_andn2_b64 vcc, exec, s[18:19]
	global_store_dwordx4 v[30:31], v[26:29], off
	s_cbranch_vccnz .LBB0_802
	s_mov_b32 s18, s39
	s_add_i32 s18, s18, s20
	v_add_u32_e32 v26, 0x5000, v25
	v_add_u32_e32 v28, 0x5200, v25
	v_add_u32_e32 v30, 0x5400, v25
	s_ashr_i32 s19, s18, 31
	ds_read2_b32 v[26:27], v26 offset0:64 offset1:129
	ds_read2_b32 v[28:29], v28 offset0:66 offset1:131
	ds_read2_b32 v[30:31], v30 offset0:68 offset1:133
	s_lshr_b32 s19, s19, 28
	s_add_i32 s19, s18, s19
	s_and_b32 s20, s19, 0x3fffff0
	s_lshl_b32 s19, s19, 2
	v_add_u32_e32 v32, 0x5600, v25
	s_andn2_b32 s19, s19, 63
	ds_read2_b32 v[32:33], v32 offset0:70 offset1:135
	s_waitcnt lgkmcnt(0)
	v_cvt_pk_bf16_f32 v26, v26, v27
	v_cvt_pk_bf16_f32 v27, v28, v29
	v_cvt_pk_bf16_f32 v28, v30, v31
	v_add_u32_e32 v30, s19, v3
	s_sub_i32 s18, s18, s20
	v_ashrrev_i32_e32 v31, 31, v30
	s_lshl_b32 s18, s18, 6
	v_lshlrev_b64 v[30:31], 11, v[30:31]
	v_lshl_add_u64 v[30:31], s[14:15], 0, v[30:31]
	s_ashr_i32 s19, s18, 31
	v_lshl_add_u64 v[30:31], s[18:19], 1, v[30:31]
	v_cvt_pk_bf16_f32 v29, v32, v33
	v_lshl_add_u64 v[30:31], v[30:31], 0, v[0:1]
	global_store_dwordx4 v[30:31], v[26:29], off
	s_branch .LBB0_802

; __device__ __forceinline__ int NBLK() { int t = gridDim.x; asm volatile("" : "+s"(t)); return t; }
; __device__ __forceinline__ uint4 pack8(const float (&f)[8]) { uint4 r; r.x = cvt_pk_bf16(f[0], f[1]); r.y = cvt_pk_bf16(f[2], f[3]); r.z = cvt_pk_bf16(f[4], f[5]); r.w = cvt_pk_bf16(f[6], f[7]); return r; }
; __device__ __forceinline__ void tr_cvt(const float* __restrict__ src, const float* __restrict__ src2, int srcsel, int ld, int K, int N, bf16_t* __restrict__ dst, LAS float* tl) {
;     ...
; #pragma unroll
;         for (int q = 0; q < 2; ++q) if (q == 0 || has2) {
;             const int tt = t + q * NBLK(); const int n0 = (tt / nkt) * 64, k0 = (tt % nkt) * 64;
;             float f[8];
; #pragma unroll
;             for (int j = 0; j < 8; ++j) f[j] = tl[q * 4160 + (wk + j) * 65 + wn];
;             *(uint4*)(dst + (size_t)(n0 + wn) * K + k0 + wk) = pack8(f); }
.LBB0_841:
	s_mov_b32 s35, s39
	v_add_u32_e32 v0, 0x1000, v25
	s_waitcnt lgkmcnt(0)
	s_barrier
	ds_read2_b32 v[26:27], v0 offset1:65
	ds_read2_b32 v[28:29], v0 offset0:130 offset1:195
	v_add_u32_e32 v0, 0x1400, v25
	s_ashr_i32 s35, s20, 31
	ds_read2_b32 v[30:31], v0 offset0:4 offset1:69
	ds_read2_b32 v[32:33], v0 offset0:134 offset1:199
	s_lshr_b32 s35, s35, 29
	s_add_i32 s35, s20, s35
	s_ashr_i32 s35, s35, 3
	s_waitcnt lgkmcnt(0)
	v_cvt_pk_bf16_f32 v26, v26, v27
	s_waitcnt lgkmcnt(2)
	v_cvt_pk_bf16_f32 v27, v28, v29
	s_waitcnt lgkmcnt(1)
	v_cvt_pk_bf16_f32 v28, v30, v31
	v_lshl_add_u32 v30, s35, 6, v3
	s_lshl_b32 s40, s35, 9
	v_ashrrev_i32_e32 v31, 31, v30
	s_sub_i32 s40, s24, s40
	v_lshlrev_b64 v[30:31], 10, v[30:31]
	v_lshl_add_u64 v[30:31], s[14:15], 0, v[30:31]
	s_ashr_i32 s41, s40, 31
	v_lshl_add_u64 v[30:31], s[40:41], 1, v[30:31]
	v_lshlrev_b32_e32 v0, 1, v2
	s_waitcnt lgkmcnt(0)
	v_cvt_pk_bf16_f32 v29, v32, v33
	v_lshl_add_u64 v[30:31], v[30:31], 0, v[0:1]
	s_andn2_b64 vcc, exec, s[18:19]
	global_store_dwordx4 v[30:31], v[26:29], off
	s_cbranch_vccnz .LBB0_834
	s_mov_b32 s18, s39
	s_add_i32 s18, s18, s20
	v_add_u32_e32 v26, 0x5000, v25
	v_add_u32_e32 v28, 0x5200, v25
	v_add_u32_e32 v30, 0x5400, v25
	s_ashr_i32 s19, s18, 31
	ds_read2_b32 v[26:27], v26 offset0:64 offset1:129
	ds_read2_b32 v[28:29], v28 offset0:66 offset1:131
	ds_read2_b32 v[30:31], v30 offset0:68 offset1:133
	s_lshr_b32 s19, s19, 29
	s_add_i32 s19, s18, s19
	s_and_b32 s20, s19, 0x3fffff8
	s_lshl_b32 s19, s19, 3
	v_add_u32_e32 v32, 0x5600, v25
	s_andn2_b32 s19, s19, 63
	ds_read2_b32 v[32:33], v32 offset0:70 offset1:135
	s_waitcnt lgkmcnt(0)
	v_cvt_pk_bf16_f32 v26, v26, v27
	v_cvt_pk_bf16_f32 v27, v28, v29
	v_cvt_pk_bf16_f32 v28, v30, v31
	v_add_u32_e32 v30, s19, v3
	s_sub_i32 s18, s18, s20
	v_ashrrev_i32_e32 v31, 31, v30
	s_lshl_b32 s18, s18, 6
	v_lshlrev_b64 v[30:31], 10, v[30:31]
	v_lshl_add_u64 v[30:31], s[14:15], 0, v[30:31]
	s_ashr_i32 s19, s18, 31
	v_lshl_add_u64 v[30:31], s[18:19], 1, v[30:31]
	v_cvt_pk_bf16_f32 v29, v32, v33
	v_lshl_add_u64 v[30:31], v[30:31], 0, v[0:1]
	global_store_dwordx4 v[30:31], v[26:29], off
	s_branch .LBB0_834

; __device__ __forceinline__ int NBLK() { int t = gridDim.x; asm volatile("" : "+s"(t)); return t; }
; __device__ __forceinline__ uint4 pack8(const float (&f)[8]) { uint4 r; r.x = cvt_pk_bf16(f[0], f[1]); r.y = cvt_pk_bf16(f[2], f[3]); r.z = cvt_pk_bf16(f[4], f[5]); r.w = cvt_pk_bf16(f[6], f[7]); return r; }
; __device__ __forceinline__ void tr_cvt(const float* __restrict__ src, const float* __restrict__ src2, int srcsel, int ld, int K, int N, bf16_t* __restrict__ dst, LAS float* tl) {
;     ...
; #pragma unroll
;         for (int q = 0; q < 2; ++q) if (q == 0 || has2) {
;             const int tt = t + q * NBLK(); const int n0 = (tt / nkt) * 64, k0 = (tt % nkt) * 64;
;             float f[8];
; #pragma unroll
;             for (int j = 0; j < 8; ++j) f[j] = tl[q * 4160 + (wk + j) * 65 + wn];
;             *(uint4*)(dst + (size_t)(n0 + wn) * K + k0 + wk) = pack8(f); }
.LBB0_857:
	s_mov_b32 s41, s39
	v_add_u32_e32 v0, 0x1000, v25
	s_waitcnt lgkmcnt(0)
	s_barrier
	ds_read2_b32 v[26:27], v0 offset1:65
	ds_read2_b32 v[28:29], v0 offset0:130 offset1:195
	v_add_u32_e32 v0, 0x1400, v25
	s_ashr_i32 s41, s24, 31
	ds_read2_b32 v[30:31], v0 offset0:4 offset1:69
	ds_read2_b32 v[32:33], v0 offset0:134 offset1:199
	s_lshr_b32 s41, s41, 29
	s_add_i32 s41, s24, s41
	s_ashr_i32 s41, s41, 3
	s_waitcnt lgkmcnt(0)
	v_cvt_pk_bf16_f32 v26, v26, v27
	s_waitcnt lgkmcnt(2)
	v_cvt_pk_bf16_f32 v27, v28, v29
	s_waitcnt lgkmcnt(1)
	v_cvt_pk_bf16_f32 v28, v30, v31
	v_lshl_add_u32 v30, s41, 6, v3
	s_lshl_b32 s42, s41, 9
	v_ashrrev_i32_e32 v31, 31, v30
	s_sub_i32 s42, s34, s42
	v_lshlrev_b64 v[30:31], 10, v[30:31]
	v_lshl_add_u64 v[30:31], s[16:17], 0, v[30:31]
	s_ashr_i32 s43, s42, 31
	v_lshl_add_u64 v[30:31], s[42:43], 1, v[30:31]
	v_lshlrev_b32_e32 v0, 1, v2
	s_waitcnt lgkmcnt(0)
	v_cvt_pk_bf16_f32 v29, v32, v33
	v_lshl_add_u64 v[30:31], v[30:31], 0, v[0:1]
	s_andn2_b64 vcc, exec, s[20:21]
	global_store_dwordx4 v[30:31], v[26:29], off
	s_cbranch_vccnz .LBB0_850
	s_mov_b32 s20, s39
	s_add_i32 s20, s20, s24
	v_add_u32_e32 v26, 0x5000, v25
	v_add_u32_e32 v28, 0x5200, v25
	v_add_u32_e32 v30, 0x5400, v25
	s_ashr_i32 s21, s20, 31
	ds_read2_b32 v[26:27], v26 offset0:64 offset1:129
	ds_read2_b32 v[28:29], v28 offset0:66 offset1:131
	ds_read2_b32 v[30:31], v30 offset0:68 offset1:133
	s_lshr_b32 s21, s21, 29
	s_add_i32 s21, s20, s21
	s_and_b32 s24, s21, 0x3fffff8
	s_lshl_b32 s21, s21, 3
	v_add_u32_e32 v32, 0x5600, v25
	s_andn2_b32 s21, s21, 63
	ds_read2_b32 v[32:33], v32 offset0:70 offset1:135
	s_waitcnt lgkmcnt(0)
	v_cvt_pk_bf16_f32 v26, v26, v27
	v_cvt_pk_bf16_f32 v27, v28, v29
	v_cvt_pk_bf16_f32 v28, v30, v31
	v_add_u32_e32 v30, s21, v3
	s_sub_i32 s20, s20, s24
	v_ashrrev_i32_e32 v31, 31, v30
	s_lshl_b32 s20, s20, 6
	v_lshlrev_b64 v[30:31], 10, v[30:31]
	v_lshl_add_u64 v[30:31], s[16:17], 0, v[30:31]
	s_ashr_i32 s21, s20, 31
	v_lshl_add_u64 v[30:31], s[20:21], 1, v[30:31]
	v_cvt_pk_bf16_f32 v29, v32, v33
	v_lshl_add_u64 v[30:31], v[30:31], 0, v[0:1]
	global_store_dwordx4 v[30:31], v[26:29], off
	s_branch .LBB0_850

; __device__ __forceinline__ int NBLK() { int t = gridDim.x; asm volatile("" : "+s"(t)); return t; }
; __device__ __forceinline__ uint4 pack8(const float (&f)[8]) { uint4 r; r.x = cvt_pk_bf16(f[0], f[1]); r.y = cvt_pk_bf16(f[2], f[3]); r.z = cvt_pk_bf16(f[4], f[5]); r.w = cvt_pk_bf16(f[6], f[7]); return r; }
; __device__ __forceinline__ void tr_cvt(const float* __restrict__ src, const float* __restrict__ src2, int srcsel, int ld, int K, int N, bf16_t* __restrict__ dst, LAS float* tl) {
;     ...
; #pragma unroll
;         for (int q = 0; q < 2; ++q) if (q == 0 || has2) {
;             const int tt = t + q * NBLK(); const int n0 = (tt / nkt) * 64, k0 = (tt % nkt) * 64;
;             float f[8];
; #pragma unroll
;             for (int j = 0; j < 8; ++j) f[j] = tl[q * 4160 + (wk + j) * 65 + wn];
;             *(uint4*)(dst + (size_t)(n0 + wn) * K + k0 + wk) = pack8(f); }
.LBB0_889:
	s_mov_b32 s35, s39
	v_add_u32_e32 v0, 0x1000, v25
	s_waitcnt lgkmcnt(0)
	s_barrier
	ds_read2_b32 v[26:27], v0 offset1:65
	ds_read2_b32 v[28:29], v0 offset0:130 offset1:195
	v_add_u32_e32 v0, 0x1400, v25
	s_ashr_i32 s35, s20, 31
	ds_read2_b32 v[30:31], v0 offset0:4 offset1:69
	ds_read2_b32 v[32:33], v0 offset0:134 offset1:199
	s_lshr_b32 s35, s35, 28
	s_add_i32 s35, s20, s35
	s_ashr_i32 s35, s35, 4
	s_waitcnt lgkmcnt(0)
	v_cvt_pk_bf16_f32 v26, v26, v27
	s_waitcnt lgkmcnt(2)
	v_cvt_pk_bf16_f32 v27, v28, v29
	s_waitcnt lgkmcnt(1)
	v_cvt_pk_bf16_f32 v28, v30, v31
	v_lshl_add_u32 v30, s35, 6, v3
	s_lshl_b32 s40, s35, 10
	v_ashrrev_i32_e32 v31, 31, v30
	s_sub_i32 s40, s24, s40
	v_lshlrev_b64 v[30:31], 11, v[30:31]
	v_lshl_add_u64 v[30:31], s[14:15], 0, v[30:31]
	s_ashr_i32 s41, s40, 31
	v_lshl_add_u64 v[30:31], s[40:41], 1, v[30:31]
	v_lshlrev_b32_e32 v0, 1, v2
	s_waitcnt lgkmcnt(0)
	v_cvt_pk_bf16_f32 v29, v32, v33
	v_lshl_add_u64 v[30:31], v[30:31], 0, v[0:1]
	s_andn2_b64 vcc, exec, s[18:19]
	global_store_dwordx4 v[30:31], v[26:29], off
	s_cbranch_vccnz .LBB0_882
	s_mov_b32 s18, s39
	s_add_i32 s18, s18, s20
	v_add_u32_e32 v26, 0x5000, v25
	v_add_u32_e32 v28, 0x5200, v25
	v_add_u32_e32 v30, 0x5400, v25
	s_ashr_i32 s19, s18, 31
	ds_read2_b32 v[26:27], v26 offset0:64 offset1:129
	ds_read2_b32 v[28:29], v28 offset0:66 offset1:131
	ds_read2_b32 v[30:31], v30 offset0:68 offset1:133
	s_lshr_b32 s19, s19, 28
	s_add_i32 s19, s18, s19
	s_and_b32 s20, s19, 0x3fffff0
	s_lshl_b32 s19, s19, 2
	v_add_u32_e32 v32, 0x5600, v25
	s_andn2_b32 s19, s19, 63
	ds_read2_b32 v[32:33], v32 offset0:70 offset1:135
	s_waitcnt lgkmcnt(0)
	v_cvt_pk_bf16_f32 v26, v26, v27
	v_cvt_pk_bf16_f32 v27, v28, v29
	v_cvt_pk_bf16_f32 v28, v30, v31
	v_add_u32_e32 v30, s19, v3
	s_sub_i32 s18, s18, s20
	v_ashrrev_i32_e32 v31, 31, v30
	s_lshl_b32 s18, s18, 6
	v_lshlrev_b64 v[30:31], 11, v[30:31]
	v_lshl_add_u64 v[30:31], s[14:15], 0, v[30:31]
	s_ashr_i32 s19, s18, 31
	v_lshl_add_u64 v[30:31], s[18:19], 1, v[30:31]
	v_cvt_pk_bf16_f32 v29, v32, v33
	v_lshl_add_u64 v[30:31], v[30:31], 0, v[0:1]
	global_store_dwordx4 v[30:31], v[26:29], off
	s_branch .LBB0_882

; __device__ __forceinline__ int NBLK() { int t = gridDim.x; asm volatile("" : "+s"(t)); return t; }
; __device__ __forceinline__ uint4 pack8(const float (&f)[8]) { uint4 r; r.x = cvt_pk_bf16(f[0], f[1]); r.y = cvt_pk_bf16(f[2], f[3]); r.z = cvt_pk_bf16(f[4], f[5]); r.w = cvt_pk_bf16(f[6], f[7]); return r; }
; __device__ __forceinline__ void tr_cvt(const float* __restrict__ src, const float* __restrict__ src2, int srcsel, int ld, int K, int N, bf16_t* __restrict__ dst, LAS float* tl) {
;     ...
; #pragma unroll
;         for (int q = 0; q < 2; ++q) if (q == 0 || has2) {
;             const int tt = t + q * NBLK(); const int n0 = (tt / nkt) * 64, k0 = (tt % nkt) * 64;
;             float f[8];
; #pragma unroll
;             for (int j = 0; j < 8; ++j) f[j] = tl[q * 4160 + (wk + j) * 65 + wn];
;             *(uint4*)(dst + (size_t)(n0 + wn) * K + k0 + wk) = pack8(f); }
.LBB0_905:
	s_mov_b32 s41, s39
	v_add_u32_e32 v0, 0x1000, v25
	s_waitcnt lgkmcnt(0)
	s_barrier
	ds_read2_b32 v[26:27], v0 offset1:65
	ds_read2_b32 v[28:29], v0 offset0:130 offset1:195
	v_add_u32_e32 v0, 0x1400, v25
	s_ashr_i32 s41, s24, 31
	ds_read2_b32 v[30:31], v0 offset0:4 offset1:69
	ds_read2_b32 v[32:33], v0 offset0:134 offset1:199
	s_lshr_b32 s41, s41, 28
	s_add_i32 s41, s24, s41
	s_ashr_i32 s41, s41, 4
	s_waitcnt lgkmcnt(0)
	v_cvt_pk_bf16_f32 v26, v26, v27
	s_waitcnt lgkmcnt(2)
	v_cvt_pk_bf16_f32 v27, v28, v29
	s_waitcnt lgkmcnt(1)
	v_cvt_pk_bf16_f32 v28, v30, v31
	v_lshl_add_u32 v30, s41, 6, v3
	s_lshl_b32 s42, s41, 10
	v_ashrrev_i32_e32 v31, 31, v30
	s_sub_i32 s42, s34, s42
	v_lshlrev_b64 v[30:31], 11, v[30:31]
	v_lshl_add_u64 v[30:31], s[12:13], 0, v[30:31]
	s_ashr_i32 s43, s42, 31
	v_lshl_add_u64 v[30:31], s[42:43], 1, v[30:31]
	v_lshlrev_b32_e32 v0, 1, v2
	s_waitcnt lgkmcnt(0)
	v_cvt_pk_bf16_f32 v29, v32, v33
	v_lshl_add_u64 v[30:31], v[30:31], 0, v[0:1]
	s_andn2_b64 vcc, exec, s[16:17]
	global_store_dwordx4 v[30:31], v[26:29], off
	s_cbranch_vccnz .LBB0_898
	s_mov_b32 s16, s39
	s_add_i32 s16, s16, s24
	v_add_u32_e32 v26, 0x5000, v25
	v_add_u32_e32 v28, 0x5200, v25
	v_add_u32_e32 v30, 0x5400, v25
	s_ashr_i32 s17, s16, 31
	ds_read2_b32 v[26:27], v26 offset0:64 offset1:129
	ds_read2_b32 v[28:29], v28 offset0:66 offset1:131
	ds_read2_b32 v[30:31], v30 offset0:68 offset1:133
	s_lshr_b32 s17, s17, 28
	s_add_i32 s17, s16, s17
	s_and_b32 s24, s17, 0x3fffff0
	s_lshl_b32 s17, s17, 2
	v_add_u32_e32 v32, 0x5600, v25
	s_andn2_b32 s17, s17, 63
	ds_read2_b32 v[32:33], v32 offset0:70 offset1:135
	s_waitcnt lgkmcnt(0)
	v_cvt_pk_bf16_f32 v26, v26, v27
	v_cvt_pk_bf16_f32 v27, v28, v29
	v_cvt_pk_bf16_f32 v28, v30, v31
	v_add_u32_e32 v30, s17, v3
	s_sub_i32 s16, s16, s24
	v_ashrrev_i32_e32 v31, 31, v30
	s_lshl_b32 s16, s16, 6
	v_lshlrev_b64 v[30:31], 11, v[30:31]
	v_lshl_add_u64 v[30:31], s[12:13], 0, v[30:31]
	s_ashr_i32 s17, s16, 31
	v_lshl_add_u64 v[30:31], s[16:17], 1, v[30:31]
	v_cvt_pk_bf16_f32 v29, v32, v33
	v_lshl_add_u64 v[30:31], v[30:31], 0, v[0:1]
	global_store_dwordx4 v[30:31], v[26:29], off
	s_branch .LBB0_898

; __device__ __forceinline__ int NBLK() { int t = gridDim.x; asm volatile("" : "+s"(t)); return t; }
; __device__ __forceinline__ uint4 pack8(const float (&f)[8]) { uint4 r; r.x = cvt_pk_bf16(f[0], f[1]); r.y = cvt_pk_bf16(f[2], f[3]); r.z = cvt_pk_bf16(f[4], f[5]); r.w = cvt_pk_bf16(f[6], f[7]); return r; }
; __device__ __forceinline__ void tr_cvt(const float* __restrict__ src, const float* __restrict__ src2, int srcsel, int ld, int K, int N, bf16_t* __restrict__ dst, LAS float* tl) {
;     ...
; #pragma unroll
;         for (int q = 0; q < 2; ++q) if (q == 0 || has2) {
;             const int tt = t + q * NBLK(); const int n0 = (tt / nkt) * 64, k0 = (tt % nkt) * 64;
;             float f[8];
; #pragma unroll
;             for (int j = 0; j < 8; ++j) f[j] = tl[q * 4160 + (wk + j) * 65 + wn];
;             *(uint4*)(dst + (size_t)(n0 + wn) * K + k0 + wk) = pack8(f); }
.LBB0_921:
	s_mov_b32 s21, s39
	v_add_u32_e32 v0, 0x1000, v25
	s_waitcnt lgkmcnt(0)
	s_barrier
	ds_read2_b32 v[26:27], v0 offset1:65
	ds_read2_b32 v[28:29], v0 offset0:130 offset1:195
	v_add_u32_e32 v0, 0x1400, v25
	s_mul_hi_i32 s21, s16, 0x2e8ba2e9
	ds_read2_b32 v[30:31], v0 offset0:4 offset1:69
	ds_read2_b32 v[32:33], v0 offset0:134 offset1:199
	s_lshr_b32 s24, s21, 31
	s_ashr_i32 s21, s21, 3
	s_add_i32 s21, s21, s24
	s_mul_i32 s24, s21, 0xfffff500
	s_add_i32 s24, s18, s24
	s_waitcnt lgkmcnt(0)
	v_cvt_pk_bf16_f32 v26, v26, v27
	s_waitcnt lgkmcnt(2)
	v_cvt_pk_bf16_f32 v27, v28, v29
	s_waitcnt lgkmcnt(1)
	v_cvt_pk_bf16_f32 v28, v30, v31
	v_lshl_add_u32 v0, s21, 6, v3
	v_mov_b64_e32 v[30:31], s[4:5]
	v_mad_i64_i32 v[30:31], s[34:35], v0, s67, v[30:31]
	s_ashr_i32 s25, s24, 31
	v_lshl_add_u64 v[30:31], s[24:25], 1, v[30:31]
	v_lshlrev_b32_e32 v0, 1, v2
	s_waitcnt lgkmcnt(0)
	v_cvt_pk_bf16_f32 v29, v32, v33
	v_lshl_add_u64 v[30:31], v[30:31], 0, v[0:1]
	s_andn2_b64 vcc, exec, s[14:15]
	global_store_dwordx4 v[30:31], v[26:29], off
	s_cbranch_vccnz .LBB0_914
	s_mov_b32 s14, s39
	s_add_i32 s14, s14, s16
	v_add_u32_e32 v26, 0x5000, v25
	v_add_u32_e32 v28, 0x5200, v25
	v_add_u32_e32 v30, 0x5400, v25
	v_add_u32_e32 v32, 0x5600, v25
	s_mul_hi_i32 s15, s14, 0x2e8ba2e9
	ds_read2_b32 v[26:27], v26 offset0:64 offset1:129
	ds_read2_b32 v[28:29], v28 offset0:66 offset1:131
	ds_read2_b32 v[30:31], v30 offset0:68 offset1:133
	ds_read2_b32 v[32:33], v32 offset0:70 offset1:135
	s_lshr_b32 s16, s15, 31
	s_ashr_i32 s15, s15, 3
	s_add_i32 s15, s15, s16
	s_mul_i32 s16, s15, 44
	s_sub_i32 s14, s14, s16
	s_lshl_b32 s14, s14, 6
	s_waitcnt lgkmcnt(0)
	v_cvt_pk_bf16_f32 v26, v26, v27
	v_cvt_pk_bf16_f32 v27, v28, v29
	v_cvt_pk_bf16_f32 v28, v30, v31
	v_cvt_pk_bf16_f32 v29, v32, v33
	v_lshl_add_u32 v32, s15, 6, v3
	v_mov_b64_e32 v[30:31], s[4:5]
	v_mad_i64_i32 v[30:31], s[24:25], v32, s67, v[30:31]
	s_ashr_i32 s15, s14, 31
	v_lshl_add_u64 v[30:31], s[14:15], 1, v[30:31]
	v_lshl_add_u64 v[30:31], v[30:31], 0, v[0:1]
	global_store_dwordx4 v[30:31], v[26:29], off
	s_branch .LBB0_914

; __device__ __forceinline__ uint4 pack8(const float (&f)[8]) { uint4 r; r.x = cvt_pk_bf16(f[0], f[1]); r.y = cvt_pk_bf16(f[2], f[3]); r.z = cvt_pk_bf16(f[4], f[5]); r.w = cvt_pk_bf16(f[6], f[7]); return r; }
; __device__ void prep_phase(const Params& p, int l, LAS unsigned char* lds) {
;     ...
;     for (int i = gtid; i < 64 * (D_ / 8); i += gsz) {
;         const int n = i & 63, kc = i >> 6; const int srccol = (n < 32) ? (1536 + n) : (2080 + 1728 + (n - 32)); const int drow = (n < 32) ? (1536 + n) : (ZGC + 1728 + (n - 32));
;         float v[8];
; #pragma unroll
;         for (int j = 0; j < 8; ++j) v[j] = w_in[(size_t)(kc * 8 + j) * WINC + srccol];
;         *(uint4*)(W + W_IN + (size_t)drow * D_ + kc * 8) = pack8(v);
;     }
.LBB0_925:
	v_ashrrev_i32_e32 v3, 3, v0
	v_and_b32_e32 v8, -8, v3
	v_or_b32_e32 v9, 1, v8
	v_or_b32_e32 v16, 2, v8
	v_or_b32_e32 v18, 3, v8
	v_or_b32_e32 v3, 7, v3
	v_mad_i64_i32 v[10:11], s[12:13], v8, s69, v[4:5]
	v_or_b32_e32 v20, 4, v8
	v_or_b32_e32 v24, 5, v8
	v_or_b32_e32 v26, 6, v8
	v_mad_i64_i32 v[14:15], s[12:13], v9, s69, v[4:5]
	v_mad_i64_i32 v[16:17], s[12:13], v16, s69, v[4:5]
	v_mad_i64_i32 v[18:19], s[12:13], v18, s69, v[4:5]
	v_mad_i64_i32 v[12:13], s[12:13], v3, s69, v[4:5]
	v_mad_i64_i32 v[22:23], s[12:13], v20, s69, v[4:5]
	v_mad_i64_i32 v[24:25], s[12:13], v24, s69, v[4:5]
	v_mad_i64_i32 v[26:27], s[12:13], v26, s69, v[4:5]
	global_load_dword v3, v[10:11], off
	s_nop 0
	global_load_dword v10, v[14:15], off
	global_load_dword v11, v[16:17], off
	s_nop 0
	global_load_dword v14, v[18:19], off
	global_load_dword v15, v[22:23], off
	global_load_dword v16, v[24:25], off
	global_load_dword v17, v[26:27], off
	s_nop 0
	global_load_dword v18, v[12:13], off
	v_add_u32_e32 v0, s4, v0
	v_cmp_lt_i32_e32 vcc, s5, v0
	v_ashrrev_i32_e32 v9, 31, v8
	s_or_b64 s[10:11], vcc, s[10:11]
	v_lshl_add_u64 v[12:13], v[8:9], 1, v[6:7]
	s_waitcnt vmcnt(0)
	v_cvt_pk_bf16_f32 v8, v3, v10
	v_cvt_pk_bf16_f32 v9, v11, v14
	v_cvt_pk_bf16_f32 v10, v15, v16
	v_cvt_pk_bf16_f32 v11, v17, v18
	global_store_dwordx4 v[12:13], v[8:11], off
	s_andn2_b64 exec, exec, s[10:11]
	s_cbranch_execnz .LBB0_925

; __device__ __forceinline__ int BID() { int t = blockIdx.x; asm volatile("" : "+s"(t)); return t; }
; __device__ __forceinline__ int NBLK() { int t = gridDim.x; asm volatile("" : "+s"(t)); return t; }
; __device__ __forceinline__ unsigned cvt_pk_bf16(float lo, float hi) { const f32x2_t v = {lo, hi}; const bf16x2_t b = __builtin_convertvector(v, bf16x2_t); return __builtin_bit_cast(unsigned, b); }
; __device__ void prep_phase(const Params& p, int l, LAS unsigned char* lds) {
;     ...
;         for (int pr = BID() * 4; pr < 4096; pr += NBLK() * 4) {
;             const int pair = pr + q, k = pair >> 2, g = pair & 3;
;             __syncthreads();
;             ws_[tid] = w_in[(size_t)k * WINC + 1568 + g * 128 + cp];
;             __syncthreads();
;             float ca = 0.f, sa = 0.f;
; #pragma unroll 8
;             for (int c = 0; c < 128; ++c) { const float w = ws_[q * 128 + c]; const int j = (c * cp) & 127; ca += w * cosT[j]; sa += w * sinT[j]; }
;             const size_t n0 = (size_t)(g * 128 + cp) * 2;
;             W[W_FOLD + n0 * 1024 + k] = (bf16_t)(cvt_pk_bf16(ca, ca) & 0xffffu); W[W_FOLD + (n0 + 1) * 1024 + k] = (bf16_t)(cvt_pk_bf16(sa, sa) & 0xffffu);
;         }
.LBB0_929:
	v_and_b32_e32 v32, 0x78, v9
	v_add_u32_e32 v28, s2, v16
	v_add_u32_e32 v33, v21, v9
	v_lshl_add_u32 v32, v32, 2, 0
	ds_read_b128 v[24:27], v28
	ds_read_b128 v[28:31], v28 offset:16
	v_and_b32_e32 v40, 0x7f, v33
	ds_read2st64_b32 v[32:33], v32 offset1:2
	v_add_u32_e32 v34, v18, v9
	v_add_u32_e32 v35, v19, v9
	v_add_u32_e32 v36, v14, v9
	v_add_u32_e32 v37, v20, v9
	v_add_u32_e32 v38, v22, v9
	v_add_u32_e32 v39, v23, v9
	v_and_b32_e32 v34, 0x7e, v34
	v_and_b32_e32 v35, 0x7f, v35
	v_and_b32_e32 v36, 0x7c, v36
	v_and_b32_e32 v37, 0x7f, v37
	v_and_b32_e32 v38, 0x7e, v38
	v_and_b32_e32 v39, 0x7f, v39
	v_lshl_add_u32 v40, v40, 2, 0
	v_lshl_add_u32 v41, v34, 2, 0
	v_lshl_add_u32 v42, v35, 2, 0
	v_lshl_add_u32 v43, v36, 2, 0
	v_lshl_add_u32 v44, v37, 2, 0
	v_lshl_add_u32 v45, v38, 2, 0
	v_lshl_add_u32 v46, v39, 2, 0
	s_waitcnt lgkmcnt(0)
	v_pk_fma_f32 v[12:13], v[24:25], v[32:33], v[12:13] op_sel_hi:[0,1,1]
	ds_read2st64_b32 v[34:35], v40 offset1:2
	ds_read2st64_b32 v[36:37], v41 offset1:2
	ds_read2st64_b32 v[38:39], v42 offset1:2
	ds_read2st64_b32 v[40:41], v43 offset1:2
	ds_read2st64_b32 v[42:43], v44 offset1:2
	ds_read2st64_b32 v[44:45], v45 offset1:2
	ds_read2st64_b32 v[46:47], v46 offset1:2
	s_waitcnt lgkmcnt(6)
	v_pk_fma_f32 v[12:13], v[24:25], v[34:35], v[12:13] op_sel:[1,0,0]
	v_mov_b32_e32 v48, v27
	s_waitcnt lgkmcnt(5)
	v_pk_fma_f32 v[12:13], v[26:27], v[36:37], v[12:13] op_sel_hi:[0,1,1]
	s_waitcnt lgkmcnt(4)
	v_pk_fma_f32 v[12:13], v[48:49], v[38:39], v[12:13] op_sel_hi:[0,1,1]
	s_waitcnt lgkmcnt(3)
	v_pk_fma_f32 v[12:13], v[28:29], v[40:41], v[12:13] op_sel_hi:[0,1,1]
	s_waitcnt lgkmcnt(2)
	v_pk_fma_f32 v[12:13], v[28:29], v[42:43], v[12:13] op_sel:[1,0,0]
	s_add_i32 s2, s2, 32
	v_mov_b32_e32 v50, v31
	s_waitcnt lgkmcnt(1)
	v_pk_fma_f32 v[12:13], v[30:31], v[44:45], v[12:13] op_sel_hi:[0,1,1]
	v_add_u32_e32 v9, v9, v17
	s_cmpk_eq_i32 s2, 0x200
	s_waitcnt lgkmcnt(0)
	v_pk_fma_f32 v[12:13], v[50:51], v[46:47], v[12:13] op_sel_hi:[0,1,1]
	s_cbranch_scc0 .LBB0_929
	v_lshlrev_b64 v[10:11], 1, v[10:11]
	v_cvt_pk_bf16_f32 v9, v12, s0
	v_lshl_add_u64 v[24:25], v[4:5], 0, v[10:11]
	global_store_short v[24:25], v9, off
	v_cvt_pk_bf16_f32 v9, v13, s0
	v_lshl_add_u64 v[10:11], v[6:7], 0, v[10:11]
	s_mov_b32 s2, s39
	global_store_short v[10:11], v9, off
	s_lshl_b32 s2, s2, 2
	s_add_i32 s5, s2, s5
	s_cmpk_gt_i32 s5, 0xfff
	s_cbranch_scc0 .LBB0_928

; __device__ __forceinline__ unsigned cvt_pk_bf16(float lo, float hi) { const f32x2_t v = {lo, hi}; const bf16x2_t b = __builtin_convertvector(v, bf16x2_t); return __builtin_bit_cast(unsigned, b); }
; __device__ void prep_phase(const Params& p, int l, LAS unsigned char* lds) {
;     ...
;         for (int i = gtid; i < 2 * 1024 * 1024; i += gsz) {
;             const int part = i >> 20, sp = (i >> 10) & 1023, s0 = (i & 1023) * 2;
;             const int j0 = (sp * s0) & 2047, j1 = (sp * (s0 + 1)) & 2047;
;             float v0, v1;
;             if (part) { v0 = sinpif((float)j0 * (1.0f / 1024.0f)); v1 = sinpif((float)j1 * (1.0f / 1024.0f)); }
;             else { v0 = cospif((float)j0 * (1.0f / 1024.0f)); v1 = cospif((float)j1 * (1.0f / 1024.0f)); }
;             DM[i] = cvt_pk_bf16(v0, v1);
.LBB0_934:
	s_or_b64 exec, exec, s[12:13]
	v_cmp_lg_f32_e32 vcc, s49, v3
	v_add_u32_e32 v2, s4, v2
	s_mov_b32 s2, 0x1fffff
	v_cndmask_b32_e32 v3, v252, v11, vcc
	v_cvt_pk_bf16_f32 v3, v6, v3
	v_cmp_lt_i32_e32 vcc, s2, v2
	global_store_dword v[4:5], v3, off
	v_lshl_add_u64 v[4:5], v[4:5], 0, s[8:9]
	s_or_b64 s[10:11], vcc, s[10:11]
	v_add_u32_e32 v0, s5, v0
	s_andn2_b64 exec, exec, s[10:11]
	s_cbranch_execz .LBB0_939

; __device__ __forceinline__ unsigned cvt_pk_bf16(float lo, float hi) { const f32x2_t v = {lo, hi}; const bf16x2_t b = __builtin_convertvector(v, bf16x2_t); return __builtin_bit_cast(unsigned, b); }
; __device__ void rmsnorm_phase(const float* __restrict__ x, const float* __restrict__ g, bf16_t* h, float* outf) {
;     ...
;     for (int row = gw; row < T_; row += nw) {
;         const float4* xr = (const float4*)(x + (size_t)row * D_);
;         float4 v[4]; float ss = 0.f;
; #pragma unroll
;         for (int i = 0; i < 4; ++i) { v[i] = xr[lane + 64 * i]; ss += v[i].x * v[i].x + v[i].y * v[i].y + v[i].z * v[i].z + v[i].w * v[i].w; }
; #pragma unroll
;         for (int o = 32; o >= 1; o >>= 1) ss += __shfl_xor(ss, o);
;         const float rs = rsqrtf(ss * (1.0f / 1024.0f) + 1e-6f);
; #pragma unroll
;         for (int i = 0; i < 4; ++i) {
;             const float a = v[i].x * rs * gv[i].x, b = v[i].y * rs * gv[i].y, c = v[i].z * rs * gv[i].z, d = v[i].w * rs * gv[i].w;
;             if (outf) ((float4*)(outf + (size_t)row * D_))[lane + 64 * i] = make_float4(a, b, c, d);
;             else { u32x2 w; w.x = cvt_pk_bf16(a, b); w.y = cvt_pk_bf16(c, d); *(u32x2*)(h + (size_t)row * D_ + (lane + 64 * i) * 4) = w; }
;         }
.LBB0_942:
	global_load_dwordx4 v[30:33], v[22:23], off
	global_load_dwordx4 v[34:37], v[22:23], off offset:1024
	global_load_dwordx4 v[38:41], v[22:23], off offset:2048
	global_load_dwordx4 v[42:45], v[22:23], off offset:3072
	v_add_u32_e32 v18, s4, v18
	v_cmp_lt_i32_e32 vcc, s59, v18
	s_or_b64 s[10:11], vcc, s[10:11]
	v_lshl_add_u64 v[22:23], v[22:23], 0, s[8:9]
	s_waitcnt vmcnt(0) lgkmcnt(0)
	v_mov_b32_e32 v52, v31
	v_mov_b32_e32 v53, v35
	v_mov_b32_e32 v50, v30
	v_mov_b32_e32 v51, v34
	v_mov_b32_e32 v60, v39
	v_mov_b32_e32 v61, v43
	v_pk_mul_f32 v[52:53], v[52:53], v[52:53]
	v_mov_b32_e32 v46, v32
	v_mov_b32_e32 v47, v36
	v_mov_b32_e32 v58, v38
	v_mov_b32_e32 v59, v42
	v_pk_mul_f32 v[60:61], v[60:61], v[60:61]
	v_pk_fma_f32 v[50:51], v[50:51], v[50:51], v[52:53]
	v_mov_b32_e32 v48, v33
	v_mov_b32_e32 v49, v37
	v_mov_b32_e32 v54, v40
	v_mov_b32_e32 v55, v44
	v_pk_fma_f32 v[52:53], v[58:59], v[58:59], v[60:61]
	v_pk_fma_f32 v[46:47], v[46:47], v[46:47], v[50:51]
	v_mov_b32_e32 v56, v41
	v_mov_b32_e32 v57, v45
	v_pk_fma_f32 v[50:51], v[54:55], v[54:55], v[52:53]
	v_pk_fma_f32 v[46:47], v[48:49], v[48:49], v[46:47]
	v_pk_fma_f32 v[48:49], v[56:57], v[56:57], v[50:51]
	v_add_f32_e32 v19, v46, v47
	v_add_f32_e32 v19, v19, v48
	v_add_f32_e32 v19, v19, v49
	ds_bpermute_b32 v29, v0, v19
	s_waitcnt lgkmcnt(0)
	v_add_f32_e32 v19, v19, v29
	ds_bpermute_b32 v29, v24, v19
	s_waitcnt lgkmcnt(0)
	v_add_f32_e32 v19, v19, v29
	ds_bpermute_b32 v29, v25, v19
	s_waitcnt lgkmcnt(0)
	v_add_f32_e32 v19, v19, v29
	ds_bpermute_b32 v29, v26, v19
	s_waitcnt lgkmcnt(0)
	v_add_f32_e32 v19, v19, v29
	ds_bpermute_b32 v29, v27, v19
	s_waitcnt lgkmcnt(0)
	v_add_f32_e32 v19, v19, v29
	ds_bpermute_b32 v29, v28, v19
	s_waitcnt lgkmcnt(0)
	v_add_f32_e32 v19, v19, v29
	v_fmamk_f32 v19, v19, 0x3a800000, v169
	v_mul_f32_e32 v29, 0x4b800000, v19
	v_cmp_gt_f32_e32 vcc, s33, v19
	s_nop 1
	v_cndmask_b32_e32 v19, v19, v29, vcc
	v_rsq_f32_e32 v19, v19
	s_nop 0
	v_mul_f32_e32 v29, 0x45800000, v19
	v_cndmask_b32_e32 v46, v19, v29, vcc
	v_pk_mul_f32 v[30:31], v[30:31], v[46:47] op_sel_hi:[1,0]
	v_pk_mul_f32 v[32:33], v[32:33], v[46:47] op_sel_hi:[1,0]
	v_pk_mul_f32 v[34:35], v[34:35], v[46:47] op_sel_hi:[1,0]
	v_pk_mul_f32 v[36:37], v[36:37], v[46:47] op_sel_hi:[1,0]
	v_pk_mul_f32 v[38:39], v[38:39], v[46:47] op_sel_hi:[1,0]
	v_pk_mul_f32 v[40:41], v[40:41], v[46:47] op_sel_hi:[1,0]
	v_pk_mul_f32 v[42:43], v[42:43], v[46:47] op_sel_hi:[1,0]
	v_pk_mul_f32 v[44:45], v[44:45], v[46:47] op_sel_hi:[1,0]
	v_pk_mul_f32 v[30:31], v[2:3], v[30:31]
	v_pk_mul_f32 v[32:33], v[4:5], v[32:33]
	v_pk_mul_f32 v[34:35], v[6:7], v[34:35]
	v_pk_mul_f32 v[36:37], v[8:9], v[36:37]
	v_pk_mul_f32 v[38:39], v[10:11], v[38:39]
	v_pk_mul_f32 v[40:41], v[12:13], v[40:41]
	v_pk_mul_f32 v[42:43], v[14:15], v[42:43]
	v_pk_mul_f32 v[44:45], v[16:17], v[44:45]
	v_cvt_pk_bf16_f32 v30, v30, v31
	v_cvt_pk_bf16_f32 v31, v32, v33
	v_cvt_pk_bf16_f32 v32, v34, v35
	v_cvt_pk_bf16_f32 v33, v36, v37
	v_cvt_pk_bf16_f32 v34, v38, v39
	v_cvt_pk_bf16_f32 v35, v40, v41
	v_cvt_pk_bf16_f32 v36, v42, v43
	v_cvt_pk_bf16_f32 v37, v44, v45
	global_store_dwordx2 v[20:21], v[30:31], off
	global_store_dwordx2 v[20:21], v[32:33], off offset:512
	global_store_dwordx2 v[20:21], v[34:35], off offset:1024
	global_store_dwordx2 v[20:21], v[36:37], off offset:1536
	v_lshl_add_u64 v[20:21], v[20:21], 0, s[6:7]
	s_andn2_b64 exec, exec, s[10:11]
	s_cbranch_execnz .LBB0_942
